# GEMM K-loops: per-segment s_setprio toggling removed (both half-workgroups at priority 0); deferred SSQ atomics kept
# speedup vs baseline: 1.0122x; 1.0122x over previous
; #define PG8_STAGE(bufoff, gbase, voff) do { _Pragma("unroll") for (int _i = 0; _i < 2; ++_i) \
;         __builtin_amdgcn_global_load_lds((const unsigned*)((const char*)(gbase) + (voff)[_i]), (PG8_LAS unsigned*)(lds + (bufoff) + ldsw + _i * 8192), 16, 0, 0); } while (0)
; #define PG8_LDA(dst, b, h) do { _Pragma("unroll") for (int m = 0; m < 4; ++m) _Pragma("unroll") for (int k = 0; k < 2; ++k) dst[m][k] = *(const PG8_LAS bf16x8*)(lds + PG8_SA(b, h) + aoff + m * 2048 + k * 1024); } while (0)
; #define PG8_LDB(dst, b, h) do { _Pragma("unroll") for (int n = 0; n < 2; ++n) _Pragma("unroll") for (int k = 0; k < 2; ++k) dst[n][k] = *(const PG8_LAS bf16x8*)(lds + PG8_SB(b, h) + boff + n * 2048 + k * 1024); } while (0)
; #define PG8_MMA(ai, bj, At, Bt) do { __builtin_amdgcn_s_setprio(1); _Pragma("unroll") for (int m = 0; m < 4; ++m) _Pragma("unroll") for (int n = 0; n < 2; ++n) _Pragma("unroll") for (int k = 0; k < 2; ++k) \
;         acc[ai][bj][m][n] = __builtin_amdgcn_mfma_f32_16x16x32_bf16(Bt[n][k], At[m][k], acc[ai][bj][m][n], 0, 0, 0); __builtin_amdgcn_s_setprio(0); } while (0)
; #define PG8_WAIT_V(n) asm volatile("s_waitcnt vmcnt(" #n ")" ::: "memory")
; #define PG8_WAIT_L(n) asm volatile("s_waitcnt lgkmcnt(" #n ")" ::: "memory")
; template <class Epi, class Sched, bool ALIGN_EPI = false, bool SP2 = false>
; __device__ __forceinline__ void gemm_phase(PG8_LAS unsigned char* lds, const Gemm g, const Sched& S, const Epi& E, const int wid) {
;     ...
;         for (int t = 0; t < nt; t += 2) {
;             const bool last = (t == nt - 2);
;             const char* a1 = cA + (size_t)(t + 1) * kstep;
;             const char* a2 = last ? nA : cA + (size_t)(t + 2) * kstep; const char* b2 = last ? nB : cB + (size_t)(t + 2) * kstep;
;             const char* a3 = a2 + kstep; const char* b3 = b2 + kstep;
;             if constexpr (SP2) {
;             PG8_LDB(B0, 0, 0); PG8_LDB(B1, 0, 1); PG8_SCHED; PG8_LDA(At, 0, 0); PG8_STAGE(PG8_SA(1, 1), a1 + hsA, voffA);
;             PG8_WAIT_V(8); PG8_WAIT_L(0); PG8_BAR; PG8_MMA(0, 0, At, B0); PG8_MMA(0, 1, At, B1); PG8_BAR; PG8_SCHED;
;             PG8_LDA(At, 0, 1); PG8_STAGE(PG8_SB(0, 0), b2, voffB); PG8_STAGE(PG8_SB(0, 1), b2 + hsB, voffB); PG8_STAGE(PG8_SA(0, 0), a2, voffA);
;             PG8_WAIT_V(8); PG8_WAIT_L(0); PG8_BAR; PG8_MMA(1, 0, At, B0); PG8_MMA(1, 1, At, B1); PG8_BAR; PG8_SCHED;
.LBB0_418:
	ds_read_b128 v[144:147], v149
	ds_read_b128 v[152:155], v149 offset:1024
	ds_read_b128 v[156:159], v149 offset:2048
	ds_read_b128 v[160:163], v149 offset:3072
	ds_read_b128 v[164:167], v150
	ds_read_b128 v[168:171], v150 offset:1024
	ds_read_b128 v[172:175], v150 offset:2048
	ds_read_b128 v[176:179], v150 offset:3072
	s_add_u32 s26, s24, 0xfff80080
	s_addc_u32 s27, s25, -1
	s_cmp_eq_u32 s55, 28
	s_cselect_b32 s29, s17, s27
	s_cselect_b32 s28, s51, s26
	s_cselect_b32 s27, s15, s54
	s_cselect_b32 s26, s52, s53
	v_lshl_add_u64 v[212:213], s[24:25], 0, v[138:139]
	s_add_i32 m0, s23, 0xc000
	ds_read_b128 v[180:183], v151
	ds_read_b128 v[184:187], v151 offset:1024
	ds_read_b128 v[188:191], v151 offset:2048
	ds_read_b128 v[192:195], v151 offset:3072
	ds_read_b128 v[196:199], v151 offset:4096
	ds_read_b128 v[200:203], v151 offset:5120
	ds_read_b128 v[204:207], v151 offset:6144
	ds_read_b128 v[208:211], v151 offset:7168
	global_load_lds_dwordx4 v[212:213], off
	v_lshl_add_u64 v[212:213], s[24:25], 0, v[136:137]
	s_add_i32 m0, s23, 0xe000
	s_nop 0
	global_load_lds_dwordx4 v[212:213], off
	s_waitcnt vmcnt(8)
	s_waitcnt lgkmcnt(0)
	s_barrier
	s_waitcnt lgkmcnt(0)
	v_mfma_f32_16x16x32_bf16 v[124:127], v[144:147], v[180:183], v[124:127]
	v_mfma_f32_16x16x32_bf16 v[120:123], v[156:159], v[180:183], v[120:123]
	v_mfma_f32_16x16x32_bf16 v[108:111], v[144:147], v[188:191], v[108:111]
	v_mfma_f32_16x16x32_bf16 v[104:107], v[156:159], v[188:191], v[104:107]
	v_mfma_f32_16x16x32_bf16 v[92:95], v[144:147], v[196:199], v[92:95]
	v_mfma_f32_16x16x32_bf16 v[88:91], v[156:159], v[196:199], v[88:91]
	v_mfma_f32_16x16x32_bf16 v[76:79], v[144:147], v[204:207], v[76:79]
	v_mfma_f32_16x16x32_bf16 v[72:75], v[156:159], v[204:207], v[72:75]
	v_mfma_f32_16x16x32_bf16 v[124:127], v[152:155], v[184:187], v[124:127]
	v_mfma_f32_16x16x32_bf16 v[120:123], v[160:163], v[184:187], v[120:123]
	v_mfma_f32_16x16x32_bf16 v[108:111], v[152:155], v[192:195], v[108:111]
	v_mfma_f32_16x16x32_bf16 v[104:107], v[160:163], v[192:195], v[104:107]
	v_mfma_f32_16x16x32_bf16 v[92:95], v[152:155], v[200:203], v[92:95]
	v_mfma_f32_16x16x32_bf16 v[88:91], v[160:163], v[200:203], v[88:91]
	v_mfma_f32_16x16x32_bf16 v[76:79], v[152:155], v[208:211], v[76:79]
	v_mfma_f32_16x16x32_bf16 v[72:75], v[160:163], v[208:211], v[72:75]
	v_mfma_f32_16x16x32_bf16 v[116:119], v[164:167], v[180:183], v[116:119]
	v_mfma_f32_16x16x32_bf16 v[112:115], v[172:175], v[180:183], v[112:115]
	v_mfma_f32_16x16x32_bf16 v[100:103], v[164:167], v[188:191], v[100:103]
	v_mfma_f32_16x16x32_bf16 v[96:99], v[172:175], v[188:191], v[96:99]
	v_mfma_f32_16x16x32_bf16 v[84:87], v[164:167], v[196:199], v[84:87]
	v_mfma_f32_16x16x32_bf16 v[80:83], v[172:175], v[196:199], v[80:83]
	v_mfma_f32_16x16x32_bf16 v[68:71], v[164:167], v[204:207], v[68:71]
	v_mfma_f32_16x16x32_bf16 v[64:67], v[172:175], v[204:207], v[64:67]
	v_mfma_f32_16x16x32_bf16 v[116:119], v[168:171], v[184:187], v[116:119]
	v_mfma_f32_16x16x32_bf16 v[112:115], v[176:179], v[184:187], v[112:115]
	v_mfma_f32_16x16x32_bf16 v[100:103], v[168:171], v[192:195], v[100:103]
	v_mfma_f32_16x16x32_bf16 v[96:99], v[176:179], v[192:195], v[96:99]
	v_mfma_f32_16x16x32_bf16 v[84:87], v[168:171], v[200:203], v[84:87]
	v_mfma_f32_16x16x32_bf16 v[80:83], v[176:179], v[200:203], v[80:83]
	v_mfma_f32_16x16x32_bf16 v[68:71], v[168:171], v[208:211], v[68:71]
	v_mfma_f32_16x16x32_bf16 v[64:67], v[176:179], v[208:211], v[64:67]
	s_barrier
	s_add_i32 s56, s47, s34
	v_lshl_add_u64 v[212:213], s[26:27], 0, v[132:133]
	s_mov_b32 m0, s56
	ds_read_b128 v[180:183], v151 offset:16384
	ds_read_b128 v[184:187], v151 offset:17408
	ds_read_b128 v[188:191], v151 offset:18432
	ds_read_b128 v[192:195], v151 offset:19456
	ds_read_b128 v[196:199], v151 offset:20480
	ds_read_b128 v[200:203], v151 offset:21504
	ds_read_b128 v[204:207], v151 offset:22528
	ds_read_b128 v[208:211], v151 offset:23552
	global_load_lds_dwordx4 v[212:213], off
	s_add_i32 m0, s56, 0x2000
	s_add_u32 s56, s26, 0x80000
	v_lshl_add_u64 v[214:215], s[26:27], 0, v[128:129]
	s_addc_u32 s57, s27, 0
	s_add_i32 s58, s48, s34
	global_load_lds_dwordx4 v[214:215], off
	v_lshl_add_u64 v[216:217], s[56:57], 0, v[132:133]
	s_mov_b32 m0, s58
	v_lshl_add_u64 v[218:219], s[28:29], 0, v[130:131]
	global_load_lds_dwordx4 v[216:217], off
	v_lshl_add_u64 v[216:217], s[56:57], 0, v[128:129]
	s_add_i32 m0, s58, 0x2000
	s_nop 0
	global_load_lds_dwordx4 v[216:217], off
	v_lshl_add_u64 v[216:217], s[28:29], 0, v[134:135]
	s_mov_b32 m0, s23
	s_nop 0
	global_load_lds_dwordx4 v[216:217], off
	s_mov_b32 m0, s37
	s_nop 0
	global_load_lds_dwordx4 v[218:219], off
	s_waitcnt vmcnt(8)
	s_waitcnt lgkmcnt(0)
	s_barrier
; #define PG8_STAGE(bufoff, gbase, voff) do { _Pragma("unroll") for (int _i = 0; _i < 2; ++_i) \
;         __builtin_amdgcn_global_load_lds((const unsigned*)((const char*)(gbase) + (voff)[_i]), (PG8_LAS unsigned*)(lds + (bufoff) + ldsw + _i * 8192), 16, 0, 0); } while (0)
; #define PG8_LDA(dst, b, h) do { _Pragma("unroll") for (int m = 0; m < 4; ++m) _Pragma("unroll") for (int k = 0; k < 2; ++k) dst[m][k] = *(const PG8_LAS bf16x8*)(lds + PG8_SA(b, h) + aoff + m * 2048 + k * 1024); } while (0)
; #define PG8_LDB(dst, b, h) do { _Pragma("unroll") for (int n = 0; n < 2; ++n) _Pragma("unroll") for (int k = 0; k < 2; ++k) dst[n][k] = *(const PG8_LAS bf16x8*)(lds + PG8_SB(b, h) + boff + n * 2048 + k * 1024); } while (0)
; #define PG8_MMA(ai, bj, At, Bt) do { __builtin_amdgcn_s_setprio(1); _Pragma("unroll") for (int m = 0; m < 4; ++m) _Pragma("unroll") for (int n = 0; n < 2; ++n) _Pragma("unroll") for (int k = 0; k < 2; ++k) \
;         acc[ai][bj][m][n] = __builtin_amdgcn_mfma_f32_16x16x32_bf16(Bt[n][k], At[m][k], acc[ai][bj][m][n], 0, 0, 0); __builtin_amdgcn_s_setprio(0); } while (0)
; #define PG8_WAIT_V(n) asm volatile("s_waitcnt vmcnt(" #n ")" ::: "memory")
; #define PG8_WAIT_L(n) asm volatile("s_waitcnt lgkmcnt(" #n ")" ::: "memory")
; #define PG8_BAR __builtin_amdgcn_s_barrier()
; #define PG8_SCHED __builtin_amdgcn_sched_barrier(0)
; template <class Epi, class Sched, bool ALIGN_EPI = false, bool SP2 = false>
; __device__ __forceinline__ void gemm_phase(PG8_LAS unsigned char* lds, const Gemm g, const Sched& S, const Epi& E, const int wid) {
;     ...
;             PG8_WAIT_V(8); PG8_WAIT_L(0); PG8_BAR; PG8_MMA(1, 0, At, B0); PG8_MMA(1, 1, At, B1); PG8_BAR; PG8_SCHED;
;             PG8_LDB(B0, 1, 0); PG8_LDB(B1, 1, 1); PG8_SCHED; PG8_LDA(At, 1, 0); PG8_STAGE(PG8_SA(0, 1), a2 + hsA, voffA);
;             PG8_WAIT_V(8); PG8_WAIT_L(0); PG8_BAR; PG8_MMA(0, 0, At, B0); PG8_MMA(0, 1, At, B1); PG8_BAR; PG8_SCHED;
	s_waitcnt lgkmcnt(0)
	v_mfma_f32_16x16x32_bf16 v[60:63], v[144:147], v[180:183], v[60:63]
	v_mfma_f32_16x16x32_bf16 v[56:59], v[156:159], v[180:183], v[56:59]
	v_mfma_f32_16x16x32_bf16 v[44:47], v[144:147], v[188:191], v[44:47]
	v_mfma_f32_16x16x32_bf16 v[40:43], v[156:159], v[188:191], v[40:43]
	v_mfma_f32_16x16x32_bf16 v[28:31], v[144:147], v[196:199], v[28:31]
	v_mfma_f32_16x16x32_bf16 v[24:27], v[156:159], v[196:199], v[24:27]
	v_mfma_f32_16x16x32_bf16 v[12:15], v[144:147], v[204:207], v[12:15]
	v_mfma_f32_16x16x32_bf16 v[8:11], v[156:159], v[204:207], v[8:11]
	v_mfma_f32_16x16x32_bf16 v[60:63], v[152:155], v[184:187], v[60:63]
	v_mfma_f32_16x16x32_bf16 v[56:59], v[160:163], v[184:187], v[56:59]
	v_mfma_f32_16x16x32_bf16 v[44:47], v[152:155], v[192:195], v[44:47]
	v_mfma_f32_16x16x32_bf16 v[40:43], v[160:163], v[192:195], v[40:43]
	v_mfma_f32_16x16x32_bf16 v[28:31], v[152:155], v[200:203], v[28:31]
	v_mfma_f32_16x16x32_bf16 v[24:27], v[160:163], v[200:203], v[24:27]
	v_mfma_f32_16x16x32_bf16 v[12:15], v[152:155], v[208:211], v[12:15]
	v_mfma_f32_16x16x32_bf16 v[8:11], v[160:163], v[208:211], v[8:11]
	v_mfma_f32_16x16x32_bf16 v[52:55], v[164:167], v[180:183], v[52:55]
	v_mfma_f32_16x16x32_bf16 v[48:51], v[172:175], v[180:183], v[48:51]
	v_mfma_f32_16x16x32_bf16 v[36:39], v[164:167], v[188:191], v[36:39]
	v_mfma_f32_16x16x32_bf16 v[32:35], v[172:175], v[188:191], v[32:35]
	v_mfma_f32_16x16x32_bf16 v[20:23], v[164:167], v[196:199], v[20:23]
	v_mfma_f32_16x16x32_bf16 v[16:19], v[172:175], v[196:199], v[16:19]
	v_mfma_f32_16x16x32_bf16 v[4:7], v[164:167], v[204:207], v[4:7]
	v_mfma_f32_16x16x32_bf16 v[0:3], v[172:175], v[204:207], v[0:3]
	v_mfma_f32_16x16x32_bf16 v[52:55], v[168:171], v[184:187], v[52:55]
	v_mfma_f32_16x16x32_bf16 v[48:51], v[176:179], v[184:187], v[48:51]
	v_mfma_f32_16x16x32_bf16 v[36:39], v[168:171], v[192:195], v[36:39]
	v_mfma_f32_16x16x32_bf16 v[32:35], v[176:179], v[192:195], v[32:35]
	v_mfma_f32_16x16x32_bf16 v[20:23], v[168:171], v[200:203], v[20:23]
	v_mfma_f32_16x16x32_bf16 v[16:19], v[176:179], v[200:203], v[16:19]
	v_mfma_f32_16x16x32_bf16 v[4:7], v[168:171], v[208:211], v[4:7]
	v_mfma_f32_16x16x32_bf16 v[0:3], v[176:179], v[208:211], v[0:3]
	s_barrier
	s_add_i32 s56, 0, 0x18000
	s_add_i32 s57, 0, 0x1c000
	v_add_u32_e32 v160, s56, v148
	v_add_u32_e32 v176, s57, v148
	ds_read_b128 v[144:147], v160
	ds_read_b128 v[152:155], v160 offset:1024
	ds_read_b128 v[156:159], v160 offset:2048
	ds_read_b128 v[160:163], v160 offset:3072
	ds_read_b128 v[164:167], v176
	ds_read_b128 v[168:171], v176 offset:1024
	ds_read_b128 v[172:175], v176 offset:2048
	ds_read_b128 v[176:179], v176 offset:3072
	s_add_u32 s28, s28, 0x80000
	s_addc_u32 s29, s29, 0
	s_mov_b32 m0, s38
	v_lshl_add_u64 v[220:221], s[28:29], 0, v[134:135]
	ds_read_b128 v[180:183], v151 offset:32768
	ds_read_b128 v[184:187], v151 offset:33792
	ds_read_b128 v[188:191], v151 offset:34816
	ds_read_b128 v[192:195], v151 offset:35840
	ds_read_b128 v[196:199], v151 offset:36864
	ds_read_b128 v[200:203], v151 offset:37888
	ds_read_b128 v[204:207], v151 offset:38912
	ds_read_b128 v[208:211], v151 offset:39936
	global_load_lds_dwordx4 v[220:221], off
	v_lshl_add_u64 v[220:221], s[28:29], 0, v[130:131]
	s_mov_b32 m0, s39
	s_nop 0
	global_load_lds_dwordx4 v[220:221], off
	s_waitcnt vmcnt(8)
	s_waitcnt lgkmcnt(0)
	s_barrier
	s_waitcnt lgkmcnt(0)
	v_mfma_f32_16x16x32_bf16 v[124:127], v[144:147], v[180:183], v[124:127]
	v_mfma_f32_16x16x32_bf16 v[120:123], v[156:159], v[180:183], v[120:123]
	v_mfma_f32_16x16x32_bf16 v[108:111], v[144:147], v[188:191], v[108:111]
	v_mfma_f32_16x16x32_bf16 v[104:107], v[156:159], v[188:191], v[104:107]
	v_mfma_f32_16x16x32_bf16 v[92:95], v[144:147], v[196:199], v[92:95]
	v_mfma_f32_16x16x32_bf16 v[88:91], v[156:159], v[196:199], v[88:91]
	v_mfma_f32_16x16x32_bf16 v[76:79], v[144:147], v[204:207], v[76:79]
	v_mfma_f32_16x16x32_bf16 v[72:75], v[156:159], v[204:207], v[72:75]
	v_mfma_f32_16x16x32_bf16 v[124:127], v[152:155], v[184:187], v[124:127]
	v_mfma_f32_16x16x32_bf16 v[120:123], v[160:163], v[184:187], v[120:123]
	v_mfma_f32_16x16x32_bf16 v[108:111], v[152:155], v[192:195], v[108:111]
	v_mfma_f32_16x16x32_bf16 v[104:107], v[160:163], v[192:195], v[104:107]
	v_mfma_f32_16x16x32_bf16 v[92:95], v[152:155], v[200:203], v[92:95]
	v_mfma_f32_16x16x32_bf16 v[88:91], v[160:163], v[200:203], v[88:91]
	v_mfma_f32_16x16x32_bf16 v[76:79], v[152:155], v[208:211], v[76:79]
	v_mfma_f32_16x16x32_bf16 v[72:75], v[160:163], v[208:211], v[72:75]
	v_mfma_f32_16x16x32_bf16 v[116:119], v[164:167], v[180:183], v[116:119]
	v_mfma_f32_16x16x32_bf16 v[112:115], v[172:175], v[180:183], v[112:115]
	v_mfma_f32_16x16x32_bf16 v[100:103], v[164:167], v[188:191], v[100:103]
	v_mfma_f32_16x16x32_bf16 v[96:99], v[172:175], v[188:191], v[96:99]
	v_mfma_f32_16x16x32_bf16 v[84:87], v[164:167], v[196:199], v[84:87]
	v_mfma_f32_16x16x32_bf16 v[80:83], v[172:175], v[196:199], v[80:83]
	v_mfma_f32_16x16x32_bf16 v[68:71], v[164:167], v[204:207], v[68:71]
	v_mfma_f32_16x16x32_bf16 v[64:67], v[172:175], v[204:207], v[64:67]
	v_mfma_f32_16x16x32_bf16 v[116:119], v[168:171], v[184:187], v[116:119]
	v_mfma_f32_16x16x32_bf16 v[112:115], v[176:179], v[184:187], v[112:115]
	v_mfma_f32_16x16x32_bf16 v[100:103], v[168:171], v[192:195], v[100:103]
	v_mfma_f32_16x16x32_bf16 v[96:99], v[176:179], v[192:195], v[96:99]
	v_mfma_f32_16x16x32_bf16 v[84:87], v[168:171], v[200:203], v[84:87]
	v_mfma_f32_16x16x32_bf16 v[80:83], v[176:179], v[200:203], v[80:83]
	v_mfma_f32_16x16x32_bf16 v[68:71], v[168:171], v[208:211], v[68:71]
	v_mfma_f32_16x16x32_bf16 v[64:67], v[176:179], v[208:211], v[64:67]
	s_barrier
; #define PG8_STAGE(bufoff, gbase, voff) do { _Pragma("unroll") for (int _i = 0; _i < 2; ++_i) \
;         __builtin_amdgcn_global_load_lds((const unsigned*)((const char*)(gbase) + (voff)[_i]), (PG8_LAS unsigned*)(lds + (bufoff) + ldsw + _i * 8192), 16, 0, 0); } while (0)
; #define PG8_LDA(dst, b, h) do { _Pragma("unroll") for (int m = 0; m < 4; ++m) _Pragma("unroll") for (int k = 0; k < 2; ++k) dst[m][k] = *(const PG8_LAS bf16x8*)(lds + PG8_SA(b, h) + aoff + m * 2048 + k * 1024); } while (0)
; #define PG8_MMA(ai, bj, At, Bt) do { __builtin_amdgcn_s_setprio(1); _Pragma("unroll") for (int m = 0; m < 4; ++m) _Pragma("unroll") for (int n = 0; n < 2; ++n) _Pragma("unroll") for (int k = 0; k < 2; ++k) \
;         acc[ai][bj][m][n] = __builtin_amdgcn_mfma_f32_16x16x32_bf16(Bt[n][k], At[m][k], acc[ai][bj][m][n], 0, 0, 0); __builtin_amdgcn_s_setprio(0); } while (0)
; #define PG8_WAIT_V(n) asm volatile("s_waitcnt vmcnt(" #n ")" ::: "memory")
; #define PG8_WAIT_L(n) asm volatile("s_waitcnt lgkmcnt(" #n ")" ::: "memory")
; #define PG8_BAR __builtin_amdgcn_s_barrier()
; #define PG8_SCHED __builtin_amdgcn_sched_barrier(0)
; template <class Epi, class Sched, bool ALIGN_EPI = false, bool SP2 = false>
; __device__ __forceinline__ void gemm_phase(PG8_LAS unsigned char* lds, const Gemm g, const Sched& S, const Epi& E, const int wid) {
;     ...
;             PG8_LDA(At, 1, 1); PG8_STAGE(PG8_SB(1, 0), b3, voffB); PG8_STAGE(PG8_SB(1, 1), b3 + hsB, voffB); PG8_STAGE(PG8_SA(1, 0), a3, voffA);
;             PG8_WAIT_V(8); PG8_WAIT_L(0); PG8_BAR; PG8_MMA(1, 0, At, B0); PG8_MMA(1, 1, At, B1); PG8_BAR; PG8_SCHED;
	s_add_i32 s28, s56, s34
	v_lshl_add_u64 v[212:213], v[212:213], 0, s[10:11]
	s_mov_b32 m0, s28
	ds_read_b128 v[180:183], v151 offset:49152
	ds_read_b128 v[184:187], v151 offset:50176
	ds_read_b128 v[188:191], v151 offset:51200
	ds_read_b128 v[192:195], v151 offset:52224
	ds_read_b128 v[196:199], v151 offset:53248
	ds_read_b128 v[200:203], v151 offset:54272
	ds_read_b128 v[204:207], v151 offset:55296
	ds_read_b128 v[208:211], v151 offset:56320
	global_load_lds_dwordx4 v[212:213], off
	s_add_i32 m0, s28, 0x2000
	s_add_u32 s26, s26, 0x80080
	v_lshl_add_u64 v[212:213], v[214:215], 0, s[10:11]
	s_addc_u32 s27, s27, 0
	s_add_i32 s28, s57, s34
	global_load_lds_dwordx4 v[212:213], off
	v_lshl_add_u64 v[212:213], s[26:27], 0, v[132:133]
	s_mov_b32 m0, s28
	s_nop 0
	global_load_lds_dwordx4 v[212:213], off
	v_lshl_add_u64 v[212:213], s[26:27], 0, v[128:129]
	s_add_i32 m0, s28, 0x2000
	s_nop 0
	global_load_lds_dwordx4 v[212:213], off
	v_lshl_add_u64 v[212:213], v[216:217], 0, s[10:11]
	s_mov_b32 m0, s42
	s_nop 0
	global_load_lds_dwordx4 v[212:213], off
	v_lshl_add_u64 v[212:213], v[218:219], 0, s[10:11]
	s_mov_b32 m0, s43
	s_nop 0
	global_load_lds_dwordx4 v[212:213], off
	s_waitcnt vmcnt(8)
	s_waitcnt lgkmcnt(0)
	s_barrier
	s_waitcnt lgkmcnt(0)
	v_mfma_f32_16x16x32_bf16 v[60:63], v[144:147], v[180:183], v[60:63]
	v_mfma_f32_16x16x32_bf16 v[56:59], v[156:159], v[180:183], v[56:59]
	v_mfma_f32_16x16x32_bf16 v[44:47], v[144:147], v[188:191], v[44:47]
	v_mfma_f32_16x16x32_bf16 v[40:43], v[156:159], v[188:191], v[40:43]
	v_mfma_f32_16x16x32_bf16 v[28:31], v[144:147], v[196:199], v[28:31]
	v_mfma_f32_16x16x32_bf16 v[24:27], v[156:159], v[196:199], v[24:27]
	v_mfma_f32_16x16x32_bf16 v[12:15], v[144:147], v[204:207], v[12:15]
	v_mfma_f32_16x16x32_bf16 v[8:11], v[156:159], v[204:207], v[8:11]
	v_mfma_f32_16x16x32_bf16 v[60:63], v[152:155], v[184:187], v[60:63]
	v_mfma_f32_16x16x32_bf16 v[56:59], v[160:163], v[184:187], v[56:59]
	v_mfma_f32_16x16x32_bf16 v[44:47], v[152:155], v[192:195], v[44:47]
	v_mfma_f32_16x16x32_bf16 v[40:43], v[160:163], v[192:195], v[40:43]
	v_mfma_f32_16x16x32_bf16 v[28:31], v[152:155], v[200:203], v[28:31]
	v_mfma_f32_16x16x32_bf16 v[24:27], v[160:163], v[200:203], v[24:27]
	v_mfma_f32_16x16x32_bf16 v[12:15], v[152:155], v[208:211], v[12:15]
	v_mfma_f32_16x16x32_bf16 v[8:11], v[160:163], v[208:211], v[8:11]
	v_mfma_f32_16x16x32_bf16 v[52:55], v[164:167], v[180:183], v[52:55]
	v_mfma_f32_16x16x32_bf16 v[48:51], v[172:175], v[180:183], v[48:51]
	v_mfma_f32_16x16x32_bf16 v[36:39], v[164:167], v[188:191], v[36:39]
	v_mfma_f32_16x16x32_bf16 v[32:35], v[172:175], v[188:191], v[32:35]
	v_mfma_f32_16x16x32_bf16 v[20:23], v[164:167], v[196:199], v[20:23]
	v_mfma_f32_16x16x32_bf16 v[16:19], v[172:175], v[196:199], v[16:19]
	v_mfma_f32_16x16x32_bf16 v[4:7], v[164:167], v[204:207], v[4:7]
	v_mfma_f32_16x16x32_bf16 v[0:3], v[172:175], v[204:207], v[0:3]
	v_mfma_f32_16x16x32_bf16 v[52:55], v[168:171], v[184:187], v[52:55]
	v_mfma_f32_16x16x32_bf16 v[48:51], v[176:179], v[184:187], v[48:51]
	v_mfma_f32_16x16x32_bf16 v[36:39], v[168:171], v[192:195], v[36:39]
	v_mfma_f32_16x16x32_bf16 v[32:35], v[176:179], v[192:195], v[32:35]
	v_mfma_f32_16x16x32_bf16 v[20:23], v[168:171], v[200:203], v[20:23]
	v_mfma_f32_16x16x32_bf16 v[16:19], v[176:179], v[200:203], v[16:19]
	v_mfma_f32_16x16x32_bf16 v[4:7], v[168:171], v[208:211], v[4:7]
	v_mfma_f32_16x16x32_bf16 v[0:3], v[176:179], v[208:211], v[0:3]
	s_barrier
	s_add_i32 s55, s55, 2
	s_add_u32 s53, s53, 0x100
	s_addc_u32 s54, s54, 0
	s_add_u32 s24, s24, 0x100
	s_addc_u32 s25, s25, 0
	s_cmp_gt_u32 s55, 29
	s_cbranch_scc0 .LBB0_418
	s_and_b64 vcc, exec, s[12:13]
	s_cbranch_vccz .LBB0_421
	s_barrier

; #define PG8_STAGE(bufoff, gbase, voff) do { _Pragma("unroll") for (int _i = 0; _i < 2; ++_i) \
;         __builtin_amdgcn_global_load_lds((const unsigned*)((const char*)(gbase) + (voff)[_i]), (PG8_LAS unsigned*)(lds + (bufoff) + ldsw + _i * 8192), 16, 0, 0); } while (0)
; #define PG8_LDA(dst, b, h) do { _Pragma("unroll") for (int m = 0; m < 4; ++m) _Pragma("unroll") for (int k = 0; k < 2; ++k) dst[m][k] = *(const PG8_LAS bf16x8*)(lds + PG8_SA(b, h) + aoff + m * 2048 + k * 1024); } while (0)
; #define PG8_LDB(dst, b, h) do { _Pragma("unroll") for (int n = 0; n < 2; ++n) _Pragma("unroll") for (int k = 0; k < 2; ++k) dst[n][k] = *(const PG8_LAS bf16x8*)(lds + PG8_SB(b, h) + boff + n * 2048 + k * 1024); } while (0)
; #define PG8_MMA(ai, bj, At, Bt) do { __builtin_amdgcn_s_setprio(1); _Pragma("unroll") for (int m = 0; m < 4; ++m) _Pragma("unroll") for (int n = 0; n < 2; ++n) _Pragma("unroll") for (int k = 0; k < 2; ++k) \
;         acc[ai][bj][m][n] = __builtin_amdgcn_mfma_f32_16x16x32_bf16(Bt[n][k], At[m][k], acc[ai][bj][m][n], 0, 0, 0); __builtin_amdgcn_s_setprio(0); } while (0)
; #define PG8_WAIT_V(n) asm volatile("s_waitcnt vmcnt(" #n ")" ::: "memory")
; #define PG8_WAIT_L(n) asm volatile("s_waitcnt lgkmcnt(" #n ")" ::: "memory")
; template <class Epi, class Sched, bool ALIGN_EPI = false, bool SP2 = false>
; __device__ __forceinline__ void gemm_phase(PG8_LAS unsigned char* lds, const Gemm g, const Sched& S, const Epi& E, const int wid) {
;     ...
;         for (int t = 0; t < nt; t += 2) {
;             const bool last = (t == nt - 2);
;             const char* a1 = cA + (size_t)(t + 1) * kstep;
;             const char* a2 = last ? nA : cA + (size_t)(t + 2) * kstep; const char* b2 = last ? nB : cB + (size_t)(t + 2) * kstep;
;             const char* a3 = a2 + kstep; const char* b3 = b2 + kstep;
;             if constexpr (SP2) {
;             PG8_LDB(B0, 0, 0); PG8_LDB(B1, 0, 1); PG8_SCHED; PG8_LDA(At, 0, 0); PG8_STAGE(PG8_SA(1, 1), a1 + hsA, voffA);
;             PG8_WAIT_V(8); PG8_WAIT_L(0); PG8_BAR; PG8_MMA(0, 0, At, B0); PG8_MMA(0, 1, At, B1); PG8_BAR; PG8_SCHED;
;             PG8_LDA(At, 0, 1); PG8_STAGE(PG8_SB(0, 0), b2, voffB); PG8_STAGE(PG8_SB(0, 1), b2 + hsB, voffB); PG8_STAGE(PG8_SA(0, 0), a2, voffA);
;             PG8_WAIT_V(8); PG8_WAIT_L(0); PG8_BAR; PG8_MMA(1, 0, At, B0); PG8_MMA(1, 1, At, B1); PG8_BAR; PG8_SCHED;
.LBB0_497:
	ds_read_b128 v[64:67], v197
	ds_read_b128 v[72:75], v197 offset:1024
	ds_read_b128 v[80:83], v197 offset:2048
	ds_read_b128 v[84:87], v197 offset:3072
	ds_read_b128 v[88:91], v198
	ds_read_b128 v[92:95], v198 offset:1024
	ds_read_b128 v[100:103], v198 offset:2048
	ds_read_b128 v[104:107], v198 offset:3072
	s_add_u32 s4, s30, 0x100
	s_addc_u32 s5, s31, 0
	s_cmpk_eq_i32 s61, 0x54
	s_cselect_b32 s37, s27, s5
	s_cselect_b32 s36, s26, s4
	s_cselect_b32 s35, s29, s60
	s_cselect_b32 s34, s28, s59
	v_lshl_add_u64 v[210:211], s[30:31], 0, v[182:183]
	s_add_i32 m0, s41, 0xc000
	ds_read_b128 v[160:163], v199
	ds_read_b128 v[164:167], v199 offset:1024
	ds_read_b128 v[168:171], v199 offset:2048
	ds_read_b128 v[172:175], v199 offset:3072
	ds_read_b128 v[188:191], v199 offset:4096
	ds_read_b128 v[192:195], v199 offset:5120
	ds_read_b128 v[202:205], v199 offset:6144
	ds_read_b128 v[206:209], v199 offset:7168
	global_load_lds_dwordx4 v[210:211], off
	v_lshl_add_u64 v[210:211], s[30:31], 0, v[180:181]
	s_add_i32 m0, s41, 0xe000
	s_nop 0
	global_load_lds_dwordx4 v[210:211], off
	s_waitcnt vmcnt(8)
	s_waitcnt lgkmcnt(0)
	s_barrier
	s_waitcnt lgkmcnt(0)
	v_mfma_f32_16x16x32_bf16 v[156:159], v[64:67], v[160:163], v[156:159]
	v_mfma_f32_16x16x32_bf16 v[152:155], v[80:83], v[160:163], v[152:155]
	v_mfma_f32_16x16x32_bf16 v[140:143], v[64:67], v[168:171], v[140:143]
	v_mfma_f32_16x16x32_bf16 v[136:139], v[80:83], v[168:171], v[136:139]
	v_mfma_f32_16x16x32_bf16 v[124:127], v[64:67], v[188:191], v[124:127]
	v_mfma_f32_16x16x32_bf16 v[120:123], v[80:83], v[188:191], v[120:123]
	v_mfma_f32_16x16x32_bf16 v[108:111], v[64:67], v[202:205], v[108:111]
	v_mfma_f32_16x16x32_bf16 v[96:99], v[80:83], v[202:205], v[96:99]
	v_mfma_f32_16x16x32_bf16 v[156:159], v[72:75], v[164:167], v[156:159]
	v_mfma_f32_16x16x32_bf16 v[152:155], v[84:87], v[164:167], v[152:155]
	v_mfma_f32_16x16x32_bf16 v[140:143], v[72:75], v[172:175], v[140:143]
	v_mfma_f32_16x16x32_bf16 v[136:139], v[84:87], v[172:175], v[136:139]
	v_mfma_f32_16x16x32_bf16 v[124:127], v[72:75], v[192:195], v[124:127]
	v_mfma_f32_16x16x32_bf16 v[120:123], v[84:87], v[192:195], v[120:123]
	v_mfma_f32_16x16x32_bf16 v[108:111], v[72:75], v[206:209], v[108:111]
	v_mfma_f32_16x16x32_bf16 v[96:99], v[84:87], v[206:209], v[96:99]
	v_mfma_f32_16x16x32_bf16 v[148:151], v[88:91], v[160:163], v[148:151]
	v_mfma_f32_16x16x32_bf16 v[144:147], v[100:103], v[160:163], v[144:147]
	v_mfma_f32_16x16x32_bf16 v[132:135], v[88:91], v[168:171], v[132:135]
	v_mfma_f32_16x16x32_bf16 v[128:131], v[100:103], v[168:171], v[128:131]
	v_mfma_f32_16x16x32_bf16 v[116:119], v[88:91], v[188:191], v[116:119]
	v_mfma_f32_16x16x32_bf16 v[112:115], v[100:103], v[188:191], v[112:115]
	v_mfma_f32_16x16x32_bf16 v[76:79], v[88:91], v[202:205], v[76:79]
	v_mfma_f32_16x16x32_bf16 v[68:71], v[100:103], v[202:205], v[68:71]
	v_mfma_f32_16x16x32_bf16 v[148:151], v[92:95], v[164:167], v[148:151]
	v_mfma_f32_16x16x32_bf16 v[144:147], v[104:107], v[164:167], v[144:147]
	v_mfma_f32_16x16x32_bf16 v[132:135], v[92:95], v[172:175], v[132:135]
	v_mfma_f32_16x16x32_bf16 v[128:131], v[104:107], v[172:175], v[128:131]
	v_mfma_f32_16x16x32_bf16 v[116:119], v[92:95], v[192:195], v[116:119]
	v_mfma_f32_16x16x32_bf16 v[112:115], v[104:107], v[192:195], v[112:115]
	v_mfma_f32_16x16x32_bf16 v[76:79], v[92:95], v[206:209], v[76:79]
	v_mfma_f32_16x16x32_bf16 v[68:71], v[104:107], v[206:209], v[68:71]
	s_barrier
	s_add_i32 s30, s53, s40
	v_lshl_add_u64 v[210:211], s[34:35], 0, v[176:177]
	s_mov_b32 m0, s30
	ds_read_b128 v[160:163], v199 offset:16384
	ds_read_b128 v[164:167], v199 offset:17408
	ds_read_b128 v[168:171], v199 offset:18432
	ds_read_b128 v[172:175], v199 offset:19456
	ds_read_b128 v[188:191], v199 offset:20480
	ds_read_b128 v[192:195], v199 offset:21504
	ds_read_b128 v[202:205], v199 offset:22528
	ds_read_b128 v[206:209], v199 offset:23552
	global_load_lds_dwordx4 v[210:211], off
	s_add_i32 m0, s30, 0x2000
	s_add_u32 s30, s34, 0x160000
	v_lshl_add_u64 v[212:213], s[34:35], 0, v[178:179]
	s_addc_u32 s31, s35, 0
	s_add_i32 s62, s54, s40
	global_load_lds_dwordx4 v[212:213], off
	v_lshl_add_u64 v[214:215], s[30:31], 0, v[176:177]
	s_mov_b32 m0, s62
	v_lshl_add_u64 v[216:217], s[36:37], 0, v[178:179]
	global_load_lds_dwordx4 v[214:215], off
	v_lshl_add_u64 v[214:215], s[30:31], 0, v[178:179]
	s_add_i32 m0, s62, 0x2000
	s_nop 0
	global_load_lds_dwordx4 v[214:215], off
	v_lshl_add_u64 v[214:215], s[36:37], 0, v[176:177]
	s_mov_b32 m0, s41
	s_nop 0
	global_load_lds_dwordx4 v[214:215], off
	s_mov_b32 m0, s42
	s_nop 0
	global_load_lds_dwordx4 v[216:217], off
	s_waitcnt vmcnt(8)
	s_waitcnt lgkmcnt(0)
	s_barrier
; #define PG8_STAGE(bufoff, gbase, voff) do { _Pragma("unroll") for (int _i = 0; _i < 2; ++_i) \
;         __builtin_amdgcn_global_load_lds((const unsigned*)((const char*)(gbase) + (voff)[_i]), (PG8_LAS unsigned*)(lds + (bufoff) + ldsw + _i * 8192), 16, 0, 0); } while (0)
; #define PG8_LDA(dst, b, h) do { _Pragma("unroll") for (int m = 0; m < 4; ++m) _Pragma("unroll") for (int k = 0; k < 2; ++k) dst[m][k] = *(const PG8_LAS bf16x8*)(lds + PG8_SA(b, h) + aoff + m * 2048 + k * 1024); } while (0)
; #define PG8_LDB(dst, b, h) do { _Pragma("unroll") for (int n = 0; n < 2; ++n) _Pragma("unroll") for (int k = 0; k < 2; ++k) dst[n][k] = *(const PG8_LAS bf16x8*)(lds + PG8_SB(b, h) + boff + n * 2048 + k * 1024); } while (0)
; #define PG8_MMA(ai, bj, At, Bt) do { __builtin_amdgcn_s_setprio(1); _Pragma("unroll") for (int m = 0; m < 4; ++m) _Pragma("unroll") for (int n = 0; n < 2; ++n) _Pragma("unroll") for (int k = 0; k < 2; ++k) \
;         acc[ai][bj][m][n] = __builtin_amdgcn_mfma_f32_16x16x32_bf16(Bt[n][k], At[m][k], acc[ai][bj][m][n], 0, 0, 0); __builtin_amdgcn_s_setprio(0); } while (0)
; #define PG8_WAIT_V(n) asm volatile("s_waitcnt vmcnt(" #n ")" ::: "memory")
; #define PG8_WAIT_L(n) asm volatile("s_waitcnt lgkmcnt(" #n ")" ::: "memory")
; #define PG8_BAR __builtin_amdgcn_s_barrier()
; #define PG8_SCHED __builtin_amdgcn_sched_barrier(0)
; template <class Epi, class Sched, bool ALIGN_EPI = false, bool SP2 = false>
; __device__ __forceinline__ void gemm_phase(PG8_LAS unsigned char* lds, const Gemm g, const Sched& S, const Epi& E, const int wid) {
;     ...
;             PG8_WAIT_V(8); PG8_WAIT_L(0); PG8_BAR; PG8_MMA(1, 0, At, B0); PG8_MMA(1, 1, At, B1); PG8_BAR; PG8_SCHED;
;             PG8_LDB(B0, 1, 0); PG8_LDB(B1, 1, 1); PG8_SCHED; PG8_LDA(At, 1, 0); PG8_STAGE(PG8_SA(0, 1), a2 + hsA, voffA);
;             PG8_WAIT_V(8); PG8_WAIT_L(0); PG8_BAR; PG8_MMA(0, 0, At, B0); PG8_MMA(0, 1, At, B1); PG8_BAR; PG8_SCHED;
	s_waitcnt lgkmcnt(0)
	v_mfma_f32_16x16x32_bf16 v[60:63], v[64:67], v[160:163], v[60:63]
	v_mfma_f32_16x16x32_bf16 v[56:59], v[80:83], v[160:163], v[56:59]
	v_mfma_f32_16x16x32_bf16 v[44:47], v[64:67], v[168:171], v[44:47]
	v_mfma_f32_16x16x32_bf16 v[40:43], v[80:83], v[168:171], v[40:43]
	v_mfma_f32_16x16x32_bf16 v[28:31], v[64:67], v[188:191], v[28:31]
	v_mfma_f32_16x16x32_bf16 v[24:27], v[80:83], v[188:191], v[24:27]
	v_mfma_f32_16x16x32_bf16 v[12:15], v[64:67], v[202:205], v[12:15]
	v_mfma_f32_16x16x32_bf16 v[8:11], v[80:83], v[202:205], v[8:11]
	v_mfma_f32_16x16x32_bf16 v[60:63], v[72:75], v[164:167], v[60:63]
	v_mfma_f32_16x16x32_bf16 v[56:59], v[84:87], v[164:167], v[56:59]
	v_mfma_f32_16x16x32_bf16 v[44:47], v[72:75], v[172:175], v[44:47]
	v_mfma_f32_16x16x32_bf16 v[40:43], v[84:87], v[172:175], v[40:43]
	v_mfma_f32_16x16x32_bf16 v[28:31], v[72:75], v[192:195], v[28:31]
	v_mfma_f32_16x16x32_bf16 v[24:27], v[84:87], v[192:195], v[24:27]
	v_mfma_f32_16x16x32_bf16 v[12:15], v[72:75], v[206:209], v[12:15]
	v_mfma_f32_16x16x32_bf16 v[8:11], v[84:87], v[206:209], v[8:11]
	v_mfma_f32_16x16x32_bf16 v[52:55], v[88:91], v[160:163], v[52:55]
	v_mfma_f32_16x16x32_bf16 v[48:51], v[100:103], v[160:163], v[48:51]
	v_mfma_f32_16x16x32_bf16 v[36:39], v[88:91], v[168:171], v[36:39]
	v_mfma_f32_16x16x32_bf16 v[32:35], v[100:103], v[168:171], v[32:35]
	v_mfma_f32_16x16x32_bf16 v[20:23], v[88:91], v[188:191], v[20:23]
	v_mfma_f32_16x16x32_bf16 v[16:19], v[100:103], v[188:191], v[16:19]
	v_mfma_f32_16x16x32_bf16 v[4:7], v[88:91], v[202:205], v[4:7]
	v_mfma_f32_16x16x32_bf16 v[0:3], v[100:103], v[202:205], v[0:3]
	v_mfma_f32_16x16x32_bf16 v[52:55], v[92:95], v[164:167], v[52:55]
	v_mfma_f32_16x16x32_bf16 v[48:51], v[104:107], v[164:167], v[48:51]
	v_mfma_f32_16x16x32_bf16 v[36:39], v[92:95], v[172:175], v[36:39]
	v_mfma_f32_16x16x32_bf16 v[32:35], v[104:107], v[172:175], v[32:35]
	v_mfma_f32_16x16x32_bf16 v[20:23], v[92:95], v[192:195], v[20:23]
	v_mfma_f32_16x16x32_bf16 v[16:19], v[104:107], v[192:195], v[16:19]
	v_mfma_f32_16x16x32_bf16 v[4:7], v[92:95], v[206:209], v[4:7]
	v_mfma_f32_16x16x32_bf16 v[0:3], v[104:107], v[206:209], v[0:3]
	s_barrier
	s_add_i32 s62, 0, 0x18000
	s_add_i32 s63, 0, 0x1c000
	v_add_u32_e32 v84, s62, v196
	v_add_u32_e32 v104, s63, v196
	ds_read_b128 v[64:67], v84
	ds_read_b128 v[72:75], v84 offset:1024
	ds_read_b128 v[80:83], v84 offset:2048
	ds_read_b128 v[84:87], v84 offset:3072
	ds_read_b128 v[88:91], v104
	ds_read_b128 v[92:95], v104 offset:1024
	ds_read_b128 v[100:103], v104 offset:2048
	ds_read_b128 v[104:107], v104 offset:3072
	s_add_u32 s30, s36, 0x160000
	s_addc_u32 s31, s37, 0
	s_mov_b32 m0, s43
	v_lshl_add_u64 v[218:219], s[30:31], 0, v[176:177]
	ds_read_b128 v[160:163], v199 offset:32768
	ds_read_b128 v[164:167], v199 offset:33792
	ds_read_b128 v[168:171], v199 offset:34816
	ds_read_b128 v[172:175], v199 offset:35840
	ds_read_b128 v[188:191], v199 offset:36864
	ds_read_b128 v[192:195], v199 offset:37888
	ds_read_b128 v[202:205], v199 offset:38912
	ds_read_b128 v[206:209], v199 offset:39936
	global_load_lds_dwordx4 v[218:219], off
	v_lshl_add_u64 v[218:219], s[30:31], 0, v[178:179]
	s_mov_b32 m0, s44
	s_nop 0
	global_load_lds_dwordx4 v[218:219], off
	s_waitcnt vmcnt(8)
	s_waitcnt lgkmcnt(0)
	s_barrier
	s_waitcnt lgkmcnt(0)
	v_mfma_f32_16x16x32_bf16 v[156:159], v[64:67], v[160:163], v[156:159]
	v_mfma_f32_16x16x32_bf16 v[152:155], v[80:83], v[160:163], v[152:155]
	v_mfma_f32_16x16x32_bf16 v[140:143], v[64:67], v[168:171], v[140:143]
	v_mfma_f32_16x16x32_bf16 v[136:139], v[80:83], v[168:171], v[136:139]
	v_mfma_f32_16x16x32_bf16 v[124:127], v[64:67], v[188:191], v[124:127]
	v_mfma_f32_16x16x32_bf16 v[120:123], v[80:83], v[188:191], v[120:123]
	v_mfma_f32_16x16x32_bf16 v[108:111], v[64:67], v[202:205], v[108:111]
	v_mfma_f32_16x16x32_bf16 v[96:99], v[80:83], v[202:205], v[96:99]
	v_mfma_f32_16x16x32_bf16 v[156:159], v[72:75], v[164:167], v[156:159]
	v_mfma_f32_16x16x32_bf16 v[152:155], v[84:87], v[164:167], v[152:155]
	v_mfma_f32_16x16x32_bf16 v[140:143], v[72:75], v[172:175], v[140:143]
	v_mfma_f32_16x16x32_bf16 v[136:139], v[84:87], v[172:175], v[136:139]
	v_mfma_f32_16x16x32_bf16 v[124:127], v[72:75], v[192:195], v[124:127]
	v_mfma_f32_16x16x32_bf16 v[120:123], v[84:87], v[192:195], v[120:123]
	v_mfma_f32_16x16x32_bf16 v[108:111], v[72:75], v[206:209], v[108:111]
	v_mfma_f32_16x16x32_bf16 v[96:99], v[84:87], v[206:209], v[96:99]
	v_mfma_f32_16x16x32_bf16 v[148:151], v[88:91], v[160:163], v[148:151]
	v_mfma_f32_16x16x32_bf16 v[144:147], v[100:103], v[160:163], v[144:147]
	v_mfma_f32_16x16x32_bf16 v[132:135], v[88:91], v[168:171], v[132:135]
	v_mfma_f32_16x16x32_bf16 v[128:131], v[100:103], v[168:171], v[128:131]
	v_mfma_f32_16x16x32_bf16 v[116:119], v[88:91], v[188:191], v[116:119]
	v_mfma_f32_16x16x32_bf16 v[112:115], v[100:103], v[188:191], v[112:115]
	v_mfma_f32_16x16x32_bf16 v[76:79], v[88:91], v[202:205], v[76:79]
	v_mfma_f32_16x16x32_bf16 v[68:71], v[100:103], v[202:205], v[68:71]
	v_mfma_f32_16x16x32_bf16 v[148:151], v[92:95], v[164:167], v[148:151]
	v_mfma_f32_16x16x32_bf16 v[144:147], v[104:107], v[164:167], v[144:147]
	v_mfma_f32_16x16x32_bf16 v[132:135], v[92:95], v[172:175], v[132:135]
	v_mfma_f32_16x16x32_bf16 v[128:131], v[104:107], v[172:175], v[128:131]
	v_mfma_f32_16x16x32_bf16 v[116:119], v[92:95], v[192:195], v[116:119]
	v_mfma_f32_16x16x32_bf16 v[112:115], v[104:107], v[192:195], v[112:115]
	v_mfma_f32_16x16x32_bf16 v[76:79], v[92:95], v[206:209], v[76:79]
	v_mfma_f32_16x16x32_bf16 v[68:71], v[104:107], v[206:209], v[68:71]
	s_barrier
; #define PG8_STAGE(bufoff, gbase, voff) do { _Pragma("unroll") for (int _i = 0; _i < 2; ++_i) \
;         __builtin_amdgcn_global_load_lds((const unsigned*)((const char*)(gbase) + (voff)[_i]), (PG8_LAS unsigned*)(lds + (bufoff) + ldsw + _i * 8192), 16, 0, 0); } while (0)
; #define PG8_LDA(dst, b, h) do { _Pragma("unroll") for (int m = 0; m < 4; ++m) _Pragma("unroll") for (int k = 0; k < 2; ++k) dst[m][k] = *(const PG8_LAS bf16x8*)(lds + PG8_SA(b, h) + aoff + m * 2048 + k * 1024); } while (0)
; #define PG8_MMA(ai, bj, At, Bt) do { __builtin_amdgcn_s_setprio(1); _Pragma("unroll") for (int m = 0; m < 4; ++m) _Pragma("unroll") for (int n = 0; n < 2; ++n) _Pragma("unroll") for (int k = 0; k < 2; ++k) \
;         acc[ai][bj][m][n] = __builtin_amdgcn_mfma_f32_16x16x32_bf16(Bt[n][k], At[m][k], acc[ai][bj][m][n], 0, 0, 0); __builtin_amdgcn_s_setprio(0); } while (0)
; #define PG8_WAIT_V(n) asm volatile("s_waitcnt vmcnt(" #n ")" ::: "memory")
; #define PG8_WAIT_L(n) asm volatile("s_waitcnt lgkmcnt(" #n ")" ::: "memory")
; #define PG8_BAR __builtin_amdgcn_s_barrier()
; #define PG8_SCHED __builtin_amdgcn_sched_barrier(0)
; template <class Epi, class Sched, bool ALIGN_EPI = false, bool SP2 = false>
; __device__ __forceinline__ void gemm_phase(PG8_LAS unsigned char* lds, const Gemm g, const Sched& S, const Epi& E, const int wid) {
;     ...
;             PG8_LDA(At, 1, 1); PG8_STAGE(PG8_SB(1, 0), b3, voffB); PG8_STAGE(PG8_SB(1, 1), b3 + hsB, voffB); PG8_STAGE(PG8_SA(1, 0), a3, voffA);
;             PG8_WAIT_V(8); PG8_WAIT_L(0); PG8_BAR; PG8_MMA(1, 0, At, B0); PG8_MMA(1, 1, At, B1); PG8_BAR; PG8_SCHED;
	s_add_i32 s30, s62, s40
	v_lshl_add_u64 v[210:211], v[210:211], 0, s[22:23]
	s_mov_b32 m0, s30
	ds_read_b128 v[160:163], v199 offset:49152
	ds_read_b128 v[164:167], v199 offset:50176
	ds_read_b128 v[168:171], v199 offset:51200
	ds_read_b128 v[172:175], v199 offset:52224
	ds_read_b128 v[188:191], v199 offset:53248
	ds_read_b128 v[192:195], v199 offset:54272
	ds_read_b128 v[202:205], v199 offset:55296
	ds_read_b128 v[206:209], v199 offset:56320
	global_load_lds_dwordx4 v[210:211], off
	s_add_i32 m0, s30, 0x2000
	s_add_u32 s30, s34, 0x160080
	v_lshl_add_u64 v[210:211], v[212:213], 0, s[22:23]
	s_addc_u32 s31, s35, 0
	s_add_i32 s34, s63, s40
	global_load_lds_dwordx4 v[210:211], off
	v_lshl_add_u64 v[210:211], s[30:31], 0, v[176:177]
	s_mov_b32 m0, s34
	s_nop 0
	global_load_lds_dwordx4 v[210:211], off
	v_lshl_add_u64 v[210:211], s[30:31], 0, v[178:179]
	s_add_i32 m0, s34, 0x2000
	s_nop 0
	global_load_lds_dwordx4 v[210:211], off
	v_lshl_add_u64 v[210:211], v[214:215], 0, s[22:23]
	s_mov_b32 m0, s48
	s_nop 0
	global_load_lds_dwordx4 v[210:211], off
	v_lshl_add_u64 v[210:211], v[216:217], 0, s[22:23]
	s_mov_b32 m0, s49
	s_nop 0
	global_load_lds_dwordx4 v[210:211], off
	s_waitcnt vmcnt(8)
	s_waitcnt lgkmcnt(0)
	s_barrier
	s_waitcnt lgkmcnt(0)
	v_mfma_f32_16x16x32_bf16 v[60:63], v[64:67], v[160:163], v[60:63]
	v_mfma_f32_16x16x32_bf16 v[56:59], v[80:83], v[160:163], v[56:59]
	v_mfma_f32_16x16x32_bf16 v[44:47], v[64:67], v[168:171], v[44:47]
	v_mfma_f32_16x16x32_bf16 v[40:43], v[80:83], v[168:171], v[40:43]
	v_mfma_f32_16x16x32_bf16 v[28:31], v[64:67], v[188:191], v[28:31]
	v_mfma_f32_16x16x32_bf16 v[24:27], v[80:83], v[188:191], v[24:27]
	v_mfma_f32_16x16x32_bf16 v[12:15], v[64:67], v[202:205], v[12:15]
	v_mfma_f32_16x16x32_bf16 v[8:11], v[80:83], v[202:205], v[8:11]
	v_mfma_f32_16x16x32_bf16 v[60:63], v[72:75], v[164:167], v[60:63]
	v_mfma_f32_16x16x32_bf16 v[56:59], v[84:87], v[164:167], v[56:59]
	v_mfma_f32_16x16x32_bf16 v[44:47], v[72:75], v[172:175], v[44:47]
	v_mfma_f32_16x16x32_bf16 v[40:43], v[84:87], v[172:175], v[40:43]
	v_mfma_f32_16x16x32_bf16 v[28:31], v[72:75], v[192:195], v[28:31]
	v_mfma_f32_16x16x32_bf16 v[24:27], v[84:87], v[192:195], v[24:27]
	v_mfma_f32_16x16x32_bf16 v[12:15], v[72:75], v[206:209], v[12:15]
	v_mfma_f32_16x16x32_bf16 v[8:11], v[84:87], v[206:209], v[8:11]
	v_mfma_f32_16x16x32_bf16 v[52:55], v[88:91], v[160:163], v[52:55]
	v_mfma_f32_16x16x32_bf16 v[48:51], v[100:103], v[160:163], v[48:51]
	v_mfma_f32_16x16x32_bf16 v[36:39], v[88:91], v[168:171], v[36:39]
	v_mfma_f32_16x16x32_bf16 v[32:35], v[100:103], v[168:171], v[32:35]
	v_mfma_f32_16x16x32_bf16 v[20:23], v[88:91], v[188:191], v[20:23]
	v_mfma_f32_16x16x32_bf16 v[16:19], v[100:103], v[188:191], v[16:19]
	v_mfma_f32_16x16x32_bf16 v[4:7], v[88:91], v[202:205], v[4:7]
	v_mfma_f32_16x16x32_bf16 v[0:3], v[100:103], v[202:205], v[0:3]
	v_mfma_f32_16x16x32_bf16 v[52:55], v[92:95], v[164:167], v[52:55]
	v_mfma_f32_16x16x32_bf16 v[48:51], v[104:107], v[164:167], v[48:51]
	v_mfma_f32_16x16x32_bf16 v[36:39], v[92:95], v[172:175], v[36:39]
	v_mfma_f32_16x16x32_bf16 v[32:35], v[104:107], v[172:175], v[32:35]
	v_mfma_f32_16x16x32_bf16 v[20:23], v[92:95], v[192:195], v[20:23]
	v_mfma_f32_16x16x32_bf16 v[16:19], v[104:107], v[192:195], v[16:19]
	v_mfma_f32_16x16x32_bf16 v[4:7], v[92:95], v[206:209], v[4:7]
	v_mfma_f32_16x16x32_bf16 v[0:3], v[104:107], v[206:209], v[0:3]
	s_barrier
	s_add_i32 s61, s61, 2
	s_add_u32 s59, s59, 0x100
	s_addc_u32 s60, s60, 0
	s_cmpk_gt_u32 s61, 0x55
	s_mov_b64 s[30:31], s[4:5]
	s_cbranch_scc0 .LBB0_497
	s_and_b64 vcc, exec, s[24:25]
	s_cbranch_vccz .LBB0_500
	s_barrier

; #define PG8_STAGE(bufoff, gbase, voff) do { _Pragma("unroll") for (int _i = 0; _i < 2; ++_i) \
;         __builtin_amdgcn_global_load_lds((const unsigned*)((const char*)(gbase) + (voff)[_i]), (PG8_LAS unsigned*)(lds + (bufoff) + ldsw + _i * 8192), 16, 0, 0); } while (0)
; #define PG8_LDA(dst, b, h) do { _Pragma("unroll") for (int m = 0; m < 4; ++m) _Pragma("unroll") for (int k = 0; k < 2; ++k) dst[m][k] = *(const PG8_LAS bf16x8*)(lds + PG8_SA(b, h) + aoff + m * 2048 + k * 1024); } while (0)
; #define PG8_LDB(dst, b, h) do { _Pragma("unroll") for (int n = 0; n < 2; ++n) _Pragma("unroll") for (int k = 0; k < 2; ++k) dst[n][k] = *(const PG8_LAS bf16x8*)(lds + PG8_SB(b, h) + boff + n * 2048 + k * 1024); } while (0)
; #define PG8_MMA(ai, bj, At, Bt) do { __builtin_amdgcn_s_setprio(1); _Pragma("unroll") for (int m = 0; m < 4; ++m) _Pragma("unroll") for (int n = 0; n < 2; ++n) _Pragma("unroll") for (int k = 0; k < 2; ++k) \
;         acc[ai][bj][m][n] = __builtin_amdgcn_mfma_f32_16x16x32_bf16(Bt[n][k], At[m][k], acc[ai][bj][m][n], 0, 0, 0); __builtin_amdgcn_s_setprio(0); } while (0)
; #define PG8_WAIT_V(n) asm volatile("s_waitcnt vmcnt(" #n ")" ::: "memory")
; #define PG8_WAIT_L(n) asm volatile("s_waitcnt lgkmcnt(" #n ")" ::: "memory")
; #define PG8_BAR __builtin_amdgcn_s_barrier()
; template <class Epi, class Sched, bool ALIGN_EPI = false, bool SP2 = false>
; __device__ __forceinline__ void gemm_phase(PG8_LAS unsigned char* lds, const Gemm g, const Sched& S, const Epi& E, const int wid) {
;     ...
;             const bool last = (t == nt - 2);
;             const char* a1 = cA + (size_t)(t + 1) * kstep;
;             const char* a2 = last ? nA : cA + (size_t)(t + 2) * kstep; const char* b2 = last ? nB : cB + (size_t)(t + 2) * kstep;
;             const char* a3 = a2 + kstep; const char* b3 = b2 + kstep;
;             if constexpr (SP2) {
;             PG8_LDB(B0, 0, 0); PG8_LDB(B1, 0, 1); PG8_SCHED; PG8_LDA(At, 0, 0); PG8_STAGE(PG8_SA(1, 1), a1 + hsA, voffA);
;             PG8_WAIT_V(8); PG8_WAIT_L(0); PG8_BAR; PG8_MMA(0, 0, At, B0); PG8_MMA(0, 1, At, B1); PG8_BAR; PG8_SCHED;
;             PG8_LDA(At, 0, 1); PG8_STAGE(PG8_SB(0, 0), b2, voffB); PG8_STAGE(PG8_SB(0, 1), b2 + hsB, voffB); PG8_STAGE(PG8_SA(0, 0), a2, voffA);
;             PG8_WAIT_V(8); PG8_WAIT_L(0); PG8_BAR; PG8_MMA(1, 0, At, B0); PG8_MMA(1, 1, At, B1); PG8_BAR; PG8_SCHED;
.LBB0_588:
	ds_read_b128 v[128:131], v237
	ds_read_b128 v[132:135], v237 offset:1024
	ds_read_b128 v[136:139], v237 offset:2048
	ds_read_b128 v[140:143], v237 offset:3072
	ds_read_b128 v[144:147], v238
	ds_read_b128 v[148:151], v238 offset:1024
	ds_read_b128 v[152:155], v238 offset:2048
	ds_read_b128 v[156:159], v238 offset:3072
	s_add_u32 s8, s6, 0xfff80080
	s_addc_u32 s9, s7, -1
	s_cmp_eq_u32 s87, 28
	s_cselect_b32 s53, s5, s9
	s_cselect_b32 s52, s47, s8
	s_cselect_b32 s9, s45, s86
	s_cselect_b32 s8, s54, s55
	v_lshl_add_u64 v[210:211], s[6:7], 0, v[180:181]
	s_add_i32 m0, s59, 0xc000
	ds_read_b128 v[160:163], v239
	ds_read_b128 v[164:167], v239 offset:1024
	ds_read_b128 v[186:189], v239 offset:2048
	ds_read_b128 v[190:193], v239 offset:3072
	ds_read_b128 v[194:197], v239 offset:4096
	ds_read_b128 v[198:201], v239 offset:5120
	ds_read_b128 v[202:205], v239 offset:6144
	ds_read_b128 v[206:209], v239 offset:7168
	global_load_lds_dwordx4 v[210:211], off
	v_lshl_add_u64 v[210:211], s[6:7], 0, v[178:179]
	s_add_i32 m0, s59, 0xe000
	s_nop 0
	global_load_lds_dwordx4 v[210:211], off
	s_waitcnt vmcnt(8)
	s_waitcnt lgkmcnt(0)
	s_barrier
	s_waitcnt lgkmcnt(0)
	v_mfma_f32_16x16x32_bf16 v[124:127], v[128:131], v[160:163], v[124:127]
	v_mfma_f32_16x16x32_bf16 v[120:123], v[136:139], v[160:163], v[120:123]
	v_mfma_f32_16x16x32_bf16 v[108:111], v[128:131], v[186:189], v[108:111]
	v_mfma_f32_16x16x32_bf16 v[104:107], v[136:139], v[186:189], v[104:107]
	v_mfma_f32_16x16x32_bf16 v[92:95], v[128:131], v[194:197], v[92:95]
	v_mfma_f32_16x16x32_bf16 v[88:91], v[136:139], v[194:197], v[88:91]
	v_mfma_f32_16x16x32_bf16 v[76:79], v[128:131], v[202:205], v[76:79]
	v_mfma_f32_16x16x32_bf16 v[72:75], v[136:139], v[202:205], v[72:75]
	v_mfma_f32_16x16x32_bf16 v[124:127], v[132:135], v[164:167], v[124:127]
	v_mfma_f32_16x16x32_bf16 v[120:123], v[140:143], v[164:167], v[120:123]
	v_mfma_f32_16x16x32_bf16 v[108:111], v[132:135], v[190:193], v[108:111]
	v_mfma_f32_16x16x32_bf16 v[104:107], v[140:143], v[190:193], v[104:107]
	v_mfma_f32_16x16x32_bf16 v[92:95], v[132:135], v[198:201], v[92:95]
	v_mfma_f32_16x16x32_bf16 v[88:91], v[140:143], v[198:201], v[88:91]
	v_mfma_f32_16x16x32_bf16 v[76:79], v[132:135], v[206:209], v[76:79]
	v_mfma_f32_16x16x32_bf16 v[72:75], v[140:143], v[206:209], v[72:75]
	v_mfma_f32_16x16x32_bf16 v[116:119], v[144:147], v[160:163], v[116:119]
	v_mfma_f32_16x16x32_bf16 v[112:115], v[152:155], v[160:163], v[112:115]
	v_mfma_f32_16x16x32_bf16 v[100:103], v[144:147], v[186:189], v[100:103]
	v_mfma_f32_16x16x32_bf16 v[96:99], v[152:155], v[186:189], v[96:99]
	v_mfma_f32_16x16x32_bf16 v[84:87], v[144:147], v[194:197], v[84:87]
	v_mfma_f32_16x16x32_bf16 v[80:83], v[152:155], v[194:197], v[80:83]
	v_mfma_f32_16x16x32_bf16 v[68:71], v[144:147], v[202:205], v[68:71]
	v_mfma_f32_16x16x32_bf16 v[64:67], v[152:155], v[202:205], v[64:67]
	v_mfma_f32_16x16x32_bf16 v[116:119], v[148:151], v[164:167], v[116:119]
	v_mfma_f32_16x16x32_bf16 v[112:115], v[156:159], v[164:167], v[112:115]
	v_mfma_f32_16x16x32_bf16 v[100:103], v[148:151], v[190:193], v[100:103]
	v_mfma_f32_16x16x32_bf16 v[96:99], v[156:159], v[190:193], v[96:99]
	v_mfma_f32_16x16x32_bf16 v[84:87], v[148:151], v[198:201], v[84:87]
	v_mfma_f32_16x16x32_bf16 v[80:83], v[156:159], v[198:201], v[80:83]
	v_mfma_f32_16x16x32_bf16 v[68:71], v[148:151], v[206:209], v[68:71]
	v_mfma_f32_16x16x32_bf16 v[64:67], v[156:159], v[206:209], v[64:67]
	s_barrier
	s_add_i32 s88, s81, s58
	v_lshl_add_u64 v[210:211], s[8:9], 0, v[170:171]
	s_mov_b32 m0, s88
	ds_read_b128 v[160:163], v239 offset:16384
	ds_read_b128 v[164:167], v239 offset:17408
	ds_read_b128 v[186:189], v239 offset:18432
	ds_read_b128 v[190:193], v239 offset:19456
	ds_read_b128 v[194:197], v239 offset:20480
	ds_read_b128 v[198:201], v239 offset:21504
	ds_read_b128 v[202:205], v239 offset:22528
	ds_read_b128 v[206:209], v239 offset:23552
	global_load_lds_dwordx4 v[210:211], off
	s_add_i32 m0, s88, 0x2000
	s_add_u32 s88, s8, 0x80000
	v_lshl_add_u64 v[212:213], s[8:9], 0, v[174:175]
	s_addc_u32 s89, s9, 0
	s_add_i32 s90, s82, s58
	global_load_lds_dwordx4 v[212:213], off
	v_lshl_add_u64 v[214:215], s[88:89], 0, v[170:171]
	s_mov_b32 m0, s90
	v_lshl_add_u64 v[216:217], s[52:53], 0, v[172:173]
	global_load_lds_dwordx4 v[214:215], off
	v_lshl_add_u64 v[214:215], s[88:89], 0, v[174:175]
	s_add_i32 m0, s90, 0x2000
	s_nop 0
	global_load_lds_dwordx4 v[214:215], off
	v_lshl_add_u64 v[214:215], s[52:53], 0, v[168:169]
	s_mov_b32 m0, s59
	s_nop 0
	global_load_lds_dwordx4 v[214:215], off
	s_mov_b32 m0, s60
	s_nop 0
	global_load_lds_dwordx4 v[216:217], off
	s_waitcnt vmcnt(8)
	s_waitcnt lgkmcnt(0)
	s_barrier
; #define PG8_STAGE(bufoff, gbase, voff) do { _Pragma("unroll") for (int _i = 0; _i < 2; ++_i) \
;         __builtin_amdgcn_global_load_lds((const unsigned*)((const char*)(gbase) + (voff)[_i]), (PG8_LAS unsigned*)(lds + (bufoff) + ldsw + _i * 8192), 16, 0, 0); } while (0)
; #define PG8_LDA(dst, b, h) do { _Pragma("unroll") for (int m = 0; m < 4; ++m) _Pragma("unroll") for (int k = 0; k < 2; ++k) dst[m][k] = *(const PG8_LAS bf16x8*)(lds + PG8_SA(b, h) + aoff + m * 2048 + k * 1024); } while (0)
; #define PG8_LDB(dst, b, h) do { _Pragma("unroll") for (int n = 0; n < 2; ++n) _Pragma("unroll") for (int k = 0; k < 2; ++k) dst[n][k] = *(const PG8_LAS bf16x8*)(lds + PG8_SB(b, h) + boff + n * 2048 + k * 1024); } while (0)
; #define PG8_MMA(ai, bj, At, Bt) do { __builtin_amdgcn_s_setprio(1); _Pragma("unroll") for (int m = 0; m < 4; ++m) _Pragma("unroll") for (int n = 0; n < 2; ++n) _Pragma("unroll") for (int k = 0; k < 2; ++k) \
;         acc[ai][bj][m][n] = __builtin_amdgcn_mfma_f32_16x16x32_bf16(Bt[n][k], At[m][k], acc[ai][bj][m][n], 0, 0, 0); __builtin_amdgcn_s_setprio(0); } while (0)
; #define PG8_WAIT_V(n) asm volatile("s_waitcnt vmcnt(" #n ")" ::: "memory")
; #define PG8_WAIT_L(n) asm volatile("s_waitcnt lgkmcnt(" #n ")" ::: "memory")
; #define PG8_BAR __builtin_amdgcn_s_barrier()
; #define PG8_SCHED __builtin_amdgcn_sched_barrier(0)
; template <class Epi, class Sched, bool ALIGN_EPI = false, bool SP2 = false>
; __device__ __forceinline__ void gemm_phase(PG8_LAS unsigned char* lds, const Gemm g, const Sched& S, const Epi& E, const int wid) {
;     ...
;             PG8_WAIT_V(8); PG8_WAIT_L(0); PG8_BAR; PG8_MMA(1, 0, At, B0); PG8_MMA(1, 1, At, B1); PG8_BAR; PG8_SCHED;
;             PG8_LDB(B0, 1, 0); PG8_LDB(B1, 1, 1); PG8_SCHED; PG8_LDA(At, 1, 0); PG8_STAGE(PG8_SA(0, 1), a2 + hsA, voffA);
;             PG8_WAIT_V(8); PG8_WAIT_L(0); PG8_BAR; PG8_MMA(0, 0, At, B0); PG8_MMA(0, 1, At, B1); PG8_BAR; PG8_SCHED;
	s_waitcnt lgkmcnt(0)
	v_mfma_f32_16x16x32_bf16 v[60:63], v[128:131], v[160:163], v[60:63]
	v_mfma_f32_16x16x32_bf16 v[56:59], v[136:139], v[160:163], v[56:59]
	v_mfma_f32_16x16x32_bf16 v[44:47], v[128:131], v[186:189], v[44:47]
	v_mfma_f32_16x16x32_bf16 v[40:43], v[136:139], v[186:189], v[40:43]
	v_mfma_f32_16x16x32_bf16 v[28:31], v[128:131], v[194:197], v[28:31]
	v_mfma_f32_16x16x32_bf16 v[24:27], v[136:139], v[194:197], v[24:27]
	v_mfma_f32_16x16x32_bf16 v[12:15], v[128:131], v[202:205], v[12:15]
	v_mfma_f32_16x16x32_bf16 v[8:11], v[136:139], v[202:205], v[8:11]
	v_mfma_f32_16x16x32_bf16 v[60:63], v[132:135], v[164:167], v[60:63]
	v_mfma_f32_16x16x32_bf16 v[56:59], v[140:143], v[164:167], v[56:59]
	v_mfma_f32_16x16x32_bf16 v[44:47], v[132:135], v[190:193], v[44:47]
	v_mfma_f32_16x16x32_bf16 v[40:43], v[140:143], v[190:193], v[40:43]
	v_mfma_f32_16x16x32_bf16 v[28:31], v[132:135], v[198:201], v[28:31]
	v_mfma_f32_16x16x32_bf16 v[24:27], v[140:143], v[198:201], v[24:27]
	v_mfma_f32_16x16x32_bf16 v[12:15], v[132:135], v[206:209], v[12:15]
	v_mfma_f32_16x16x32_bf16 v[8:11], v[140:143], v[206:209], v[8:11]
	v_mfma_f32_16x16x32_bf16 v[52:55], v[144:147], v[160:163], v[52:55]
	v_mfma_f32_16x16x32_bf16 v[48:51], v[152:155], v[160:163], v[48:51]
	v_mfma_f32_16x16x32_bf16 v[36:39], v[144:147], v[186:189], v[36:39]
	v_mfma_f32_16x16x32_bf16 v[32:35], v[152:155], v[186:189], v[32:35]
	v_mfma_f32_16x16x32_bf16 v[20:23], v[144:147], v[194:197], v[20:23]
	v_mfma_f32_16x16x32_bf16 v[16:19], v[152:155], v[194:197], v[16:19]
	v_mfma_f32_16x16x32_bf16 v[4:7], v[144:147], v[202:205], v[4:7]
	v_mfma_f32_16x16x32_bf16 v[0:3], v[152:155], v[202:205], v[0:3]
	v_mfma_f32_16x16x32_bf16 v[52:55], v[148:151], v[164:167], v[52:55]
	v_mfma_f32_16x16x32_bf16 v[48:51], v[156:159], v[164:167], v[48:51]
	v_mfma_f32_16x16x32_bf16 v[36:39], v[148:151], v[190:193], v[36:39]
	v_mfma_f32_16x16x32_bf16 v[32:35], v[156:159], v[190:193], v[32:35]
	v_mfma_f32_16x16x32_bf16 v[20:23], v[148:151], v[198:201], v[20:23]
	v_mfma_f32_16x16x32_bf16 v[16:19], v[156:159], v[198:201], v[16:19]
	v_mfma_f32_16x16x32_bf16 v[4:7], v[148:151], v[206:209], v[4:7]
	v_mfma_f32_16x16x32_bf16 v[0:3], v[156:159], v[206:209], v[0:3]
	s_barrier
	s_add_i32 s88, 0, 0x18000
	s_add_i32 s89, 0, 0x1c000
	v_add_u32_e32 v140, s88, v236
	v_add_u32_e32 v156, s89, v236
	ds_read_b128 v[128:131], v140
	ds_read_b128 v[132:135], v140 offset:1024
	ds_read_b128 v[136:139], v140 offset:2048
	ds_read_b128 v[140:143], v140 offset:3072
	ds_read_b128 v[144:147], v156
	ds_read_b128 v[148:151], v156 offset:1024
	ds_read_b128 v[152:155], v156 offset:2048
	ds_read_b128 v[156:159], v156 offset:3072
	s_add_u32 s52, s52, 0x80000
	s_addc_u32 s53, s53, 0
	s_mov_b32 m0, s61
	v_lshl_add_u64 v[218:219], s[52:53], 0, v[168:169]
	ds_read_b128 v[160:163], v239 offset:32768
	ds_read_b128 v[164:167], v239 offset:33792
	ds_read_b128 v[186:189], v239 offset:34816
	ds_read_b128 v[190:193], v239 offset:35840
	ds_read_b128 v[194:197], v239 offset:36864
	ds_read_b128 v[198:201], v239 offset:37888
	ds_read_b128 v[202:205], v239 offset:38912
	ds_read_b128 v[206:209], v239 offset:39936
	global_load_lds_dwordx4 v[218:219], off
	v_lshl_add_u64 v[218:219], s[52:53], 0, v[172:173]
	s_mov_b32 m0, s62
	s_nop 0
	global_load_lds_dwordx4 v[218:219], off
	s_waitcnt vmcnt(8)
	s_waitcnt lgkmcnt(0)
	s_barrier
	s_waitcnt lgkmcnt(0)
	v_mfma_f32_16x16x32_bf16 v[124:127], v[128:131], v[160:163], v[124:127]
	v_mfma_f32_16x16x32_bf16 v[120:123], v[136:139], v[160:163], v[120:123]
	v_mfma_f32_16x16x32_bf16 v[108:111], v[128:131], v[186:189], v[108:111]
	v_mfma_f32_16x16x32_bf16 v[104:107], v[136:139], v[186:189], v[104:107]
	v_mfma_f32_16x16x32_bf16 v[92:95], v[128:131], v[194:197], v[92:95]
	v_mfma_f32_16x16x32_bf16 v[88:91], v[136:139], v[194:197], v[88:91]
	v_mfma_f32_16x16x32_bf16 v[76:79], v[128:131], v[202:205], v[76:79]
	v_mfma_f32_16x16x32_bf16 v[72:75], v[136:139], v[202:205], v[72:75]
	v_mfma_f32_16x16x32_bf16 v[124:127], v[132:135], v[164:167], v[124:127]
	v_mfma_f32_16x16x32_bf16 v[120:123], v[140:143], v[164:167], v[120:123]
	v_mfma_f32_16x16x32_bf16 v[108:111], v[132:135], v[190:193], v[108:111]
	v_mfma_f32_16x16x32_bf16 v[104:107], v[140:143], v[190:193], v[104:107]
	v_mfma_f32_16x16x32_bf16 v[92:95], v[132:135], v[198:201], v[92:95]
	v_mfma_f32_16x16x32_bf16 v[88:91], v[140:143], v[198:201], v[88:91]
	v_mfma_f32_16x16x32_bf16 v[76:79], v[132:135], v[206:209], v[76:79]
	v_mfma_f32_16x16x32_bf16 v[72:75], v[140:143], v[206:209], v[72:75]
	v_mfma_f32_16x16x32_bf16 v[116:119], v[144:147], v[160:163], v[116:119]
	v_mfma_f32_16x16x32_bf16 v[112:115], v[152:155], v[160:163], v[112:115]
	v_mfma_f32_16x16x32_bf16 v[100:103], v[144:147], v[186:189], v[100:103]
	v_mfma_f32_16x16x32_bf16 v[96:99], v[152:155], v[186:189], v[96:99]
	v_mfma_f32_16x16x32_bf16 v[84:87], v[144:147], v[194:197], v[84:87]
	v_mfma_f32_16x16x32_bf16 v[80:83], v[152:155], v[194:197], v[80:83]
	v_mfma_f32_16x16x32_bf16 v[68:71], v[144:147], v[202:205], v[68:71]
	v_mfma_f32_16x16x32_bf16 v[64:67], v[152:155], v[202:205], v[64:67]
	v_mfma_f32_16x16x32_bf16 v[116:119], v[148:151], v[164:167], v[116:119]
	v_mfma_f32_16x16x32_bf16 v[112:115], v[156:159], v[164:167], v[112:115]
	v_mfma_f32_16x16x32_bf16 v[100:103], v[148:151], v[190:193], v[100:103]
	v_mfma_f32_16x16x32_bf16 v[96:99], v[156:159], v[190:193], v[96:99]
	v_mfma_f32_16x16x32_bf16 v[84:87], v[148:151], v[198:201], v[84:87]
	v_mfma_f32_16x16x32_bf16 v[80:83], v[156:159], v[198:201], v[80:83]
	v_mfma_f32_16x16x32_bf16 v[68:71], v[148:151], v[206:209], v[68:71]
	v_mfma_f32_16x16x32_bf16 v[64:67], v[156:159], v[206:209], v[64:67]
	s_barrier
; #define PG8_STAGE(bufoff, gbase, voff) do { _Pragma("unroll") for (int _i = 0; _i < 2; ++_i) \
;         __builtin_amdgcn_global_load_lds((const unsigned*)((const char*)(gbase) + (voff)[_i]), (PG8_LAS unsigned*)(lds + (bufoff) + ldsw + _i * 8192), 16, 0, 0); } while (0)
; #define PG8_LDA(dst, b, h) do { _Pragma("unroll") for (int m = 0; m < 4; ++m) _Pragma("unroll") for (int k = 0; k < 2; ++k) dst[m][k] = *(const PG8_LAS bf16x8*)(lds + PG8_SA(b, h) + aoff + m * 2048 + k * 1024); } while (0)
; #define PG8_MMA(ai, bj, At, Bt) do { __builtin_amdgcn_s_setprio(1); _Pragma("unroll") for (int m = 0; m < 4; ++m) _Pragma("unroll") for (int n = 0; n < 2; ++n) _Pragma("unroll") for (int k = 0; k < 2; ++k) \
;         acc[ai][bj][m][n] = __builtin_amdgcn_mfma_f32_16x16x32_bf16(Bt[n][k], At[m][k], acc[ai][bj][m][n], 0, 0, 0); __builtin_amdgcn_s_setprio(0); } while (0)
; #define PG8_WAIT_V(n) asm volatile("s_waitcnt vmcnt(" #n ")" ::: "memory")
; #define PG8_WAIT_L(n) asm volatile("s_waitcnt lgkmcnt(" #n ")" ::: "memory")
; #define PG8_BAR __builtin_amdgcn_s_barrier()
; #define PG8_SCHED __builtin_amdgcn_sched_barrier(0)
; template <class Epi, class Sched, bool ALIGN_EPI = false, bool SP2 = false>
; __device__ __forceinline__ void gemm_phase(PG8_LAS unsigned char* lds, const Gemm g, const Sched& S, const Epi& E, const int wid) {
;     ...
;         for (int t = 0; t < nt; t += 2) {
;     ...
;             PG8_LDA(At, 1, 1); PG8_STAGE(PG8_SB(1, 0), b3, voffB); PG8_STAGE(PG8_SB(1, 1), b3 + hsB, voffB); PG8_STAGE(PG8_SA(1, 0), a3, voffA);
;             PG8_WAIT_V(8); PG8_WAIT_L(0); PG8_BAR; PG8_MMA(1, 0, At, B0); PG8_MMA(1, 1, At, B1); PG8_BAR; PG8_SCHED;
;     ...
;         if constexpr (ALIGN_EPI) { if (wr == 0) PG8_BAR; }
	s_add_i32 s52, s88, s58
	v_lshl_add_u64 v[210:211], v[210:211], 0, s[26:27]
	s_mov_b32 m0, s52
	ds_read_b128 v[160:163], v239 offset:49152
	ds_read_b128 v[164:167], v239 offset:50176
	ds_read_b128 v[186:189], v239 offset:51200
	ds_read_b128 v[190:193], v239 offset:52224
	ds_read_b128 v[194:197], v239 offset:53248
	ds_read_b128 v[198:201], v239 offset:54272
	ds_read_b128 v[202:205], v239 offset:55296
	ds_read_b128 v[206:209], v239 offset:56320
	global_load_lds_dwordx4 v[210:211], off
	s_add_i32 m0, s52, 0x2000
	s_add_u32 s8, s8, 0x80080
	v_lshl_add_u64 v[210:211], v[212:213], 0, s[26:27]
	s_addc_u32 s9, s9, 0
	s_add_i32 s52, s89, s58
	global_load_lds_dwordx4 v[210:211], off
	v_lshl_add_u64 v[210:211], s[8:9], 0, v[170:171]
	s_mov_b32 m0, s52
	s_nop 0
	global_load_lds_dwordx4 v[210:211], off
	v_lshl_add_u64 v[210:211], s[8:9], 0, v[174:175]
	s_add_i32 m0, s52, 0x2000
	s_nop 0
	global_load_lds_dwordx4 v[210:211], off
	v_lshl_add_u64 v[210:211], v[214:215], 0, s[26:27]
	s_mov_b32 m0, s73
	s_nop 0
	global_load_lds_dwordx4 v[210:211], off
	v_lshl_add_u64 v[210:211], v[216:217], 0, s[26:27]
	s_mov_b32 m0, s74
	s_nop 0
	global_load_lds_dwordx4 v[210:211], off
	s_waitcnt vmcnt(8)
	s_waitcnt lgkmcnt(0)
	s_barrier
	s_waitcnt lgkmcnt(0)
	v_mfma_f32_16x16x32_bf16 v[60:63], v[128:131], v[160:163], v[60:63]
	v_mfma_f32_16x16x32_bf16 v[56:59], v[136:139], v[160:163], v[56:59]
	v_mfma_f32_16x16x32_bf16 v[44:47], v[128:131], v[186:189], v[44:47]
	v_mfma_f32_16x16x32_bf16 v[40:43], v[136:139], v[186:189], v[40:43]
	v_mfma_f32_16x16x32_bf16 v[28:31], v[128:131], v[194:197], v[28:31]
	v_mfma_f32_16x16x32_bf16 v[24:27], v[136:139], v[194:197], v[24:27]
	v_mfma_f32_16x16x32_bf16 v[12:15], v[128:131], v[202:205], v[12:15]
	v_mfma_f32_16x16x32_bf16 v[8:11], v[136:139], v[202:205], v[8:11]
	v_mfma_f32_16x16x32_bf16 v[60:63], v[132:135], v[164:167], v[60:63]
	v_mfma_f32_16x16x32_bf16 v[56:59], v[140:143], v[164:167], v[56:59]
	v_mfma_f32_16x16x32_bf16 v[44:47], v[132:135], v[190:193], v[44:47]
	v_mfma_f32_16x16x32_bf16 v[40:43], v[140:143], v[190:193], v[40:43]
	v_mfma_f32_16x16x32_bf16 v[28:31], v[132:135], v[198:201], v[28:31]
	v_mfma_f32_16x16x32_bf16 v[24:27], v[140:143], v[198:201], v[24:27]
	v_mfma_f32_16x16x32_bf16 v[12:15], v[132:135], v[206:209], v[12:15]
	v_mfma_f32_16x16x32_bf16 v[8:11], v[140:143], v[206:209], v[8:11]
	v_mfma_f32_16x16x32_bf16 v[52:55], v[144:147], v[160:163], v[52:55]
	v_mfma_f32_16x16x32_bf16 v[48:51], v[152:155], v[160:163], v[48:51]
	v_mfma_f32_16x16x32_bf16 v[36:39], v[144:147], v[186:189], v[36:39]
	v_mfma_f32_16x16x32_bf16 v[32:35], v[152:155], v[186:189], v[32:35]
	v_mfma_f32_16x16x32_bf16 v[20:23], v[144:147], v[194:197], v[20:23]
	v_mfma_f32_16x16x32_bf16 v[16:19], v[152:155], v[194:197], v[16:19]
	v_mfma_f32_16x16x32_bf16 v[4:7], v[144:147], v[202:205], v[4:7]
	v_mfma_f32_16x16x32_bf16 v[0:3], v[152:155], v[202:205], v[0:3]
	v_mfma_f32_16x16x32_bf16 v[52:55], v[148:151], v[164:167], v[52:55]
	v_mfma_f32_16x16x32_bf16 v[48:51], v[156:159], v[164:167], v[48:51]
	v_mfma_f32_16x16x32_bf16 v[36:39], v[148:151], v[190:193], v[36:39]
	v_mfma_f32_16x16x32_bf16 v[32:35], v[156:159], v[190:193], v[32:35]
	v_mfma_f32_16x16x32_bf16 v[20:23], v[148:151], v[198:201], v[20:23]
	v_mfma_f32_16x16x32_bf16 v[16:19], v[156:159], v[198:201], v[16:19]
	v_mfma_f32_16x16x32_bf16 v[4:7], v[148:151], v[206:209], v[4:7]
	v_mfma_f32_16x16x32_bf16 v[0:3], v[156:159], v[206:209], v[0:3]
	s_barrier
	s_add_i32 s87, s87, 2
	s_add_u32 s55, s55, 0x100
	s_addc_u32 s86, s86, 0
	s_add_u32 s6, s6, 0x100
	s_addc_u32 s7, s7, 0
	s_cmp_gt_u32 s87, 29
	s_cbranch_scc0 .LBB0_588
	s_and_b64 vcc, exec, s[28:29]
	s_cbranch_vccz .LBB0_591
	s_barrier

; #define PG8_STAGE(bufoff, gbase, voff) do { _Pragma("unroll") for (int _i = 0; _i < 2; ++_i) \
;         __builtin_amdgcn_global_load_lds((const unsigned*)((const char*)(gbase) + (voff)[_i]), (PG8_LAS unsigned*)(lds + (bufoff) + ldsw + _i * 8192), 16, 0, 0); } while (0)
; #define PG8_LDA(dst, b, h) do { _Pragma("unroll") for (int m = 0; m < 4; ++m) _Pragma("unroll") for (int k = 0; k < 2; ++k) dst[m][k] = *(const PG8_LAS bf16x8*)(lds + PG8_SA(b, h) + aoff + m * 2048 + k * 1024); } while (0)
; #define PG8_LDB(dst, b, h) do { _Pragma("unroll") for (int n = 0; n < 2; ++n) _Pragma("unroll") for (int k = 0; k < 2; ++k) dst[n][k] = *(const PG8_LAS bf16x8*)(lds + PG8_SB(b, h) + boff + n * 2048 + k * 1024); } while (0)
; #define PG8_MMA(ai, bj, At, Bt) do { __builtin_amdgcn_s_setprio(1); _Pragma("unroll") for (int m = 0; m < 4; ++m) _Pragma("unroll") for (int n = 0; n < 2; ++n) _Pragma("unroll") for (int k = 0; k < 2; ++k) \
;         acc[ai][bj][m][n] = __builtin_amdgcn_mfma_f32_16x16x32_bf16(Bt[n][k], At[m][k], acc[ai][bj][m][n], 0, 0, 0); __builtin_amdgcn_s_setprio(0); } while (0)
; #define PG8_WAIT_V(n) asm volatile("s_waitcnt vmcnt(" #n ")" ::: "memory")
; #define PG8_WAIT_L(n) asm volatile("s_waitcnt lgkmcnt(" #n ")" ::: "memory")
; #define PG8_BAR __builtin_amdgcn_s_barrier()
; template <class Epi, class Sched, bool ALIGN_EPI = false, bool SP2 = false>
; __device__ __forceinline__ void gemm_phase(PG8_LAS unsigned char* lds, const Gemm g, const Sched& S, const Epi& E, const int wid) {
;     ...
;             const bool last = (t == nt - 2);
;             const char* a1 = cA + (size_t)(t + 1) * kstep;
;             const char* a2 = last ? nA : cA + (size_t)(t + 2) * kstep; const char* b2 = last ? nB : cB + (size_t)(t + 2) * kstep;
;             const char* a3 = a2 + kstep; const char* b3 = b2 + kstep;
;             if constexpr (SP2) {
;             PG8_LDB(B0, 0, 0); PG8_LDB(B1, 0, 1); PG8_SCHED; PG8_LDA(At, 0, 0); PG8_STAGE(PG8_SA(1, 1), a1 + hsA, voffA);
;             PG8_WAIT_V(8); PG8_WAIT_L(0); PG8_BAR; PG8_MMA(0, 0, At, B0); PG8_MMA(0, 1, At, B1); PG8_BAR; PG8_SCHED;
;             PG8_LDA(At, 0, 1); PG8_STAGE(PG8_SB(0, 0), b2, voffB); PG8_STAGE(PG8_SB(0, 1), b2 + hsB, voffB); PG8_STAGE(PG8_SA(0, 0), a2, voffA);
;             PG8_WAIT_V(8); PG8_WAIT_L(0); PG8_BAR; PG8_MMA(1, 0, At, B0); PG8_MMA(1, 1, At, B1); PG8_BAR; PG8_SCHED;
.LBB0_773:
	ds_read_b128 v[150:153], v147
	ds_read_b128 v[154:157], v147 offset:1024
	ds_read_b128 v[158:161], v147 offset:2048
	ds_read_b128 v[162:165], v147 offset:3072
	ds_read_b128 v[166:169], v148
	ds_read_b128 v[170:173], v148 offset:1024
	ds_read_b128 v[174:177], v148 offset:2048
	ds_read_b128 v[178:181], v148 offset:3072
	s_add_u32 s28, s26, 0x100
	s_addc_u32 s29, s27, 0
	s_cmp_eq_u32 s60, 8
	s_cselect_b32 s35, s5, s29
	s_cselect_b32 s34, s4, s28
	s_cselect_b32 s31, s25, s59
	s_cselect_b32 s30, s24, s58
	v_lshl_add_u64 v[214:215], s[26:27], 0, v[138:139]
	s_add_i32 m0, s40, 0xc000
	ds_read_b128 v[182:185], v149
	ds_read_b128 v[186:189], v149 offset:1024
	ds_read_b128 v[190:193], v149 offset:2048
	ds_read_b128 v[194:197], v149 offset:3072
	ds_read_b128 v[198:201], v149 offset:4096
	ds_read_b128 v[202:205], v149 offset:5120
	ds_read_b128 v[206:209], v149 offset:6144
	ds_read_b128 v[210:213], v149 offset:7168
	global_load_lds_dwordx4 v[214:215], off
	v_lshl_add_u64 v[214:215], s[26:27], 0, v[136:137]
	s_add_i32 m0, s40, 0xe000
	s_nop 0
	global_load_lds_dwordx4 v[214:215], off
	s_waitcnt vmcnt(8)
	s_waitcnt lgkmcnt(0)
	s_barrier
	s_waitcnt lgkmcnt(0)
	v_mfma_f32_16x16x32_bf16 v[124:127], v[150:153], v[182:185], v[124:127]
	v_mfma_f32_16x16x32_bf16 v[120:123], v[158:161], v[182:185], v[120:123]
	v_mfma_f32_16x16x32_bf16 v[116:119], v[150:153], v[190:193], v[116:119]
	v_mfma_f32_16x16x32_bf16 v[112:115], v[158:161], v[190:193], v[112:115]
	v_mfma_f32_16x16x32_bf16 v[104:107], v[150:153], v[198:201], v[104:107]
	v_mfma_f32_16x16x32_bf16 v[96:99], v[158:161], v[198:201], v[96:99]
	v_mfma_f32_16x16x32_bf16 v[88:91], v[150:153], v[206:209], v[88:91]
	v_mfma_f32_16x16x32_bf16 v[80:83], v[158:161], v[206:209], v[80:83]
	v_mfma_f32_16x16x32_bf16 v[124:127], v[154:157], v[186:189], v[124:127]
	v_mfma_f32_16x16x32_bf16 v[120:123], v[162:165], v[186:189], v[120:123]
	v_mfma_f32_16x16x32_bf16 v[116:119], v[154:157], v[194:197], v[116:119]
	v_mfma_f32_16x16x32_bf16 v[112:115], v[162:165], v[194:197], v[112:115]
	v_mfma_f32_16x16x32_bf16 v[104:107], v[154:157], v[202:205], v[104:107]
	v_mfma_f32_16x16x32_bf16 v[96:99], v[162:165], v[202:205], v[96:99]
	v_mfma_f32_16x16x32_bf16 v[88:91], v[154:157], v[210:213], v[88:91]
	v_mfma_f32_16x16x32_bf16 v[80:83], v[162:165], v[210:213], v[80:83]
	v_mfma_f32_16x16x32_bf16 v[108:111], v[166:169], v[182:185], v[108:111]
	v_mfma_f32_16x16x32_bf16 v[100:103], v[174:177], v[182:185], v[100:103]
	v_mfma_f32_16x16x32_bf16 v[92:95], v[166:169], v[190:193], v[92:95]
	v_mfma_f32_16x16x32_bf16 v[84:87], v[174:177], v[190:193], v[84:87]
	v_mfma_f32_16x16x32_bf16 v[76:79], v[166:169], v[198:201], v[76:79]
	v_mfma_f32_16x16x32_bf16 v[72:75], v[174:177], v[198:201], v[72:75]
	v_mfma_f32_16x16x32_bf16 v[68:71], v[166:169], v[206:209], v[68:71]
	v_mfma_f32_16x16x32_bf16 v[64:67], v[174:177], v[206:209], v[64:67]
	v_mfma_f32_16x16x32_bf16 v[108:111], v[170:173], v[186:189], v[108:111]
	v_mfma_f32_16x16x32_bf16 v[100:103], v[178:181], v[186:189], v[100:103]
	v_mfma_f32_16x16x32_bf16 v[92:95], v[170:173], v[194:197], v[92:95]
	v_mfma_f32_16x16x32_bf16 v[84:87], v[178:181], v[194:197], v[84:87]
	v_mfma_f32_16x16x32_bf16 v[76:79], v[170:173], v[202:205], v[76:79]
	v_mfma_f32_16x16x32_bf16 v[72:75], v[178:181], v[202:205], v[72:75]
	v_mfma_f32_16x16x32_bf16 v[68:71], v[170:173], v[210:213], v[68:71]
	v_mfma_f32_16x16x32_bf16 v[64:67], v[178:181], v[210:213], v[64:67]
	s_barrier
	s_add_i32 s26, s51, s38
	v_lshl_add_u64 v[214:215], s[30:31], 0, v[132:133]
	s_mov_b32 m0, s26
	ds_read_b128 v[182:185], v149 offset:16384
	ds_read_b128 v[186:189], v149 offset:17408
	ds_read_b128 v[190:193], v149 offset:18432
	ds_read_b128 v[194:197], v149 offset:19456
	ds_read_b128 v[198:201], v149 offset:20480
	ds_read_b128 v[202:205], v149 offset:21504
	ds_read_b128 v[206:209], v149 offset:22528
	ds_read_b128 v[210:213], v149 offset:23552
	global_load_lds_dwordx4 v[214:215], off
	s_add_i32 m0, s26, 0x2000
	s_add_u32 s26, s30, 0x30000
	v_lshl_add_u64 v[216:217], s[30:31], 0, v[128:129]
	s_addc_u32 s27, s31, 0
	s_add_i32 s61, s52, s38
	global_load_lds_dwordx4 v[216:217], off
	v_lshl_add_u64 v[218:219], s[26:27], 0, v[132:133]
	s_mov_b32 m0, s61
	v_lshl_add_u64 v[220:221], s[34:35], 0, v[130:131]
	global_load_lds_dwordx4 v[218:219], off
	v_lshl_add_u64 v[218:219], s[26:27], 0, v[128:129]
	s_add_i32 m0, s61, 0x2000
	s_nop 0
	global_load_lds_dwordx4 v[218:219], off
	v_lshl_add_u64 v[218:219], s[34:35], 0, v[134:135]
	s_mov_b32 m0, s40
	s_nop 0
	global_load_lds_dwordx4 v[218:219], off
	s_mov_b32 m0, s41
	s_nop 0
	global_load_lds_dwordx4 v[220:221], off
	s_waitcnt vmcnt(8)
	s_waitcnt lgkmcnt(0)
	s_barrier
; #define PG8_STAGE(bufoff, gbase, voff) do { _Pragma("unroll") for (int _i = 0; _i < 2; ++_i) \
;         __builtin_amdgcn_global_load_lds((const unsigned*)((const char*)(gbase) + (voff)[_i]), (PG8_LAS unsigned*)(lds + (bufoff) + ldsw + _i * 8192), 16, 0, 0); } while (0)
; #define PG8_LDA(dst, b, h) do { _Pragma("unroll") for (int m = 0; m < 4; ++m) _Pragma("unroll") for (int k = 0; k < 2; ++k) dst[m][k] = *(const PG8_LAS bf16x8*)(lds + PG8_SA(b, h) + aoff + m * 2048 + k * 1024); } while (0)
; #define PG8_LDB(dst, b, h) do { _Pragma("unroll") for (int n = 0; n < 2; ++n) _Pragma("unroll") for (int k = 0; k < 2; ++k) dst[n][k] = *(const PG8_LAS bf16x8*)(lds + PG8_SB(b, h) + boff + n * 2048 + k * 1024); } while (0)
; #define PG8_MMA(ai, bj, At, Bt) do { __builtin_amdgcn_s_setprio(1); _Pragma("unroll") for (int m = 0; m < 4; ++m) _Pragma("unroll") for (int n = 0; n < 2; ++n) _Pragma("unroll") for (int k = 0; k < 2; ++k) \
;         acc[ai][bj][m][n] = __builtin_amdgcn_mfma_f32_16x16x32_bf16(Bt[n][k], At[m][k], acc[ai][bj][m][n], 0, 0, 0); __builtin_amdgcn_s_setprio(0); } while (0)
; #define PG8_WAIT_V(n) asm volatile("s_waitcnt vmcnt(" #n ")" ::: "memory")
; #define PG8_WAIT_L(n) asm volatile("s_waitcnt lgkmcnt(" #n ")" ::: "memory")
; #define PG8_BAR __builtin_amdgcn_s_barrier()
; #define PG8_SCHED __builtin_amdgcn_sched_barrier(0)
; template <class Epi, class Sched, bool ALIGN_EPI = false, bool SP2 = false>
; __device__ __forceinline__ void gemm_phase(PG8_LAS unsigned char* lds, const Gemm g, const Sched& S, const Epi& E, const int wid) {
;     ...
;             PG8_WAIT_V(8); PG8_WAIT_L(0); PG8_BAR; PG8_MMA(1, 0, At, B0); PG8_MMA(1, 1, At, B1); PG8_BAR; PG8_SCHED;
;             PG8_LDB(B0, 1, 0); PG8_LDB(B1, 1, 1); PG8_SCHED; PG8_LDA(At, 1, 0); PG8_STAGE(PG8_SA(0, 1), a2 + hsA, voffA);
;             PG8_WAIT_V(8); PG8_WAIT_L(0); PG8_BAR; PG8_MMA(0, 0, At, B0); PG8_MMA(0, 1, At, B1); PG8_BAR; PG8_SCHED;
	s_waitcnt lgkmcnt(0)
	v_mfma_f32_16x16x32_bf16 v[60:63], v[150:153], v[182:185], v[60:63]
	v_mfma_f32_16x16x32_bf16 v[56:59], v[158:161], v[182:185], v[56:59]
	v_mfma_f32_16x16x32_bf16 v[52:55], v[150:153], v[190:193], v[52:55]
	v_mfma_f32_16x16x32_bf16 v[48:51], v[158:161], v[190:193], v[48:51]
	v_mfma_f32_16x16x32_bf16 v[40:43], v[150:153], v[198:201], v[40:43]
	v_mfma_f32_16x16x32_bf16 v[32:35], v[158:161], v[198:201], v[32:35]
	v_mfma_f32_16x16x32_bf16 v[24:27], v[150:153], v[206:209], v[24:27]
	v_mfma_f32_16x16x32_bf16 v[16:19], v[158:161], v[206:209], v[16:19]
	v_mfma_f32_16x16x32_bf16 v[60:63], v[154:157], v[186:189], v[60:63]
	v_mfma_f32_16x16x32_bf16 v[56:59], v[162:165], v[186:189], v[56:59]
	v_mfma_f32_16x16x32_bf16 v[52:55], v[154:157], v[194:197], v[52:55]
	v_mfma_f32_16x16x32_bf16 v[48:51], v[162:165], v[194:197], v[48:51]
	v_mfma_f32_16x16x32_bf16 v[40:43], v[154:157], v[202:205], v[40:43]
	v_mfma_f32_16x16x32_bf16 v[32:35], v[162:165], v[202:205], v[32:35]
	v_mfma_f32_16x16x32_bf16 v[24:27], v[154:157], v[210:213], v[24:27]
	v_mfma_f32_16x16x32_bf16 v[16:19], v[162:165], v[210:213], v[16:19]
	v_mfma_f32_16x16x32_bf16 v[44:47], v[166:169], v[182:185], v[44:47]
	v_mfma_f32_16x16x32_bf16 v[36:39], v[174:177], v[182:185], v[36:39]
	v_mfma_f32_16x16x32_bf16 v[28:31], v[166:169], v[190:193], v[28:31]
	v_mfma_f32_16x16x32_bf16 v[20:23], v[174:177], v[190:193], v[20:23]
	v_mfma_f32_16x16x32_bf16 v[12:15], v[166:169], v[198:201], v[12:15]
	v_mfma_f32_16x16x32_bf16 v[8:11], v[174:177], v[198:201], v[8:11]
	v_mfma_f32_16x16x32_bf16 v[4:7], v[166:169], v[206:209], v[4:7]
	v_mfma_f32_16x16x32_bf16 v[0:3], v[174:177], v[206:209], v[0:3]
	v_mfma_f32_16x16x32_bf16 v[44:47], v[170:173], v[186:189], v[44:47]
	v_mfma_f32_16x16x32_bf16 v[36:39], v[178:181], v[186:189], v[36:39]
	v_mfma_f32_16x16x32_bf16 v[28:31], v[170:173], v[194:197], v[28:31]
	v_mfma_f32_16x16x32_bf16 v[20:23], v[178:181], v[194:197], v[20:23]
	v_mfma_f32_16x16x32_bf16 v[12:15], v[170:173], v[202:205], v[12:15]
	v_mfma_f32_16x16x32_bf16 v[8:11], v[178:181], v[202:205], v[8:11]
	v_mfma_f32_16x16x32_bf16 v[4:7], v[170:173], v[210:213], v[4:7]
	v_mfma_f32_16x16x32_bf16 v[0:3], v[178:181], v[210:213], v[0:3]
	s_barrier
	s_add_i32 s61, 0, 0x18000
	s_add_i32 s62, 0, 0x1c000
	v_add_u32_e32 v162, s61, v145
	v_add_u32_e32 v178, s62, v145
	ds_read_b128 v[150:153], v162
	ds_read_b128 v[154:157], v162 offset:1024
	ds_read_b128 v[158:161], v162 offset:2048
	ds_read_b128 v[162:165], v162 offset:3072
	ds_read_b128 v[166:169], v178
	ds_read_b128 v[170:173], v178 offset:1024
	ds_read_b128 v[174:177], v178 offset:2048
	ds_read_b128 v[178:181], v178 offset:3072
	s_add_u32 s26, s34, 0x600000
	s_addc_u32 s27, s35, 0
	s_mov_b32 m0, s42
	v_lshl_add_u64 v[222:223], s[26:27], 0, v[134:135]
	ds_read_b128 v[182:185], v149 offset:32768
	ds_read_b128 v[186:189], v149 offset:33792
	ds_read_b128 v[190:193], v149 offset:34816
	ds_read_b128 v[194:197], v149 offset:35840
	ds_read_b128 v[198:201], v149 offset:36864
	ds_read_b128 v[202:205], v149 offset:37888
	ds_read_b128 v[206:209], v149 offset:38912
	ds_read_b128 v[210:213], v149 offset:39936
	global_load_lds_dwordx4 v[222:223], off
	v_lshl_add_u64 v[222:223], s[26:27], 0, v[130:131]
	s_mov_b32 m0, s43
	s_nop 0
	global_load_lds_dwordx4 v[222:223], off
	s_waitcnt vmcnt(8)
	s_waitcnt lgkmcnt(0)
	s_barrier
	s_waitcnt lgkmcnt(0)
	v_mfma_f32_16x16x32_bf16 v[124:127], v[150:153], v[182:185], v[124:127]
	v_mfma_f32_16x16x32_bf16 v[120:123], v[158:161], v[182:185], v[120:123]
	v_mfma_f32_16x16x32_bf16 v[116:119], v[150:153], v[190:193], v[116:119]
	v_mfma_f32_16x16x32_bf16 v[112:115], v[158:161], v[190:193], v[112:115]
	v_mfma_f32_16x16x32_bf16 v[104:107], v[150:153], v[198:201], v[104:107]
	v_mfma_f32_16x16x32_bf16 v[96:99], v[158:161], v[198:201], v[96:99]
	v_mfma_f32_16x16x32_bf16 v[88:91], v[150:153], v[206:209], v[88:91]
	v_mfma_f32_16x16x32_bf16 v[80:83], v[158:161], v[206:209], v[80:83]
	v_mfma_f32_16x16x32_bf16 v[124:127], v[154:157], v[186:189], v[124:127]
	v_mfma_f32_16x16x32_bf16 v[120:123], v[162:165], v[186:189], v[120:123]
	v_mfma_f32_16x16x32_bf16 v[116:119], v[154:157], v[194:197], v[116:119]
	v_mfma_f32_16x16x32_bf16 v[112:115], v[162:165], v[194:197], v[112:115]
	v_mfma_f32_16x16x32_bf16 v[104:107], v[154:157], v[202:205], v[104:107]
	v_mfma_f32_16x16x32_bf16 v[96:99], v[162:165], v[202:205], v[96:99]
	v_mfma_f32_16x16x32_bf16 v[88:91], v[154:157], v[210:213], v[88:91]
	v_mfma_f32_16x16x32_bf16 v[80:83], v[162:165], v[210:213], v[80:83]
	v_mfma_f32_16x16x32_bf16 v[108:111], v[166:169], v[182:185], v[108:111]
	v_mfma_f32_16x16x32_bf16 v[100:103], v[174:177], v[182:185], v[100:103]
	v_mfma_f32_16x16x32_bf16 v[92:95], v[166:169], v[190:193], v[92:95]
	v_mfma_f32_16x16x32_bf16 v[84:87], v[174:177], v[190:193], v[84:87]
	v_mfma_f32_16x16x32_bf16 v[76:79], v[166:169], v[198:201], v[76:79]
	v_mfma_f32_16x16x32_bf16 v[72:75], v[174:177], v[198:201], v[72:75]
	v_mfma_f32_16x16x32_bf16 v[68:71], v[166:169], v[206:209], v[68:71]
	v_mfma_f32_16x16x32_bf16 v[64:67], v[174:177], v[206:209], v[64:67]
	v_mfma_f32_16x16x32_bf16 v[108:111], v[170:173], v[186:189], v[108:111]
	v_mfma_f32_16x16x32_bf16 v[100:103], v[178:181], v[186:189], v[100:103]
	v_mfma_f32_16x16x32_bf16 v[92:95], v[170:173], v[194:197], v[92:95]
	v_mfma_f32_16x16x32_bf16 v[84:87], v[178:181], v[194:197], v[84:87]
	v_mfma_f32_16x16x32_bf16 v[76:79], v[170:173], v[202:205], v[76:79]
	v_mfma_f32_16x16x32_bf16 v[72:75], v[178:181], v[202:205], v[72:75]
	v_mfma_f32_16x16x32_bf16 v[68:71], v[170:173], v[210:213], v[68:71]
	v_mfma_f32_16x16x32_bf16 v[64:67], v[178:181], v[210:213], v[64:67]
	s_barrier
; #define PG8_STAGE(bufoff, gbase, voff) do { _Pragma("unroll") for (int _i = 0; _i < 2; ++_i) \
;         __builtin_amdgcn_global_load_lds((const unsigned*)((const char*)(gbase) + (voff)[_i]), (PG8_LAS unsigned*)(lds + (bufoff) + ldsw + _i * 8192), 16, 0, 0); } while (0)
; #define PG8_LDA(dst, b, h) do { _Pragma("unroll") for (int m = 0; m < 4; ++m) _Pragma("unroll") for (int k = 0; k < 2; ++k) dst[m][k] = *(const PG8_LAS bf16x8*)(lds + PG8_SA(b, h) + aoff + m * 2048 + k * 1024); } while (0)
; #define PG8_MMA(ai, bj, At, Bt) do { __builtin_amdgcn_s_setprio(1); _Pragma("unroll") for (int m = 0; m < 4; ++m) _Pragma("unroll") for (int n = 0; n < 2; ++n) _Pragma("unroll") for (int k = 0; k < 2; ++k) \
;         acc[ai][bj][m][n] = __builtin_amdgcn_mfma_f32_16x16x32_bf16(Bt[n][k], At[m][k], acc[ai][bj][m][n], 0, 0, 0); __builtin_amdgcn_s_setprio(0); } while (0)
; #define PG8_WAIT_V(n) asm volatile("s_waitcnt vmcnt(" #n ")" ::: "memory")
; #define PG8_WAIT_L(n) asm volatile("s_waitcnt lgkmcnt(" #n ")" ::: "memory")
; #define PG8_BAR __builtin_amdgcn_s_barrier()
; #define PG8_SCHED __builtin_amdgcn_sched_barrier(0)
; template <class Epi, class Sched, bool ALIGN_EPI = false, bool SP2 = false>
; __device__ __forceinline__ void gemm_phase(PG8_LAS unsigned char* lds, const Gemm g, const Sched& S, const Epi& E, const int wid) {
;     ...
;         for (int t = 0; t < nt; t += 2) {
;     ...
;             PG8_LDA(At, 1, 1); PG8_STAGE(PG8_SB(1, 0), b3, voffB); PG8_STAGE(PG8_SB(1, 1), b3 + hsB, voffB); PG8_STAGE(PG8_SA(1, 0), a3, voffA);
;             PG8_WAIT_V(8); PG8_WAIT_L(0); PG8_BAR; PG8_MMA(1, 0, At, B0); PG8_MMA(1, 1, At, B1); PG8_BAR; PG8_SCHED;
;     ...
;         if constexpr (ALIGN_EPI) { if (wr == 0) PG8_BAR; }
	s_add_i32 s26, s61, s38
	v_lshl_add_u64 v[214:215], v[214:215], 0, s[12:13]
	s_mov_b32 m0, s26
	ds_read_b128 v[182:185], v149 offset:49152
	ds_read_b128 v[186:189], v149 offset:50176
	ds_read_b128 v[190:193], v149 offset:51200
	ds_read_b128 v[194:197], v149 offset:52224
	ds_read_b128 v[198:201], v149 offset:53248
	ds_read_b128 v[202:205], v149 offset:54272
	ds_read_b128 v[206:209], v149 offset:55296
	ds_read_b128 v[210:213], v149 offset:56320
	global_load_lds_dwordx4 v[214:215], off
	s_add_i32 m0, s26, 0x2000
	s_add_u32 s26, s30, 0x30080
	v_lshl_add_u64 v[214:215], v[216:217], 0, s[12:13]
	s_addc_u32 s27, s31, 0
	s_add_i32 s30, s62, s38
	global_load_lds_dwordx4 v[214:215], off
	v_lshl_add_u64 v[214:215], s[26:27], 0, v[132:133]
	s_mov_b32 m0, s30
	s_nop 0
	global_load_lds_dwordx4 v[214:215], off
	v_lshl_add_u64 v[214:215], s[26:27], 0, v[128:129]
	s_add_i32 m0, s30, 0x2000
	s_nop 0
	global_load_lds_dwordx4 v[214:215], off
	v_lshl_add_u64 v[214:215], v[218:219], 0, s[12:13]
	s_mov_b32 m0, s46
	s_nop 0
	global_load_lds_dwordx4 v[214:215], off
	v_lshl_add_u64 v[214:215], v[220:221], 0, s[12:13]
	s_mov_b32 m0, s47
	s_nop 0
	global_load_lds_dwordx4 v[214:215], off
	s_waitcnt vmcnt(8)
	s_waitcnt lgkmcnt(0)
	s_barrier
	s_waitcnt lgkmcnt(0)
	v_mfma_f32_16x16x32_bf16 v[60:63], v[150:153], v[182:185], v[60:63]
	v_mfma_f32_16x16x32_bf16 v[56:59], v[158:161], v[182:185], v[56:59]
	v_mfma_f32_16x16x32_bf16 v[52:55], v[150:153], v[190:193], v[52:55]
	v_mfma_f32_16x16x32_bf16 v[48:51], v[158:161], v[190:193], v[48:51]
	v_mfma_f32_16x16x32_bf16 v[40:43], v[150:153], v[198:201], v[40:43]
	v_mfma_f32_16x16x32_bf16 v[32:35], v[158:161], v[198:201], v[32:35]
	v_mfma_f32_16x16x32_bf16 v[24:27], v[150:153], v[206:209], v[24:27]
	v_mfma_f32_16x16x32_bf16 v[16:19], v[158:161], v[206:209], v[16:19]
	v_mfma_f32_16x16x32_bf16 v[60:63], v[154:157], v[186:189], v[60:63]
	v_mfma_f32_16x16x32_bf16 v[56:59], v[162:165], v[186:189], v[56:59]
	v_mfma_f32_16x16x32_bf16 v[52:55], v[154:157], v[194:197], v[52:55]
	v_mfma_f32_16x16x32_bf16 v[48:51], v[162:165], v[194:197], v[48:51]
	v_mfma_f32_16x16x32_bf16 v[40:43], v[154:157], v[202:205], v[40:43]
	v_mfma_f32_16x16x32_bf16 v[32:35], v[162:165], v[202:205], v[32:35]
	v_mfma_f32_16x16x32_bf16 v[24:27], v[154:157], v[210:213], v[24:27]
	v_mfma_f32_16x16x32_bf16 v[16:19], v[162:165], v[210:213], v[16:19]
	v_mfma_f32_16x16x32_bf16 v[44:47], v[166:169], v[182:185], v[44:47]
	v_mfma_f32_16x16x32_bf16 v[36:39], v[174:177], v[182:185], v[36:39]
	v_mfma_f32_16x16x32_bf16 v[28:31], v[166:169], v[190:193], v[28:31]
	v_mfma_f32_16x16x32_bf16 v[20:23], v[174:177], v[190:193], v[20:23]
	v_mfma_f32_16x16x32_bf16 v[12:15], v[166:169], v[198:201], v[12:15]
	v_mfma_f32_16x16x32_bf16 v[8:11], v[174:177], v[198:201], v[8:11]
	v_mfma_f32_16x16x32_bf16 v[4:7], v[166:169], v[206:209], v[4:7]
	v_mfma_f32_16x16x32_bf16 v[0:3], v[174:177], v[206:209], v[0:3]
	v_mfma_f32_16x16x32_bf16 v[44:47], v[170:173], v[186:189], v[44:47]
	v_mfma_f32_16x16x32_bf16 v[36:39], v[178:181], v[186:189], v[36:39]
	v_mfma_f32_16x16x32_bf16 v[28:31], v[170:173], v[194:197], v[28:31]
	v_mfma_f32_16x16x32_bf16 v[20:23], v[178:181], v[194:197], v[20:23]
	v_mfma_f32_16x16x32_bf16 v[12:15], v[170:173], v[202:205], v[12:15]
	v_mfma_f32_16x16x32_bf16 v[8:11], v[178:181], v[202:205], v[8:11]
	v_mfma_f32_16x16x32_bf16 v[4:7], v[170:173], v[210:213], v[4:7]
	v_mfma_f32_16x16x32_bf16 v[0:3], v[178:181], v[210:213], v[0:3]
	s_barrier
	s_add_i32 s60, s60, 2
	s_add_u32 s58, s58, 0x100
	s_addc_u32 s59, s59, 0
	s_cmp_gt_u32 s60, 9
	s_mov_b64 s[26:27], s[28:29]
	s_cbranch_scc0 .LBB0_773
	s_and_b64 vcc, exec, s[14:15]
	s_cbranch_vccz .LBB0_776
	s_barrier

; #define PG8_STAGE(bufoff, gbase, voff) do { _Pragma("unroll") for (int _i = 0; _i < 2; ++_i) \
;         __builtin_amdgcn_global_load_lds((const unsigned*)((const char*)(gbase) + (voff)[_i]), (PG8_LAS unsigned*)(lds + (bufoff) + ldsw + _i * 8192), 16, 0, 0); } while (0)
; #define PG8_LDA(dst, b, h) do { _Pragma("unroll") for (int m = 0; m < 4; ++m) _Pragma("unroll") for (int k = 0; k < 2; ++k) dst[m][k] = *(const PG8_LAS bf16x8*)(lds + PG8_SA(b, h) + aoff + m * 2048 + k * 1024); } while (0)
; #define PG8_LDB(dst, b, h) do { _Pragma("unroll") for (int n = 0; n < 2; ++n) _Pragma("unroll") for (int k = 0; k < 2; ++k) dst[n][k] = *(const PG8_LAS bf16x8*)(lds + PG8_SB(b, h) + boff + n * 2048 + k * 1024); } while (0)
; #define PG8_MMA(ai, bj, At, Bt) do { __builtin_amdgcn_s_setprio(1); _Pragma("unroll") for (int m = 0; m < 4; ++m) _Pragma("unroll") for (int n = 0; n < 2; ++n) _Pragma("unroll") for (int k = 0; k < 2; ++k) \
;         acc[ai][bj][m][n] = __builtin_amdgcn_mfma_f32_16x16x32_bf16(Bt[n][k], At[m][k], acc[ai][bj][m][n], 0, 0, 0); __builtin_amdgcn_s_setprio(0); } while (0)
; #define PG8_WAIT_V(n) asm volatile("s_waitcnt vmcnt(" #n ")" ::: "memory")
; #define PG8_WAIT_L(n) asm volatile("s_waitcnt lgkmcnt(" #n ")" ::: "memory")
; #define PG8_BAR __builtin_amdgcn_s_barrier()
; template <class Epi, class Sched, bool ALIGN_EPI = false, bool SP2 = false>
; __device__ __forceinline__ void gemm_phase(PG8_LAS unsigned char* lds, const Gemm g, const Sched& S, const Epi& E, const int wid) {
;     ...
;             const bool last = (t == nt - 2);
;             const char* a1 = cA + (size_t)(t + 1) * kstep;
;             const char* a2 = last ? nA : cA + (size_t)(t + 2) * kstep; const char* b2 = last ? nB : cB + (size_t)(t + 2) * kstep;
;             const char* a3 = a2 + kstep; const char* b3 = b2 + kstep;
;             if constexpr (SP2) {
;             PG8_LDB(B0, 0, 0); PG8_LDB(B1, 0, 1); PG8_SCHED; PG8_LDA(At, 0, 0); PG8_STAGE(PG8_SA(1, 1), a1 + hsA, voffA);
;             PG8_WAIT_V(8); PG8_WAIT_L(0); PG8_BAR; PG8_MMA(0, 0, At, B0); PG8_MMA(0, 1, At, B1); PG8_BAR; PG8_SCHED;
;             PG8_LDA(At, 0, 1); PG8_STAGE(PG8_SB(0, 0), b2, voffB); PG8_STAGE(PG8_SB(0, 1), b2 + hsB, voffB); PG8_STAGE(PG8_SA(0, 0), a2, voffA);
;             PG8_WAIT_V(8); PG8_WAIT_L(0); PG8_BAR; PG8_MMA(1, 0, At, B0); PG8_MMA(1, 1, At, B1); PG8_BAR; PG8_SCHED;
.LBB0_1177:
	ds_read_b128 v[128:131], v205
	ds_read_b128 v[132:135], v205 offset:1024
	ds_read_b128 v[136:139], v205 offset:2048
	ds_read_b128 v[140:143], v205 offset:3072
	ds_read_b128 v[144:147], v206
	ds_read_b128 v[148:151], v206 offset:1024
	ds_read_b128 v[152:155], v206 offset:2048
	ds_read_b128 v[156:159], v206 offset:3072
	s_add_u32 s40, s38, 0xfffc0080
	s_addc_u32 s41, s39, -1
	s_cmp_eq_u32 s64, 12
	s_cselect_b32 s43, s29, s41
	s_cselect_b32 s42, s60, s40
	s_cselect_b32 s41, s27, s63
	s_cselect_b32 s40, s61, s62
	v_lshl_add_u64 v[200:201], s[38:39], 0, v[170:171]
	s_add_i32 m0, s37, 0xc000
	ds_read_b128 v[176:179], v207
	ds_read_b128 v[180:183], v207 offset:1024
	ds_read_b128 v[184:187], v207 offset:2048
	ds_read_b128 v[188:191], v207 offset:3072
	ds_read_b128 v[192:195], v207 offset:4096
	ds_read_b128 v[196:199], v207 offset:5120
	ds_read_b128 v[208:211], v207 offset:6144
	ds_read_b128 v[212:215], v207 offset:7168
	global_load_lds_dwordx4 v[200:201], off
	v_lshl_add_u64 v[200:201], s[38:39], 0, v[168:169]
	s_add_i32 m0, s37, 0xe000
	s_nop 0
	global_load_lds_dwordx4 v[200:201], off
	s_waitcnt vmcnt(8)
	s_waitcnt lgkmcnt(0)
	s_barrier
	s_waitcnt lgkmcnt(0)
	v_mfma_f32_16x16x32_bf16 v[124:127], v[128:131], v[176:179], v[124:127]
	v_mfma_f32_16x16x32_bf16 v[120:123], v[136:139], v[176:179], v[120:123]
	v_mfma_f32_16x16x32_bf16 v[116:119], v[128:131], v[184:187], v[116:119]
	v_mfma_f32_16x16x32_bf16 v[112:115], v[136:139], v[184:187], v[112:115]
	v_mfma_f32_16x16x32_bf16 v[108:111], v[128:131], v[192:195], v[108:111]
	v_mfma_f32_16x16x32_bf16 v[104:107], v[136:139], v[192:195], v[104:107]
	v_mfma_f32_16x16x32_bf16 v[100:103], v[128:131], v[208:211], v[100:103]
	v_mfma_f32_16x16x32_bf16 v[96:99], v[136:139], v[208:211], v[96:99]
	v_mfma_f32_16x16x32_bf16 v[124:127], v[132:135], v[180:183], v[124:127]
	v_mfma_f32_16x16x32_bf16 v[120:123], v[140:143], v[180:183], v[120:123]
	v_mfma_f32_16x16x32_bf16 v[116:119], v[132:135], v[188:191], v[116:119]
	v_mfma_f32_16x16x32_bf16 v[112:115], v[140:143], v[188:191], v[112:115]
	v_mfma_f32_16x16x32_bf16 v[108:111], v[132:135], v[196:199], v[108:111]
	v_mfma_f32_16x16x32_bf16 v[104:107], v[140:143], v[196:199], v[104:107]
	v_mfma_f32_16x16x32_bf16 v[100:103], v[132:135], v[212:215], v[100:103]
	v_mfma_f32_16x16x32_bf16 v[96:99], v[140:143], v[212:215], v[96:99]
	v_mfma_f32_16x16x32_bf16 v[60:63], v[144:147], v[176:179], v[60:63]
	v_mfma_f32_16x16x32_bf16 v[56:59], v[152:155], v[176:179], v[56:59]
	v_mfma_f32_16x16x32_bf16 v[52:55], v[144:147], v[184:187], v[52:55]
	v_mfma_f32_16x16x32_bf16 v[48:51], v[152:155], v[184:187], v[48:51]
	v_mfma_f32_16x16x32_bf16 v[44:47], v[144:147], v[192:195], v[44:47]
	v_mfma_f32_16x16x32_bf16 v[40:43], v[152:155], v[192:195], v[40:43]
	v_mfma_f32_16x16x32_bf16 v[36:39], v[144:147], v[208:211], v[36:39]
	v_mfma_f32_16x16x32_bf16 v[32:35], v[152:155], v[208:211], v[32:35]
	v_mfma_f32_16x16x32_bf16 v[60:63], v[148:151], v[180:183], v[60:63]
	v_mfma_f32_16x16x32_bf16 v[56:59], v[156:159], v[180:183], v[56:59]
	v_mfma_f32_16x16x32_bf16 v[52:55], v[148:151], v[188:191], v[52:55]
	v_mfma_f32_16x16x32_bf16 v[48:51], v[156:159], v[188:191], v[48:51]
	v_mfma_f32_16x16x32_bf16 v[44:47], v[148:151], v[196:199], v[44:47]
	v_mfma_f32_16x16x32_bf16 v[40:43], v[156:159], v[196:199], v[40:43]
	v_mfma_f32_16x16x32_bf16 v[36:39], v[148:151], v[212:215], v[36:39]
	v_mfma_f32_16x16x32_bf16 v[32:35], v[156:159], v[212:215], v[32:35]
	s_barrier
	s_add_i32 s65, s54, s45
	v_lshl_add_u64 v[200:201], s[40:41], 0, v[162:163]
	s_mov_b32 m0, s65
	ds_read_b128 v[176:179], v207 offset:16384
	ds_read_b128 v[180:183], v207 offset:17408
	ds_read_b128 v[184:187], v207 offset:18432
	ds_read_b128 v[188:191], v207 offset:19456
	ds_read_b128 v[192:195], v207 offset:20480
	ds_read_b128 v[196:199], v207 offset:21504
	ds_read_b128 v[208:211], v207 offset:22528
	ds_read_b128 v[212:215], v207 offset:23552
	global_load_lds_dwordx4 v[200:201], off
	s_add_i32 m0, s65, 0x2000
	s_add_u32 s66, s40, 0x40000
	v_lshl_add_u64 v[216:217], s[40:41], 0, v[166:167]
	s_addc_u32 s67, s41, 0
	s_add_i32 s65, s55, s45
	global_load_lds_dwordx4 v[216:217], off
	v_lshl_add_u64 v[218:219], s[66:67], 0, v[162:163]
	s_mov_b32 m0, s65
	v_lshl_add_u64 v[220:221], s[42:43], 0, v[164:165]
	global_load_lds_dwordx4 v[218:219], off
	v_lshl_add_u64 v[218:219], s[66:67], 0, v[166:167]
	s_add_i32 m0, s65, 0x2000
	s_nop 0
	global_load_lds_dwordx4 v[218:219], off
	v_lshl_add_u64 v[218:219], s[42:43], 0, v[160:161]
	s_mov_b32 m0, s37
	s_nop 0
	global_load_lds_dwordx4 v[218:219], off
	s_mov_b32 m0, s46
	s_nop 0
	global_load_lds_dwordx4 v[220:221], off
	s_waitcnt vmcnt(8)
	s_waitcnt lgkmcnt(0)
	s_barrier
; #define PG8_STAGE(bufoff, gbase, voff) do { _Pragma("unroll") for (int _i = 0; _i < 2; ++_i) \
;         __builtin_amdgcn_global_load_lds((const unsigned*)((const char*)(gbase) + (voff)[_i]), (PG8_LAS unsigned*)(lds + (bufoff) + ldsw + _i * 8192), 16, 0, 0); } while (0)
; #define PG8_LDA(dst, b, h) do { _Pragma("unroll") for (int m = 0; m < 4; ++m) _Pragma("unroll") for (int k = 0; k < 2; ++k) dst[m][k] = *(const PG8_LAS bf16x8*)(lds + PG8_SA(b, h) + aoff + m * 2048 + k * 1024); } while (0)
; #define PG8_LDB(dst, b, h) do { _Pragma("unroll") for (int n = 0; n < 2; ++n) _Pragma("unroll") for (int k = 0; k < 2; ++k) dst[n][k] = *(const PG8_LAS bf16x8*)(lds + PG8_SB(b, h) + boff + n * 2048 + k * 1024); } while (0)
; #define PG8_MMA(ai, bj, At, Bt) do { __builtin_amdgcn_s_setprio(1); _Pragma("unroll") for (int m = 0; m < 4; ++m) _Pragma("unroll") for (int n = 0; n < 2; ++n) _Pragma("unroll") for (int k = 0; k < 2; ++k) \
;         acc[ai][bj][m][n] = __builtin_amdgcn_mfma_f32_16x16x32_bf16(Bt[n][k], At[m][k], acc[ai][bj][m][n], 0, 0, 0); __builtin_amdgcn_s_setprio(0); } while (0)
; #define PG8_WAIT_V(n) asm volatile("s_waitcnt vmcnt(" #n ")" ::: "memory")
; #define PG8_WAIT_L(n) asm volatile("s_waitcnt lgkmcnt(" #n ")" ::: "memory")
; #define PG8_BAR __builtin_amdgcn_s_barrier()
; #define PG8_SCHED __builtin_amdgcn_sched_barrier(0)
; template <class Epi, class Sched, bool ALIGN_EPI = false, bool SP2 = false>
; __device__ __forceinline__ void gemm_phase(PG8_LAS unsigned char* lds, const Gemm g, const Sched& S, const Epi& E, const int wid) {
;     ...
;             PG8_WAIT_V(8); PG8_WAIT_L(0); PG8_BAR; PG8_MMA(1, 0, At, B0); PG8_MMA(1, 1, At, B1); PG8_BAR; PG8_SCHED;
;             PG8_LDB(B0, 1, 0); PG8_LDB(B1, 1, 1); PG8_SCHED; PG8_LDA(At, 1, 0); PG8_STAGE(PG8_SA(0, 1), a2 + hsA, voffA);
;             PG8_WAIT_V(8); PG8_WAIT_L(0); PG8_BAR; PG8_MMA(0, 0, At, B0); PG8_MMA(0, 1, At, B1); PG8_BAR; PG8_SCHED;
	s_waitcnt lgkmcnt(0)
	v_mfma_f32_16x16x32_bf16 v[92:95], v[128:131], v[176:179], v[92:95]
	v_mfma_f32_16x16x32_bf16 v[88:91], v[136:139], v[176:179], v[88:91]
	v_mfma_f32_16x16x32_bf16 v[84:87], v[128:131], v[184:187], v[84:87]
	v_mfma_f32_16x16x32_bf16 v[80:83], v[136:139], v[184:187], v[80:83]
	v_mfma_f32_16x16x32_bf16 v[76:79], v[128:131], v[192:195], v[76:79]
	v_mfma_f32_16x16x32_bf16 v[72:75], v[136:139], v[192:195], v[72:75]
	v_mfma_f32_16x16x32_bf16 v[68:71], v[128:131], v[208:211], v[68:71]
	v_mfma_f32_16x16x32_bf16 v[64:67], v[136:139], v[208:211], v[64:67]
	v_mfma_f32_16x16x32_bf16 v[92:95], v[132:135], v[180:183], v[92:95]
	v_mfma_f32_16x16x32_bf16 v[88:91], v[140:143], v[180:183], v[88:91]
	v_mfma_f32_16x16x32_bf16 v[84:87], v[132:135], v[188:191], v[84:87]
	v_mfma_f32_16x16x32_bf16 v[80:83], v[140:143], v[188:191], v[80:83]
	v_mfma_f32_16x16x32_bf16 v[76:79], v[132:135], v[196:199], v[76:79]
	v_mfma_f32_16x16x32_bf16 v[72:75], v[140:143], v[196:199], v[72:75]
	v_mfma_f32_16x16x32_bf16 v[68:71], v[132:135], v[212:215], v[68:71]
	v_mfma_f32_16x16x32_bf16 v[64:67], v[140:143], v[212:215], v[64:67]
	v_mfma_f32_16x16x32_bf16 v[28:31], v[144:147], v[176:179], v[28:31]
	v_mfma_f32_16x16x32_bf16 v[24:27], v[152:155], v[176:179], v[24:27]
	v_mfma_f32_16x16x32_bf16 v[20:23], v[144:147], v[184:187], v[20:23]
	v_mfma_f32_16x16x32_bf16 v[16:19], v[152:155], v[184:187], v[16:19]
	v_mfma_f32_16x16x32_bf16 v[12:15], v[144:147], v[192:195], v[12:15]
	v_mfma_f32_16x16x32_bf16 v[8:11], v[152:155], v[192:195], v[8:11]
	v_mfma_f32_16x16x32_bf16 v[4:7], v[144:147], v[208:211], v[4:7]
	v_mfma_f32_16x16x32_bf16 v[0:3], v[152:155], v[208:211], v[0:3]
	v_mfma_f32_16x16x32_bf16 v[28:31], v[148:151], v[180:183], v[28:31]
	v_mfma_f32_16x16x32_bf16 v[24:27], v[156:159], v[180:183], v[24:27]
	v_mfma_f32_16x16x32_bf16 v[20:23], v[148:151], v[188:191], v[20:23]
	v_mfma_f32_16x16x32_bf16 v[16:19], v[156:159], v[188:191], v[16:19]
	v_mfma_f32_16x16x32_bf16 v[12:15], v[148:151], v[196:199], v[12:15]
	v_mfma_f32_16x16x32_bf16 v[8:11], v[156:159], v[196:199], v[8:11]
	v_mfma_f32_16x16x32_bf16 v[4:7], v[148:151], v[212:215], v[4:7]
	v_mfma_f32_16x16x32_bf16 v[0:3], v[156:159], v[212:215], v[0:3]
	s_barrier
	s_add_i32 s65, 0, 0x18000
	s_add_i32 s66, 0, 0x1c000
	v_add_u32_e32 v140, s65, v203
	v_add_u32_e32 v156, s66, v203
	ds_read_b128 v[128:131], v140
	ds_read_b128 v[132:135], v140 offset:1024
	ds_read_b128 v[136:139], v140 offset:2048
	ds_read_b128 v[140:143], v140 offset:3072
	ds_read_b128 v[144:147], v156
	ds_read_b128 v[148:151], v156 offset:1024
	ds_read_b128 v[152:155], v156 offset:2048
	ds_read_b128 v[156:159], v156 offset:3072
	s_add_u32 s42, s42, 0x40000
	s_addc_u32 s43, s43, 0
	s_mov_b32 m0, s47
	v_lshl_add_u64 v[222:223], s[42:43], 0, v[160:161]
	ds_read_b128 v[176:179], v207 offset:32768
	ds_read_b128 v[180:183], v207 offset:33792
	ds_read_b128 v[184:187], v207 offset:34816
	ds_read_b128 v[188:191], v207 offset:35840
	ds_read_b128 v[192:195], v207 offset:36864
	ds_read_b128 v[196:199], v207 offset:37888
	ds_read_b128 v[208:211], v207 offset:38912
	ds_read_b128 v[212:215], v207 offset:39936
	global_load_lds_dwordx4 v[222:223], off
	v_lshl_add_u64 v[222:223], s[42:43], 0, v[164:165]
	s_mov_b32 m0, s48
	s_nop 0
	global_load_lds_dwordx4 v[222:223], off
	s_waitcnt vmcnt(8)
	s_waitcnt lgkmcnt(0)
	s_barrier
	s_waitcnt lgkmcnt(0)
	v_mfma_f32_16x16x32_bf16 v[124:127], v[128:131], v[176:179], v[124:127]
	v_mfma_f32_16x16x32_bf16 v[120:123], v[136:139], v[176:179], v[120:123]
	v_mfma_f32_16x16x32_bf16 v[116:119], v[128:131], v[184:187], v[116:119]
	v_mfma_f32_16x16x32_bf16 v[112:115], v[136:139], v[184:187], v[112:115]
	v_mfma_f32_16x16x32_bf16 v[108:111], v[128:131], v[192:195], v[108:111]
	v_mfma_f32_16x16x32_bf16 v[104:107], v[136:139], v[192:195], v[104:107]
	v_mfma_f32_16x16x32_bf16 v[100:103], v[128:131], v[208:211], v[100:103]
	v_mfma_f32_16x16x32_bf16 v[96:99], v[136:139], v[208:211], v[96:99]
	v_mfma_f32_16x16x32_bf16 v[124:127], v[132:135], v[180:183], v[124:127]
	v_mfma_f32_16x16x32_bf16 v[120:123], v[140:143], v[180:183], v[120:123]
	v_mfma_f32_16x16x32_bf16 v[116:119], v[132:135], v[188:191], v[116:119]
	v_mfma_f32_16x16x32_bf16 v[112:115], v[140:143], v[188:191], v[112:115]
	v_mfma_f32_16x16x32_bf16 v[108:111], v[132:135], v[196:199], v[108:111]
	v_mfma_f32_16x16x32_bf16 v[104:107], v[140:143], v[196:199], v[104:107]
	v_mfma_f32_16x16x32_bf16 v[100:103], v[132:135], v[212:215], v[100:103]
	v_mfma_f32_16x16x32_bf16 v[96:99], v[140:143], v[212:215], v[96:99]
	v_mfma_f32_16x16x32_bf16 v[60:63], v[144:147], v[176:179], v[60:63]
	v_mfma_f32_16x16x32_bf16 v[56:59], v[152:155], v[176:179], v[56:59]
	v_mfma_f32_16x16x32_bf16 v[52:55], v[144:147], v[184:187], v[52:55]
	v_mfma_f32_16x16x32_bf16 v[48:51], v[152:155], v[184:187], v[48:51]
	v_mfma_f32_16x16x32_bf16 v[44:47], v[144:147], v[192:195], v[44:47]
	v_mfma_f32_16x16x32_bf16 v[40:43], v[152:155], v[192:195], v[40:43]
	v_mfma_f32_16x16x32_bf16 v[36:39], v[144:147], v[208:211], v[36:39]
	v_mfma_f32_16x16x32_bf16 v[32:35], v[152:155], v[208:211], v[32:35]
	v_mfma_f32_16x16x32_bf16 v[60:63], v[148:151], v[180:183], v[60:63]
	v_mfma_f32_16x16x32_bf16 v[56:59], v[156:159], v[180:183], v[56:59]
	v_mfma_f32_16x16x32_bf16 v[52:55], v[148:151], v[188:191], v[52:55]
	v_mfma_f32_16x16x32_bf16 v[48:51], v[156:159], v[188:191], v[48:51]
	v_mfma_f32_16x16x32_bf16 v[44:47], v[148:151], v[196:199], v[44:47]
	v_mfma_f32_16x16x32_bf16 v[40:43], v[156:159], v[196:199], v[40:43]
	v_mfma_f32_16x16x32_bf16 v[36:39], v[148:151], v[212:215], v[36:39]
	v_mfma_f32_16x16x32_bf16 v[32:35], v[156:159], v[212:215], v[32:35]
	s_barrier
; #define PG8_STAGE(bufoff, gbase, voff) do { _Pragma("unroll") for (int _i = 0; _i < 2; ++_i) \
;         __builtin_amdgcn_global_load_lds((const unsigned*)((const char*)(gbase) + (voff)[_i]), (PG8_LAS unsigned*)(lds + (bufoff) + ldsw + _i * 8192), 16, 0, 0); } while (0)
; #define PG8_LDA(dst, b, h) do { _Pragma("unroll") for (int m = 0; m < 4; ++m) _Pragma("unroll") for (int k = 0; k < 2; ++k) dst[m][k] = *(const PG8_LAS bf16x8*)(lds + PG8_SA(b, h) + aoff + m * 2048 + k * 1024); } while (0)
; #define PG8_MMA(ai, bj, At, Bt) do { __builtin_amdgcn_s_setprio(1); _Pragma("unroll") for (int m = 0; m < 4; ++m) _Pragma("unroll") for (int n = 0; n < 2; ++n) _Pragma("unroll") for (int k = 0; k < 2; ++k) \
;         acc[ai][bj][m][n] = __builtin_amdgcn_mfma_f32_16x16x32_bf16(Bt[n][k], At[m][k], acc[ai][bj][m][n], 0, 0, 0); __builtin_amdgcn_s_setprio(0); } while (0)
; #define PG8_WAIT_V(n) asm volatile("s_waitcnt vmcnt(" #n ")" ::: "memory")
; #define PG8_WAIT_L(n) asm volatile("s_waitcnt lgkmcnt(" #n ")" ::: "memory")
; #define PG8_BAR __builtin_amdgcn_s_barrier()
; #define PG8_SCHED __builtin_amdgcn_sched_barrier(0)
; template <class Epi, class Sched, bool ALIGN_EPI = false, bool SP2 = false>
; __device__ __forceinline__ void gemm_phase(PG8_LAS unsigned char* lds, const Gemm g, const Sched& S, const Epi& E, const int wid) {
;     ...
;         for (int t = 0; t < nt; t += 2) {
;     ...
;             PG8_LDA(At, 1, 1); PG8_STAGE(PG8_SB(1, 0), b3, voffB); PG8_STAGE(PG8_SB(1, 1), b3 + hsB, voffB); PG8_STAGE(PG8_SA(1, 0), a3, voffA);
;             PG8_WAIT_V(8); PG8_WAIT_L(0); PG8_BAR; PG8_MMA(1, 0, At, B0); PG8_MMA(1, 1, At, B1); PG8_BAR; PG8_SCHED;
;     ...
;         if constexpr (ALIGN_EPI) { if (wr == 0) PG8_BAR; }
	s_add_i32 s42, s65, s45
	v_lshl_add_u64 v[200:201], v[200:201], 0, s[16:17]
	s_mov_b32 m0, s42
	ds_read_b128 v[176:179], v207 offset:49152
	ds_read_b128 v[180:183], v207 offset:50176
	ds_read_b128 v[184:187], v207 offset:51200
	ds_read_b128 v[188:191], v207 offset:52224
	ds_read_b128 v[192:195], v207 offset:53248
	ds_read_b128 v[196:199], v207 offset:54272
	ds_read_b128 v[208:211], v207 offset:55296
	ds_read_b128 v[212:215], v207 offset:56320
	global_load_lds_dwordx4 v[200:201], off
	s_add_i32 m0, s42, 0x2000
	s_add_u32 s40, s40, 0x40080
	v_lshl_add_u64 v[200:201], v[216:217], 0, s[16:17]
	s_addc_u32 s41, s41, 0
	s_add_i32 s42, s66, s45
	global_load_lds_dwordx4 v[200:201], off
	v_lshl_add_u64 v[200:201], s[40:41], 0, v[162:163]
	s_mov_b32 m0, s42
	s_nop 0
	global_load_lds_dwordx4 v[200:201], off
	v_lshl_add_u64 v[200:201], s[40:41], 0, v[166:167]
	s_add_i32 m0, s42, 0x2000
	s_nop 0
	global_load_lds_dwordx4 v[200:201], off
	v_lshl_add_u64 v[200:201], v[218:219], 0, s[16:17]
	s_mov_b32 m0, s50
	s_nop 0
	global_load_lds_dwordx4 v[200:201], off
	v_lshl_add_u64 v[200:201], v[220:221], 0, s[16:17]
	s_mov_b32 m0, s51
	s_nop 0
	global_load_lds_dwordx4 v[200:201], off
	s_waitcnt vmcnt(8)
	s_waitcnt lgkmcnt(0)
	s_barrier
	s_waitcnt lgkmcnt(0)
	v_mfma_f32_16x16x32_bf16 v[92:95], v[128:131], v[176:179], v[92:95]
	v_mfma_f32_16x16x32_bf16 v[88:91], v[136:139], v[176:179], v[88:91]
	v_mfma_f32_16x16x32_bf16 v[84:87], v[128:131], v[184:187], v[84:87]
	v_mfma_f32_16x16x32_bf16 v[80:83], v[136:139], v[184:187], v[80:83]
	v_mfma_f32_16x16x32_bf16 v[76:79], v[128:131], v[192:195], v[76:79]
	v_mfma_f32_16x16x32_bf16 v[72:75], v[136:139], v[192:195], v[72:75]
	v_mfma_f32_16x16x32_bf16 v[68:71], v[128:131], v[208:211], v[68:71]
	v_mfma_f32_16x16x32_bf16 v[64:67], v[136:139], v[208:211], v[64:67]
	v_mfma_f32_16x16x32_bf16 v[92:95], v[132:135], v[180:183], v[92:95]
	v_mfma_f32_16x16x32_bf16 v[88:91], v[140:143], v[180:183], v[88:91]
	v_mfma_f32_16x16x32_bf16 v[84:87], v[132:135], v[188:191], v[84:87]
	v_mfma_f32_16x16x32_bf16 v[80:83], v[140:143], v[188:191], v[80:83]
	v_mfma_f32_16x16x32_bf16 v[76:79], v[132:135], v[196:199], v[76:79]
	v_mfma_f32_16x16x32_bf16 v[72:75], v[140:143], v[196:199], v[72:75]
	v_mfma_f32_16x16x32_bf16 v[68:71], v[132:135], v[212:215], v[68:71]
	v_mfma_f32_16x16x32_bf16 v[64:67], v[140:143], v[212:215], v[64:67]
	v_mfma_f32_16x16x32_bf16 v[28:31], v[144:147], v[176:179], v[28:31]
	v_mfma_f32_16x16x32_bf16 v[24:27], v[152:155], v[176:179], v[24:27]
	v_mfma_f32_16x16x32_bf16 v[20:23], v[144:147], v[184:187], v[20:23]
	v_mfma_f32_16x16x32_bf16 v[16:19], v[152:155], v[184:187], v[16:19]
	v_mfma_f32_16x16x32_bf16 v[12:15], v[144:147], v[192:195], v[12:15]
	v_mfma_f32_16x16x32_bf16 v[8:11], v[152:155], v[192:195], v[8:11]
	v_mfma_f32_16x16x32_bf16 v[4:7], v[144:147], v[208:211], v[4:7]
	v_mfma_f32_16x16x32_bf16 v[0:3], v[152:155], v[208:211], v[0:3]
	v_mfma_f32_16x16x32_bf16 v[28:31], v[148:151], v[180:183], v[28:31]
	v_mfma_f32_16x16x32_bf16 v[24:27], v[156:159], v[180:183], v[24:27]
	v_mfma_f32_16x16x32_bf16 v[20:23], v[148:151], v[188:191], v[20:23]
	v_mfma_f32_16x16x32_bf16 v[16:19], v[156:159], v[188:191], v[16:19]
	v_mfma_f32_16x16x32_bf16 v[12:15], v[148:151], v[196:199], v[12:15]
	v_mfma_f32_16x16x32_bf16 v[8:11], v[156:159], v[196:199], v[8:11]
	v_mfma_f32_16x16x32_bf16 v[4:7], v[148:151], v[212:215], v[4:7]
	v_mfma_f32_16x16x32_bf16 v[0:3], v[156:159], v[212:215], v[0:3]
	s_barrier
	s_add_i32 s64, s64, 2
	s_add_u32 s62, s62, 0x100
	s_addc_u32 s63, s63, 0
	s_add_u32 s38, s38, 0x100
	s_addc_u32 s39, s39, 0
	s_cmp_gt_u32 s64, 13
	s_cbranch_scc0 .LBB0_1177
	s_and_b64 vcc, exec, s[18:19]
	s_cbranch_vccz .LBB0_1180
	s_barrier

; #define PG8_STAGE(bufoff, gbase, voff) do { _Pragma("unroll") for (int _i = 0; _i < 2; ++_i) \
;         __builtin_amdgcn_global_load_lds((const unsigned*)((const char*)(gbase) + (voff)[_i]), (PG8_LAS unsigned*)(lds + (bufoff) + ldsw + _i * 8192), 16, 0, 0); } while (0)
; #define PG8_LDA(dst, b, h) do { _Pragma("unroll") for (int m = 0; m < 4; ++m) _Pragma("unroll") for (int k = 0; k < 2; ++k) dst[m][k] = *(const PG8_LAS bf16x8*)(lds + PG8_SA(b, h) + aoff + m * 2048 + k * 1024); } while (0)
; #define PG8_LDB(dst, b, h) do { _Pragma("unroll") for (int n = 0; n < 2; ++n) _Pragma("unroll") for (int k = 0; k < 2; ++k) dst[n][k] = *(const PG8_LAS bf16x8*)(lds + PG8_SB(b, h) + boff + n * 2048 + k * 1024); } while (0)
; #define PG8_MMA(ai, bj, At, Bt) do { __builtin_amdgcn_s_setprio(1); _Pragma("unroll") for (int m = 0; m < 4; ++m) _Pragma("unroll") for (int n = 0; n < 2; ++n) _Pragma("unroll") for (int k = 0; k < 2; ++k) \
;         acc[ai][bj][m][n] = __builtin_amdgcn_mfma_f32_16x16x32_bf16(Bt[n][k], At[m][k], acc[ai][bj][m][n], 0, 0, 0); __builtin_amdgcn_s_setprio(0); } while (0)
; #define PG8_WAIT_V(n) asm volatile("s_waitcnt vmcnt(" #n ")" ::: "memory")
; #define PG8_WAIT_L(n) asm volatile("s_waitcnt lgkmcnt(" #n ")" ::: "memory")
; #define PG8_BAR __builtin_amdgcn_s_barrier()
; template <class Epi, class Sched, bool ALIGN_EPI = false, bool SP2 = false>
; __device__ __forceinline__ void gemm_phase(PG8_LAS unsigned char* lds, const Gemm g, const Sched& S, const Epi& E, const int wid) {
;     ...
;             const bool last = (t == nt - 2);
;             const char* a1 = cA + (size_t)(t + 1) * kstep;
;             const char* a2 = last ? nA : cA + (size_t)(t + 2) * kstep; const char* b2 = last ? nB : cB + (size_t)(t + 2) * kstep;
;             const char* a3 = a2 + kstep; const char* b3 = b2 + kstep;
;             if constexpr (SP2) {
;             PG8_LDB(B0, 0, 0); PG8_LDB(B1, 0, 1); PG8_SCHED; PG8_LDA(At, 0, 0); PG8_STAGE(PG8_SA(1, 1), a1 + hsA, voffA);
;             PG8_WAIT_V(8); PG8_WAIT_L(0); PG8_BAR; PG8_MMA(0, 0, At, B0); PG8_MMA(0, 1, At, B1); PG8_BAR; PG8_SCHED;
;             PG8_LDA(At, 0, 1); PG8_STAGE(PG8_SB(0, 0), b2, voffB); PG8_STAGE(PG8_SB(0, 1), b2 + hsB, voffB); PG8_STAGE(PG8_SA(0, 0), a2, voffA);
;             PG8_WAIT_V(8); PG8_WAIT_L(0); PG8_BAR; PG8_MMA(1, 0, At, B0); PG8_MMA(1, 1, At, B1); PG8_BAR; PG8_SCHED;
.LBB0_1304:
	ds_read_b128 v[64:67], v199
	ds_read_b128 v[72:75], v199 offset:1024
	ds_read_b128 v[80:83], v199 offset:2048
	ds_read_b128 v[84:87], v199 offset:3072
	ds_read_b128 v[88:91], v200
	ds_read_b128 v[92:95], v200 offset:1024
	ds_read_b128 v[100:103], v200 offset:2048
	ds_read_b128 v[104:107], v200 offset:3072
	s_add_u32 s38, s36, 0xfff80080
	s_addc_u32 s39, s37, -1
	s_cmp_eq_u32 s61, 28
	s_cselect_b32 s41, s5, s39
	s_cselect_b32 s40, s27, s38
	s_cselect_b32 s39, s25, s60
	s_cselect_b32 s38, s58, s59
	v_lshl_add_u64 v[196:197], s[36:37], 0, v[182:183]
	s_add_i32 m0, s35, 0xc000
	ds_read_b128 v[160:163], v201
	ds_read_b128 v[164:167], v201 offset:1024
	ds_read_b128 v[168:171], v201 offset:2048
	ds_read_b128 v[172:175], v201 offset:3072
	ds_read_b128 v[188:191], v201 offset:4096
	ds_read_b128 v[192:195], v201 offset:5120
	ds_read_b128 v[204:207], v201 offset:6144
	ds_read_b128 v[208:211], v201 offset:7168
	global_load_lds_dwordx4 v[196:197], off
	v_lshl_add_u64 v[196:197], s[36:37], 0, v[180:181]
	s_add_i32 m0, s35, 0xe000
	s_nop 0
	global_load_lds_dwordx4 v[196:197], off
	s_waitcnt vmcnt(8)
	s_waitcnt lgkmcnt(0)
	s_barrier
	s_waitcnt lgkmcnt(0)
	v_mfma_f32_16x16x32_bf16 v[156:159], v[64:67], v[160:163], v[156:159]
	v_mfma_f32_16x16x32_bf16 v[152:155], v[80:83], v[160:163], v[152:155]
	v_mfma_f32_16x16x32_bf16 v[140:143], v[64:67], v[168:171], v[140:143]
	v_mfma_f32_16x16x32_bf16 v[136:139], v[80:83], v[168:171], v[136:139]
	v_mfma_f32_16x16x32_bf16 v[124:127], v[64:67], v[188:191], v[124:127]
	v_mfma_f32_16x16x32_bf16 v[120:123], v[80:83], v[188:191], v[120:123]
	v_mfma_f32_16x16x32_bf16 v[108:111], v[64:67], v[204:207], v[108:111]
	v_mfma_f32_16x16x32_bf16 v[96:99], v[80:83], v[204:207], v[96:99]
	v_mfma_f32_16x16x32_bf16 v[156:159], v[72:75], v[164:167], v[156:159]
	v_mfma_f32_16x16x32_bf16 v[152:155], v[84:87], v[164:167], v[152:155]
	v_mfma_f32_16x16x32_bf16 v[140:143], v[72:75], v[172:175], v[140:143]
	v_mfma_f32_16x16x32_bf16 v[136:139], v[84:87], v[172:175], v[136:139]
	v_mfma_f32_16x16x32_bf16 v[124:127], v[72:75], v[192:195], v[124:127]
	v_mfma_f32_16x16x32_bf16 v[120:123], v[84:87], v[192:195], v[120:123]
	v_mfma_f32_16x16x32_bf16 v[108:111], v[72:75], v[208:211], v[108:111]
	v_mfma_f32_16x16x32_bf16 v[96:99], v[84:87], v[208:211], v[96:99]
	v_mfma_f32_16x16x32_bf16 v[148:151], v[88:91], v[160:163], v[148:151]
	v_mfma_f32_16x16x32_bf16 v[144:147], v[100:103], v[160:163], v[144:147]
	v_mfma_f32_16x16x32_bf16 v[132:135], v[88:91], v[168:171], v[132:135]
	v_mfma_f32_16x16x32_bf16 v[128:131], v[100:103], v[168:171], v[128:131]
	v_mfma_f32_16x16x32_bf16 v[116:119], v[88:91], v[188:191], v[116:119]
	v_mfma_f32_16x16x32_bf16 v[112:115], v[100:103], v[188:191], v[112:115]
	v_mfma_f32_16x16x32_bf16 v[76:79], v[88:91], v[204:207], v[76:79]
	v_mfma_f32_16x16x32_bf16 v[68:71], v[100:103], v[204:207], v[68:71]
	v_mfma_f32_16x16x32_bf16 v[148:151], v[92:95], v[164:167], v[148:151]
	v_mfma_f32_16x16x32_bf16 v[144:147], v[104:107], v[164:167], v[144:147]
	v_mfma_f32_16x16x32_bf16 v[132:135], v[92:95], v[172:175], v[132:135]
	v_mfma_f32_16x16x32_bf16 v[128:131], v[104:107], v[172:175], v[128:131]
	v_mfma_f32_16x16x32_bf16 v[116:119], v[92:95], v[192:195], v[116:119]
	v_mfma_f32_16x16x32_bf16 v[112:115], v[104:107], v[192:195], v[112:115]
	v_mfma_f32_16x16x32_bf16 v[76:79], v[92:95], v[208:211], v[76:79]
	v_mfma_f32_16x16x32_bf16 v[68:71], v[104:107], v[208:211], v[68:71]
	s_barrier
	s_add_i32 s62, s56, s44
	v_lshl_add_u64 v[196:197], s[38:39], 0, v[176:177]
	s_mov_b32 m0, s62
	ds_read_b128 v[160:163], v201 offset:16384
	ds_read_b128 v[164:167], v201 offset:17408
	ds_read_b128 v[168:171], v201 offset:18432
	ds_read_b128 v[172:175], v201 offset:19456
	ds_read_b128 v[188:191], v201 offset:20480
	ds_read_b128 v[192:195], v201 offset:21504
	ds_read_b128 v[204:207], v201 offset:22528
	ds_read_b128 v[208:211], v201 offset:23552
	global_load_lds_dwordx4 v[196:197], off
	s_add_i32 m0, s62, 0x2000
	s_add_u32 s62, s38, 0x80000
	v_lshl_add_u64 v[212:213], s[38:39], 0, v[178:179]
	s_addc_u32 s63, s39, 0
	s_add_i32 s64, s57, s44
	global_load_lds_dwordx4 v[212:213], off
	v_lshl_add_u64 v[214:215], s[62:63], 0, v[176:177]
	s_mov_b32 m0, s64
	v_lshl_add_u64 v[216:217], s[40:41], 0, v[178:179]
	global_load_lds_dwordx4 v[214:215], off
	v_lshl_add_u64 v[214:215], s[62:63], 0, v[178:179]
	s_add_i32 m0, s64, 0x2000
	s_nop 0
	global_load_lds_dwordx4 v[214:215], off
	v_lshl_add_u64 v[214:215], s[40:41], 0, v[176:177]
	s_mov_b32 m0, s35
	s_nop 0
	global_load_lds_dwordx4 v[214:215], off
	s_mov_b32 m0, s45
	s_nop 0
	global_load_lds_dwordx4 v[216:217], off
	s_waitcnt vmcnt(8)
	s_waitcnt lgkmcnt(0)
	s_barrier
; #define PG8_STAGE(bufoff, gbase, voff) do { _Pragma("unroll") for (int _i = 0; _i < 2; ++_i) \
;         __builtin_amdgcn_global_load_lds((const unsigned*)((const char*)(gbase) + (voff)[_i]), (PG8_LAS unsigned*)(lds + (bufoff) + ldsw + _i * 8192), 16, 0, 0); } while (0)
; #define PG8_LDA(dst, b, h) do { _Pragma("unroll") for (int m = 0; m < 4; ++m) _Pragma("unroll") for (int k = 0; k < 2; ++k) dst[m][k] = *(const PG8_LAS bf16x8*)(lds + PG8_SA(b, h) + aoff + m * 2048 + k * 1024); } while (0)
; #define PG8_LDB(dst, b, h) do { _Pragma("unroll") for (int n = 0; n < 2; ++n) _Pragma("unroll") for (int k = 0; k < 2; ++k) dst[n][k] = *(const PG8_LAS bf16x8*)(lds + PG8_SB(b, h) + boff + n * 2048 + k * 1024); } while (0)
; #define PG8_MMA(ai, bj, At, Bt) do { __builtin_amdgcn_s_setprio(1); _Pragma("unroll") for (int m = 0; m < 4; ++m) _Pragma("unroll") for (int n = 0; n < 2; ++n) _Pragma("unroll") for (int k = 0; k < 2; ++k) \
;         acc[ai][bj][m][n] = __builtin_amdgcn_mfma_f32_16x16x32_bf16(Bt[n][k], At[m][k], acc[ai][bj][m][n], 0, 0, 0); __builtin_amdgcn_s_setprio(0); } while (0)
; #define PG8_WAIT_V(n) asm volatile("s_waitcnt vmcnt(" #n ")" ::: "memory")
; #define PG8_WAIT_L(n) asm volatile("s_waitcnt lgkmcnt(" #n ")" ::: "memory")
; #define PG8_BAR __builtin_amdgcn_s_barrier()
; #define PG8_SCHED __builtin_amdgcn_sched_barrier(0)
; template <class Epi, class Sched, bool ALIGN_EPI = false, bool SP2 = false>
; __device__ __forceinline__ void gemm_phase(PG8_LAS unsigned char* lds, const Gemm g, const Sched& S, const Epi& E, const int wid) {
;     ...
;             PG8_WAIT_V(8); PG8_WAIT_L(0); PG8_BAR; PG8_MMA(1, 0, At, B0); PG8_MMA(1, 1, At, B1); PG8_BAR; PG8_SCHED;
;             PG8_LDB(B0, 1, 0); PG8_LDB(B1, 1, 1); PG8_SCHED; PG8_LDA(At, 1, 0); PG8_STAGE(PG8_SA(0, 1), a2 + hsA, voffA);
;             PG8_WAIT_V(8); PG8_WAIT_L(0); PG8_BAR; PG8_MMA(0, 0, At, B0); PG8_MMA(0, 1, At, B1); PG8_BAR; PG8_SCHED;
	s_waitcnt lgkmcnt(0)
	v_mfma_f32_16x16x32_bf16 v[60:63], v[64:67], v[160:163], v[60:63]
	v_mfma_f32_16x16x32_bf16 v[56:59], v[80:83], v[160:163], v[56:59]
	v_mfma_f32_16x16x32_bf16 v[44:47], v[64:67], v[168:171], v[44:47]
	v_mfma_f32_16x16x32_bf16 v[40:43], v[80:83], v[168:171], v[40:43]
	v_mfma_f32_16x16x32_bf16 v[28:31], v[64:67], v[188:191], v[28:31]
	v_mfma_f32_16x16x32_bf16 v[24:27], v[80:83], v[188:191], v[24:27]
	v_mfma_f32_16x16x32_bf16 v[12:15], v[64:67], v[204:207], v[12:15]
	v_mfma_f32_16x16x32_bf16 v[8:11], v[80:83], v[204:207], v[8:11]
	v_mfma_f32_16x16x32_bf16 v[60:63], v[72:75], v[164:167], v[60:63]
	v_mfma_f32_16x16x32_bf16 v[56:59], v[84:87], v[164:167], v[56:59]
	v_mfma_f32_16x16x32_bf16 v[44:47], v[72:75], v[172:175], v[44:47]
	v_mfma_f32_16x16x32_bf16 v[40:43], v[84:87], v[172:175], v[40:43]
	v_mfma_f32_16x16x32_bf16 v[28:31], v[72:75], v[192:195], v[28:31]
	v_mfma_f32_16x16x32_bf16 v[24:27], v[84:87], v[192:195], v[24:27]
	v_mfma_f32_16x16x32_bf16 v[12:15], v[72:75], v[208:211], v[12:15]
	v_mfma_f32_16x16x32_bf16 v[8:11], v[84:87], v[208:211], v[8:11]
	v_mfma_f32_16x16x32_bf16 v[52:55], v[88:91], v[160:163], v[52:55]
	v_mfma_f32_16x16x32_bf16 v[48:51], v[100:103], v[160:163], v[48:51]
	v_mfma_f32_16x16x32_bf16 v[36:39], v[88:91], v[168:171], v[36:39]
	v_mfma_f32_16x16x32_bf16 v[32:35], v[100:103], v[168:171], v[32:35]
	v_mfma_f32_16x16x32_bf16 v[20:23], v[88:91], v[188:191], v[20:23]
	v_mfma_f32_16x16x32_bf16 v[16:19], v[100:103], v[188:191], v[16:19]
	v_mfma_f32_16x16x32_bf16 v[4:7], v[88:91], v[204:207], v[4:7]
	v_mfma_f32_16x16x32_bf16 v[0:3], v[100:103], v[204:207], v[0:3]
	v_mfma_f32_16x16x32_bf16 v[52:55], v[92:95], v[164:167], v[52:55]
	v_mfma_f32_16x16x32_bf16 v[48:51], v[104:107], v[164:167], v[48:51]
	v_mfma_f32_16x16x32_bf16 v[36:39], v[92:95], v[172:175], v[36:39]
	v_mfma_f32_16x16x32_bf16 v[32:35], v[104:107], v[172:175], v[32:35]
	v_mfma_f32_16x16x32_bf16 v[20:23], v[92:95], v[192:195], v[20:23]
	v_mfma_f32_16x16x32_bf16 v[16:19], v[104:107], v[192:195], v[16:19]
	v_mfma_f32_16x16x32_bf16 v[4:7], v[92:95], v[208:211], v[4:7]
	v_mfma_f32_16x16x32_bf16 v[0:3], v[104:107], v[208:211], v[0:3]
	s_barrier
	s_add_i32 s62, 0, 0x18000
	s_add_i32 s63, 0, 0x1c000
	v_add_u32_e32 v84, s62, v198
	v_add_u32_e32 v104, s63, v198
	ds_read_b128 v[64:67], v84
	ds_read_b128 v[72:75], v84 offset:1024
	ds_read_b128 v[80:83], v84 offset:2048
	ds_read_b128 v[84:87], v84 offset:3072
	ds_read_b128 v[88:91], v104
	ds_read_b128 v[92:95], v104 offset:1024
	ds_read_b128 v[100:103], v104 offset:2048
	ds_read_b128 v[104:107], v104 offset:3072
	s_add_u32 s40, s40, 0x80000
	s_addc_u32 s41, s41, 0
	s_mov_b32 m0, s46
	v_lshl_add_u64 v[218:219], s[40:41], 0, v[176:177]
	ds_read_b128 v[160:163], v201 offset:32768
	ds_read_b128 v[164:167], v201 offset:33792
	ds_read_b128 v[168:171], v201 offset:34816
	ds_read_b128 v[172:175], v201 offset:35840
	ds_read_b128 v[188:191], v201 offset:36864
	ds_read_b128 v[192:195], v201 offset:37888
	ds_read_b128 v[204:207], v201 offset:38912
	ds_read_b128 v[208:211], v201 offset:39936
	global_load_lds_dwordx4 v[218:219], off
	v_lshl_add_u64 v[218:219], s[40:41], 0, v[178:179]
	s_mov_b32 m0, s47
	s_nop 0
	global_load_lds_dwordx4 v[218:219], off
	s_waitcnt vmcnt(8)
	s_waitcnt lgkmcnt(0)
	s_barrier
	s_waitcnt lgkmcnt(0)
	v_mfma_f32_16x16x32_bf16 v[156:159], v[64:67], v[160:163], v[156:159]
	v_mfma_f32_16x16x32_bf16 v[152:155], v[80:83], v[160:163], v[152:155]
	v_mfma_f32_16x16x32_bf16 v[140:143], v[64:67], v[168:171], v[140:143]
	v_mfma_f32_16x16x32_bf16 v[136:139], v[80:83], v[168:171], v[136:139]
	v_mfma_f32_16x16x32_bf16 v[124:127], v[64:67], v[188:191], v[124:127]
	v_mfma_f32_16x16x32_bf16 v[120:123], v[80:83], v[188:191], v[120:123]
	v_mfma_f32_16x16x32_bf16 v[108:111], v[64:67], v[204:207], v[108:111]
	v_mfma_f32_16x16x32_bf16 v[96:99], v[80:83], v[204:207], v[96:99]
	v_mfma_f32_16x16x32_bf16 v[156:159], v[72:75], v[164:167], v[156:159]
	v_mfma_f32_16x16x32_bf16 v[152:155], v[84:87], v[164:167], v[152:155]
	v_mfma_f32_16x16x32_bf16 v[140:143], v[72:75], v[172:175], v[140:143]
	v_mfma_f32_16x16x32_bf16 v[136:139], v[84:87], v[172:175], v[136:139]
	v_mfma_f32_16x16x32_bf16 v[124:127], v[72:75], v[192:195], v[124:127]
	v_mfma_f32_16x16x32_bf16 v[120:123], v[84:87], v[192:195], v[120:123]
	v_mfma_f32_16x16x32_bf16 v[108:111], v[72:75], v[208:211], v[108:111]
	v_mfma_f32_16x16x32_bf16 v[96:99], v[84:87], v[208:211], v[96:99]
	v_mfma_f32_16x16x32_bf16 v[148:151], v[88:91], v[160:163], v[148:151]
	v_mfma_f32_16x16x32_bf16 v[144:147], v[100:103], v[160:163], v[144:147]
	v_mfma_f32_16x16x32_bf16 v[132:135], v[88:91], v[168:171], v[132:135]
	v_mfma_f32_16x16x32_bf16 v[128:131], v[100:103], v[168:171], v[128:131]
	v_mfma_f32_16x16x32_bf16 v[116:119], v[88:91], v[188:191], v[116:119]
	v_mfma_f32_16x16x32_bf16 v[112:115], v[100:103], v[188:191], v[112:115]
	v_mfma_f32_16x16x32_bf16 v[76:79], v[88:91], v[204:207], v[76:79]
	v_mfma_f32_16x16x32_bf16 v[68:71], v[100:103], v[204:207], v[68:71]
	v_mfma_f32_16x16x32_bf16 v[148:151], v[92:95], v[164:167], v[148:151]
	v_mfma_f32_16x16x32_bf16 v[144:147], v[104:107], v[164:167], v[144:147]
	v_mfma_f32_16x16x32_bf16 v[132:135], v[92:95], v[172:175], v[132:135]
	v_mfma_f32_16x16x32_bf16 v[128:131], v[104:107], v[172:175], v[128:131]
	v_mfma_f32_16x16x32_bf16 v[116:119], v[92:95], v[192:195], v[116:119]
	v_mfma_f32_16x16x32_bf16 v[112:115], v[104:107], v[192:195], v[112:115]
	v_mfma_f32_16x16x32_bf16 v[76:79], v[92:95], v[208:211], v[76:79]
	v_mfma_f32_16x16x32_bf16 v[68:71], v[104:107], v[208:211], v[68:71]
	s_barrier
; #define PG8_STAGE(bufoff, gbase, voff) do { _Pragma("unroll") for (int _i = 0; _i < 2; ++_i) \
;         __builtin_amdgcn_global_load_lds((const unsigned*)((const char*)(gbase) + (voff)[_i]), (PG8_LAS unsigned*)(lds + (bufoff) + ldsw + _i * 8192), 16, 0, 0); } while (0)
; #define PG8_LDA(dst, b, h) do { _Pragma("unroll") for (int m = 0; m < 4; ++m) _Pragma("unroll") for (int k = 0; k < 2; ++k) dst[m][k] = *(const PG8_LAS bf16x8*)(lds + PG8_SA(b, h) + aoff + m * 2048 + k * 1024); } while (0)
; #define PG8_MMA(ai, bj, At, Bt) do { __builtin_amdgcn_s_setprio(1); _Pragma("unroll") for (int m = 0; m < 4; ++m) _Pragma("unroll") for (int n = 0; n < 2; ++n) _Pragma("unroll") for (int k = 0; k < 2; ++k) \
;         acc[ai][bj][m][n] = __builtin_amdgcn_mfma_f32_16x16x32_bf16(Bt[n][k], At[m][k], acc[ai][bj][m][n], 0, 0, 0); __builtin_amdgcn_s_setprio(0); } while (0)
; #define PG8_WAIT_V(n) asm volatile("s_waitcnt vmcnt(" #n ")" ::: "memory")
; #define PG8_WAIT_L(n) asm volatile("s_waitcnt lgkmcnt(" #n ")" ::: "memory")
; #define PG8_BAR __builtin_amdgcn_s_barrier()
; #define PG8_SCHED __builtin_amdgcn_sched_barrier(0)
; template <class Epi, class Sched, bool ALIGN_EPI = false, bool SP2 = false>
; __device__ __forceinline__ void gemm_phase(PG8_LAS unsigned char* lds, const Gemm g, const Sched& S, const Epi& E, const int wid) {
;     ...
;         for (int t = 0; t < nt; t += 2) {
;     ...
;             PG8_LDA(At, 1, 1); PG8_STAGE(PG8_SB(1, 0), b3, voffB); PG8_STAGE(PG8_SB(1, 1), b3 + hsB, voffB); PG8_STAGE(PG8_SA(1, 0), a3, voffA);
;             PG8_WAIT_V(8); PG8_WAIT_L(0); PG8_BAR; PG8_MMA(1, 0, At, B0); PG8_MMA(1, 1, At, B1); PG8_BAR; PG8_SCHED;
;     ...
;         if constexpr (ALIGN_EPI) { if (wr == 0) PG8_BAR; }
	s_add_i32 s40, s62, s44
	v_lshl_add_u64 v[196:197], v[196:197], 0, s[20:21]
	s_mov_b32 m0, s40
	ds_read_b128 v[160:163], v201 offset:49152
	ds_read_b128 v[164:167], v201 offset:50176
	ds_read_b128 v[168:171], v201 offset:51200
	ds_read_b128 v[172:175], v201 offset:52224
	ds_read_b128 v[188:191], v201 offset:53248
	ds_read_b128 v[192:195], v201 offset:54272
	ds_read_b128 v[204:207], v201 offset:55296
	ds_read_b128 v[208:211], v201 offset:56320
	global_load_lds_dwordx4 v[196:197], off
	s_add_i32 m0, s40, 0x2000
	s_add_u32 s38, s38, 0x80080
	v_lshl_add_u64 v[196:197], v[212:213], 0, s[20:21]
	s_addc_u32 s39, s39, 0
	s_add_i32 s40, s63, s44
	global_load_lds_dwordx4 v[196:197], off
	v_lshl_add_u64 v[196:197], s[38:39], 0, v[176:177]
	s_mov_b32 m0, s40
	s_nop 0
	global_load_lds_dwordx4 v[196:197], off
	v_lshl_add_u64 v[196:197], s[38:39], 0, v[178:179]
	s_add_i32 m0, s40, 0x2000
	s_nop 0
	global_load_lds_dwordx4 v[196:197], off
	v_lshl_add_u64 v[196:197], v[214:215], 0, s[20:21]
	s_mov_b32 m0, s51
	s_nop 0
	global_load_lds_dwordx4 v[196:197], off
	v_lshl_add_u64 v[196:197], v[216:217], 0, s[20:21]
	s_mov_b32 m0, s52
	s_nop 0
	global_load_lds_dwordx4 v[196:197], off
	s_waitcnt vmcnt(8)
	s_waitcnt lgkmcnt(0)
	s_barrier
	s_waitcnt lgkmcnt(0)
	v_mfma_f32_16x16x32_bf16 v[60:63], v[64:67], v[160:163], v[60:63]
	v_mfma_f32_16x16x32_bf16 v[56:59], v[80:83], v[160:163], v[56:59]
	v_mfma_f32_16x16x32_bf16 v[44:47], v[64:67], v[168:171], v[44:47]
	v_mfma_f32_16x16x32_bf16 v[40:43], v[80:83], v[168:171], v[40:43]
	v_mfma_f32_16x16x32_bf16 v[28:31], v[64:67], v[188:191], v[28:31]
	v_mfma_f32_16x16x32_bf16 v[24:27], v[80:83], v[188:191], v[24:27]
	v_mfma_f32_16x16x32_bf16 v[12:15], v[64:67], v[204:207], v[12:15]
	v_mfma_f32_16x16x32_bf16 v[8:11], v[80:83], v[204:207], v[8:11]
	v_mfma_f32_16x16x32_bf16 v[60:63], v[72:75], v[164:167], v[60:63]
	v_mfma_f32_16x16x32_bf16 v[56:59], v[84:87], v[164:167], v[56:59]
	v_mfma_f32_16x16x32_bf16 v[44:47], v[72:75], v[172:175], v[44:47]
	v_mfma_f32_16x16x32_bf16 v[40:43], v[84:87], v[172:175], v[40:43]
	v_mfma_f32_16x16x32_bf16 v[28:31], v[72:75], v[192:195], v[28:31]
	v_mfma_f32_16x16x32_bf16 v[24:27], v[84:87], v[192:195], v[24:27]
	v_mfma_f32_16x16x32_bf16 v[12:15], v[72:75], v[208:211], v[12:15]
	v_mfma_f32_16x16x32_bf16 v[8:11], v[84:87], v[208:211], v[8:11]
	v_mfma_f32_16x16x32_bf16 v[52:55], v[88:91], v[160:163], v[52:55]
	v_mfma_f32_16x16x32_bf16 v[48:51], v[100:103], v[160:163], v[48:51]
	v_mfma_f32_16x16x32_bf16 v[36:39], v[88:91], v[168:171], v[36:39]
	v_mfma_f32_16x16x32_bf16 v[32:35], v[100:103], v[168:171], v[32:35]
	v_mfma_f32_16x16x32_bf16 v[20:23], v[88:91], v[188:191], v[20:23]
	v_mfma_f32_16x16x32_bf16 v[16:19], v[100:103], v[188:191], v[16:19]
	v_mfma_f32_16x16x32_bf16 v[4:7], v[88:91], v[204:207], v[4:7]
	v_mfma_f32_16x16x32_bf16 v[0:3], v[100:103], v[204:207], v[0:3]
	v_mfma_f32_16x16x32_bf16 v[52:55], v[92:95], v[164:167], v[52:55]
	v_mfma_f32_16x16x32_bf16 v[48:51], v[104:107], v[164:167], v[48:51]
	v_mfma_f32_16x16x32_bf16 v[36:39], v[92:95], v[172:175], v[36:39]
	v_mfma_f32_16x16x32_bf16 v[32:35], v[104:107], v[172:175], v[32:35]
	v_mfma_f32_16x16x32_bf16 v[20:23], v[92:95], v[192:195], v[20:23]
	v_mfma_f32_16x16x32_bf16 v[16:19], v[104:107], v[192:195], v[16:19]
	v_mfma_f32_16x16x32_bf16 v[4:7], v[92:95], v[208:211], v[4:7]
	v_mfma_f32_16x16x32_bf16 v[0:3], v[104:107], v[208:211], v[0:3]
	s_barrier
	s_add_i32 s61, s61, 2
	s_add_u32 s59, s59, 0x100
	s_addc_u32 s60, s60, 0
	s_add_u32 s36, s36, 0x100
	s_addc_u32 s37, s37, 0
	s_cmp_gt_u32 s61, 29
	s_cbranch_scc0 .LBB0_1304
	s_and_b64 vcc, exec, s[22:23]
	s_cbranch_vccz .LBB0_1307
	s_barrier

; #define PG8_STAGE(bufoff, gbase, voff) do { _Pragma("unroll") for (int _i = 0; _i < 2; ++_i) \
;         __builtin_amdgcn_global_load_lds((const unsigned*)((const char*)(gbase) + (voff)[_i]), (PG8_LAS unsigned*)(lds + (bufoff) + ldsw + _i * 8192), 16, 0, 0); } while (0)
; #define PG8_LDA(dst, b, h) do { _Pragma("unroll") for (int m = 0; m < 4; ++m) _Pragma("unroll") for (int k = 0; k < 2; ++k) dst[m][k] = *(const PG8_LAS bf16x8*)(lds + PG8_SA(b, h) + aoff + m * 2048 + k * 1024); } while (0)
; #define PG8_LDB(dst, b, h) do { _Pragma("unroll") for (int n = 0; n < 2; ++n) _Pragma("unroll") for (int k = 0; k < 2; ++k) dst[n][k] = *(const PG8_LAS bf16x8*)(lds + PG8_SB(b, h) + boff + n * 2048 + k * 1024); } while (0)
; #define PG8_MMA(ai, bj, At, Bt) do { __builtin_amdgcn_s_setprio(1); _Pragma("unroll") for (int m = 0; m < 4; ++m) _Pragma("unroll") for (int n = 0; n < 2; ++n) _Pragma("unroll") for (int k = 0; k < 2; ++k) \
;         acc[ai][bj][m][n] = __builtin_amdgcn_mfma_f32_16x16x32_bf16(Bt[n][k], At[m][k], acc[ai][bj][m][n], 0, 0, 0); __builtin_amdgcn_s_setprio(0); } while (0)
; #define PG8_WAIT_V(n) asm volatile("s_waitcnt vmcnt(" #n ")" ::: "memory")
; #define PG8_WAIT_L(n) asm volatile("s_waitcnt lgkmcnt(" #n ")" ::: "memory")
; #define PG8_BAR __builtin_amdgcn_s_barrier()
; template <class Epi, class Sched, bool ALIGN_EPI = false, bool SP2 = false>
; __device__ __forceinline__ void gemm_phase(PG8_LAS unsigned char* lds, const Gemm g, const Sched& S, const Epi& E, const int wid) {
;     ...
;             const bool last = (t == nt - 2);
;             const char* a1 = cA + (size_t)(t + 1) * kstep;
;             const char* a2 = last ? nA : cA + (size_t)(t + 2) * kstep; const char* b2 = last ? nB : cB + (size_t)(t + 2) * kstep;
;             const char* a3 = a2 + kstep; const char* b3 = b2 + kstep;
;             if constexpr (SP2) {
;             PG8_LDB(B0, 0, 0); PG8_LDB(B1, 0, 1); PG8_SCHED; PG8_LDA(At, 0, 0); PG8_STAGE(PG8_SA(1, 1), a1 + hsA, voffA);
;             PG8_WAIT_V(8); PG8_WAIT_L(0); PG8_BAR; PG8_MMA(0, 0, At, B0); PG8_MMA(0, 1, At, B1); PG8_BAR; PG8_SCHED;
;             PG8_LDA(At, 0, 1); PG8_STAGE(PG8_SB(0, 0), b2, voffB); PG8_STAGE(PG8_SB(0, 1), b2 + hsB, voffB); PG8_STAGE(PG8_SA(0, 0), a2, voffA);
;             PG8_WAIT_V(8); PG8_WAIT_L(0); PG8_BAR; PG8_MMA(1, 0, At, B0); PG8_MMA(1, 1, At, B1); PG8_BAR; PG8_SCHED;
.LBB0_1385:
	ds_read_b128 v[128:131], v171
	ds_read_b128 v[132:135], v171 offset:1024
	ds_read_b128 v[136:139], v171 offset:2048
	ds_read_b128 v[140:143], v171 offset:3072
	ds_read_b128 v[160:163], v173
	ds_read_b128 v[164:167], v173 offset:1024
	ds_read_b128 v[180:183], v173 offset:2048
	ds_read_b128 v[184:187], v173 offset:3072
	s_add_u32 s8, s6, 0xfff80080
	s_addc_u32 s9, s7, -1
	s_cmp_eq_u32 s60, 28
	s_cselect_b32 s31, s5, s9
	s_cselect_b32 s30, s25, s8
	s_cselect_b32 s9, s23, s59
	s_cselect_b32 s8, s57, s58
	v_lshl_add_u64 v[220:221], s[6:7], 0, v[154:155]
	s_add_i32 m0, s39, 0xc000
	ds_read_b128 v[188:191], v175
	ds_read_b128 v[192:195], v175 offset:1024
	ds_read_b128 v[196:199], v175 offset:2048
	ds_read_b128 v[200:203], v175 offset:3072
	ds_read_b128 v[204:207], v175 offset:4096
	ds_read_b128 v[208:211], v175 offset:5120
	ds_read_b128 v[212:215], v175 offset:6144
	ds_read_b128 v[216:219], v175 offset:7168
	global_load_lds_dwordx4 v[220:221], off
	v_lshl_add_u64 v[220:221], s[6:7], 0, v[152:153]
	s_add_i32 m0, s39, 0xe000
	s_nop 0
	global_load_lds_dwordx4 v[220:221], off
	s_waitcnt vmcnt(8)
	s_waitcnt lgkmcnt(0)
	s_barrier
	s_waitcnt lgkmcnt(0)
	v_mfma_f32_16x16x32_bf16 v[124:127], v[128:131], v[188:191], v[124:127]
	v_mfma_f32_16x16x32_bf16 v[120:123], v[136:139], v[188:191], v[120:123]
	v_mfma_f32_16x16x32_bf16 v[108:111], v[128:131], v[196:199], v[108:111]
	v_mfma_f32_16x16x32_bf16 v[104:107], v[136:139], v[196:199], v[104:107]
	v_mfma_f32_16x16x32_bf16 v[92:95], v[128:131], v[204:207], v[92:95]
	v_mfma_f32_16x16x32_bf16 v[88:91], v[136:139], v[204:207], v[88:91]
	v_mfma_f32_16x16x32_bf16 v[76:79], v[128:131], v[212:215], v[76:79]
	v_mfma_f32_16x16x32_bf16 v[72:75], v[136:139], v[212:215], v[72:75]
	v_mfma_f32_16x16x32_bf16 v[124:127], v[132:135], v[192:195], v[124:127]
	v_mfma_f32_16x16x32_bf16 v[120:123], v[140:143], v[192:195], v[120:123]
	v_mfma_f32_16x16x32_bf16 v[108:111], v[132:135], v[200:203], v[108:111]
	v_mfma_f32_16x16x32_bf16 v[104:107], v[140:143], v[200:203], v[104:107]
	v_mfma_f32_16x16x32_bf16 v[92:95], v[132:135], v[208:211], v[92:95]
	v_mfma_f32_16x16x32_bf16 v[88:91], v[140:143], v[208:211], v[88:91]
	v_mfma_f32_16x16x32_bf16 v[76:79], v[132:135], v[216:219], v[76:79]
	v_mfma_f32_16x16x32_bf16 v[72:75], v[140:143], v[216:219], v[72:75]
	v_mfma_f32_16x16x32_bf16 v[116:119], v[160:163], v[188:191], v[116:119]
	v_mfma_f32_16x16x32_bf16 v[112:115], v[180:183], v[188:191], v[112:115]
	v_mfma_f32_16x16x32_bf16 v[100:103], v[160:163], v[196:199], v[100:103]
	v_mfma_f32_16x16x32_bf16 v[96:99], v[180:183], v[196:199], v[96:99]
	v_mfma_f32_16x16x32_bf16 v[84:87], v[160:163], v[204:207], v[84:87]
	v_mfma_f32_16x16x32_bf16 v[80:83], v[180:183], v[204:207], v[80:83]
	v_mfma_f32_16x16x32_bf16 v[68:71], v[160:163], v[212:215], v[68:71]
	v_mfma_f32_16x16x32_bf16 v[64:67], v[180:183], v[212:215], v[64:67]
	v_mfma_f32_16x16x32_bf16 v[116:119], v[164:167], v[192:195], v[116:119]
	v_mfma_f32_16x16x32_bf16 v[112:115], v[184:187], v[192:195], v[112:115]
	v_mfma_f32_16x16x32_bf16 v[100:103], v[164:167], v[200:203], v[100:103]
	v_mfma_f32_16x16x32_bf16 v[96:99], v[184:187], v[200:203], v[96:99]
	v_mfma_f32_16x16x32_bf16 v[84:87], v[164:167], v[208:211], v[84:87]
	v_mfma_f32_16x16x32_bf16 v[80:83], v[184:187], v[208:211], v[80:83]
	v_mfma_f32_16x16x32_bf16 v[68:71], v[164:167], v[216:219], v[68:71]
	v_mfma_f32_16x16x32_bf16 v[64:67], v[184:187], v[216:219], v[64:67]
	s_barrier
	s_add_i32 s61, s52, s36
	v_lshl_add_u64 v[220:221], s[8:9], 0, v[148:149]
	s_mov_b32 m0, s61
	ds_read_b128 v[188:191], v175 offset:16384
	ds_read_b128 v[192:195], v175 offset:17408
	ds_read_b128 v[196:199], v175 offset:18432
	ds_read_b128 v[200:203], v175 offset:19456
	ds_read_b128 v[204:207], v175 offset:20480
	ds_read_b128 v[208:211], v175 offset:21504
	ds_read_b128 v[212:215], v175 offset:22528
	ds_read_b128 v[216:219], v175 offset:23552
	global_load_lds_dwordx4 v[220:221], off
	s_add_i32 m0, s61, 0x2000
	s_add_u32 s62, s8, 0x80000
	v_lshl_add_u64 v[222:223], s[8:9], 0, v[144:145]
	s_addc_u32 s63, s9, 0
	s_add_i32 s61, s53, s36
	global_load_lds_dwordx4 v[222:223], off
	v_lshl_add_u64 v[224:225], s[62:63], 0, v[148:149]
	s_mov_b32 m0, s61
	v_lshl_add_u64 v[226:227], s[30:31], 0, v[146:147]
	global_load_lds_dwordx4 v[224:225], off
	v_lshl_add_u64 v[224:225], s[62:63], 0, v[144:145]
	s_add_i32 m0, s61, 0x2000
	s_nop 0
	global_load_lds_dwordx4 v[224:225], off
	v_lshl_add_u64 v[224:225], s[30:31], 0, v[150:151]
	s_mov_b32 m0, s39
	s_nop 0
	global_load_lds_dwordx4 v[224:225], off
	s_mov_b32 m0, s40
	s_nop 0
	global_load_lds_dwordx4 v[226:227], off
	s_waitcnt vmcnt(8)
	s_waitcnt lgkmcnt(0)
	s_barrier
; #define PG8_STAGE(bufoff, gbase, voff) do { _Pragma("unroll") for (int _i = 0; _i < 2; ++_i) \
;         __builtin_amdgcn_global_load_lds((const unsigned*)((const char*)(gbase) + (voff)[_i]), (PG8_LAS unsigned*)(lds + (bufoff) + ldsw + _i * 8192), 16, 0, 0); } while (0)
; #define PG8_LDA(dst, b, h) do { _Pragma("unroll") for (int m = 0; m < 4; ++m) _Pragma("unroll") for (int k = 0; k < 2; ++k) dst[m][k] = *(const PG8_LAS bf16x8*)(lds + PG8_SA(b, h) + aoff + m * 2048 + k * 1024); } while (0)
; #define PG8_LDB(dst, b, h) do { _Pragma("unroll") for (int n = 0; n < 2; ++n) _Pragma("unroll") for (int k = 0; k < 2; ++k) dst[n][k] = *(const PG8_LAS bf16x8*)(lds + PG8_SB(b, h) + boff + n * 2048 + k * 1024); } while (0)
; #define PG8_MMA(ai, bj, At, Bt) do { __builtin_amdgcn_s_setprio(1); _Pragma("unroll") for (int m = 0; m < 4; ++m) _Pragma("unroll") for (int n = 0; n < 2; ++n) _Pragma("unroll") for (int k = 0; k < 2; ++k) \
;         acc[ai][bj][m][n] = __builtin_amdgcn_mfma_f32_16x16x32_bf16(Bt[n][k], At[m][k], acc[ai][bj][m][n], 0, 0, 0); __builtin_amdgcn_s_setprio(0); } while (0)
; #define PG8_WAIT_V(n) asm volatile("s_waitcnt vmcnt(" #n ")" ::: "memory")
; #define PG8_WAIT_L(n) asm volatile("s_waitcnt lgkmcnt(" #n ")" ::: "memory")
; #define PG8_BAR __builtin_amdgcn_s_barrier()
; #define PG8_SCHED __builtin_amdgcn_sched_barrier(0)
; template <class Epi, class Sched, bool ALIGN_EPI = false, bool SP2 = false>
; __device__ __forceinline__ void gemm_phase(PG8_LAS unsigned char* lds, const Gemm g, const Sched& S, const Epi& E, const int wid) {
;     ...
;             PG8_WAIT_V(8); PG8_WAIT_L(0); PG8_BAR; PG8_MMA(1, 0, At, B0); PG8_MMA(1, 1, At, B1); PG8_BAR; PG8_SCHED;
;             PG8_LDB(B0, 1, 0); PG8_LDB(B1, 1, 1); PG8_SCHED; PG8_LDA(At, 1, 0); PG8_STAGE(PG8_SA(0, 1), a2 + hsA, voffA);
;             PG8_WAIT_V(8); PG8_WAIT_L(0); PG8_BAR; PG8_MMA(0, 0, At, B0); PG8_MMA(0, 1, At, B1); PG8_BAR; PG8_SCHED;
	s_waitcnt lgkmcnt(0)
	v_mfma_f32_16x16x32_bf16 v[60:63], v[128:131], v[188:191], v[60:63]
	v_mfma_f32_16x16x32_bf16 v[56:59], v[136:139], v[188:191], v[56:59]
	v_mfma_f32_16x16x32_bf16 v[44:47], v[128:131], v[196:199], v[44:47]
	v_mfma_f32_16x16x32_bf16 v[40:43], v[136:139], v[196:199], v[40:43]
	v_mfma_f32_16x16x32_bf16 v[28:31], v[128:131], v[204:207], v[28:31]
	v_mfma_f32_16x16x32_bf16 v[24:27], v[136:139], v[204:207], v[24:27]
	v_mfma_f32_16x16x32_bf16 v[12:15], v[128:131], v[212:215], v[12:15]
	v_mfma_f32_16x16x32_bf16 v[8:11], v[136:139], v[212:215], v[8:11]
	v_mfma_f32_16x16x32_bf16 v[60:63], v[132:135], v[192:195], v[60:63]
	v_mfma_f32_16x16x32_bf16 v[56:59], v[140:143], v[192:195], v[56:59]
	v_mfma_f32_16x16x32_bf16 v[44:47], v[132:135], v[200:203], v[44:47]
	v_mfma_f32_16x16x32_bf16 v[40:43], v[140:143], v[200:203], v[40:43]
	v_mfma_f32_16x16x32_bf16 v[28:31], v[132:135], v[208:211], v[28:31]
	v_mfma_f32_16x16x32_bf16 v[24:27], v[140:143], v[208:211], v[24:27]
	v_mfma_f32_16x16x32_bf16 v[12:15], v[132:135], v[216:219], v[12:15]
	v_mfma_f32_16x16x32_bf16 v[8:11], v[140:143], v[216:219], v[8:11]
	v_mfma_f32_16x16x32_bf16 v[52:55], v[160:163], v[188:191], v[52:55]
	v_mfma_f32_16x16x32_bf16 v[48:51], v[180:183], v[188:191], v[48:51]
	v_mfma_f32_16x16x32_bf16 v[36:39], v[160:163], v[196:199], v[36:39]
	v_mfma_f32_16x16x32_bf16 v[32:35], v[180:183], v[196:199], v[32:35]
	v_mfma_f32_16x16x32_bf16 v[20:23], v[160:163], v[204:207], v[20:23]
	v_mfma_f32_16x16x32_bf16 v[16:19], v[180:183], v[204:207], v[16:19]
	v_mfma_f32_16x16x32_bf16 v[4:7], v[160:163], v[212:215], v[4:7]
	v_mfma_f32_16x16x32_bf16 v[0:3], v[180:183], v[212:215], v[0:3]
	v_mfma_f32_16x16x32_bf16 v[52:55], v[164:167], v[192:195], v[52:55]
	v_mfma_f32_16x16x32_bf16 v[48:51], v[184:187], v[192:195], v[48:51]
	v_mfma_f32_16x16x32_bf16 v[36:39], v[164:167], v[200:203], v[36:39]
	v_mfma_f32_16x16x32_bf16 v[32:35], v[184:187], v[200:203], v[32:35]
	v_mfma_f32_16x16x32_bf16 v[20:23], v[164:167], v[208:211], v[20:23]
	v_mfma_f32_16x16x32_bf16 v[16:19], v[184:187], v[208:211], v[16:19]
	v_mfma_f32_16x16x32_bf16 v[4:7], v[164:167], v[216:219], v[4:7]
	v_mfma_f32_16x16x32_bf16 v[0:3], v[184:187], v[216:219], v[0:3]
	s_barrier
	s_add_i32 s61, 0, 0x18000
	s_add_i32 s62, 0, 0x1c000
	v_add_u32_e32 v140, s61, v169
	v_add_u32_e32 v168, s62, v169
	ds_read_b128 v[128:131], v140
	ds_read_b128 v[132:135], v140 offset:1024
	ds_read_b128 v[136:139], v140 offset:2048
	ds_read_b128 v[140:143], v140 offset:3072
	ds_read_b128 v[160:163], v168
	ds_read_b128 v[164:167], v168 offset:1024
	ds_read_b128 v[180:183], v168 offset:2048
	ds_read_b128 v[184:187], v168 offset:3072
	s_add_u32 s30, s30, 0x80000
	s_addc_u32 s31, s31, 0
	s_mov_b32 m0, s41
	v_lshl_add_u64 v[228:229], s[30:31], 0, v[150:151]
	ds_read_b128 v[188:191], v175 offset:32768
	ds_read_b128 v[192:195], v175 offset:33792
	ds_read_b128 v[196:199], v175 offset:34816
	ds_read_b128 v[200:203], v175 offset:35840
	ds_read_b128 v[204:207], v175 offset:36864
	ds_read_b128 v[208:211], v175 offset:37888
	ds_read_b128 v[212:215], v175 offset:38912
	ds_read_b128 v[216:219], v175 offset:39936
	global_load_lds_dwordx4 v[228:229], off
	v_lshl_add_u64 v[228:229], s[30:31], 0, v[146:147]
	s_mov_b32 m0, s42
	s_nop 0
	global_load_lds_dwordx4 v[228:229], off
	s_waitcnt vmcnt(8)
	s_waitcnt lgkmcnt(0)
	s_barrier
	s_waitcnt lgkmcnt(0)
	v_mfma_f32_16x16x32_bf16 v[124:127], v[128:131], v[188:191], v[124:127]
	v_mfma_f32_16x16x32_bf16 v[120:123], v[136:139], v[188:191], v[120:123]
	v_mfma_f32_16x16x32_bf16 v[108:111], v[128:131], v[196:199], v[108:111]
	v_mfma_f32_16x16x32_bf16 v[104:107], v[136:139], v[196:199], v[104:107]
	v_mfma_f32_16x16x32_bf16 v[92:95], v[128:131], v[204:207], v[92:95]
	v_mfma_f32_16x16x32_bf16 v[88:91], v[136:139], v[204:207], v[88:91]
	v_mfma_f32_16x16x32_bf16 v[76:79], v[128:131], v[212:215], v[76:79]
	v_mfma_f32_16x16x32_bf16 v[72:75], v[136:139], v[212:215], v[72:75]
	v_mfma_f32_16x16x32_bf16 v[124:127], v[132:135], v[192:195], v[124:127]
	v_mfma_f32_16x16x32_bf16 v[120:123], v[140:143], v[192:195], v[120:123]
	v_mfma_f32_16x16x32_bf16 v[108:111], v[132:135], v[200:203], v[108:111]
	v_mfma_f32_16x16x32_bf16 v[104:107], v[140:143], v[200:203], v[104:107]
	v_mfma_f32_16x16x32_bf16 v[92:95], v[132:135], v[208:211], v[92:95]
	v_mfma_f32_16x16x32_bf16 v[88:91], v[140:143], v[208:211], v[88:91]
	v_mfma_f32_16x16x32_bf16 v[76:79], v[132:135], v[216:219], v[76:79]
	v_mfma_f32_16x16x32_bf16 v[72:75], v[140:143], v[216:219], v[72:75]
	v_mfma_f32_16x16x32_bf16 v[116:119], v[160:163], v[188:191], v[116:119]
	v_mfma_f32_16x16x32_bf16 v[112:115], v[180:183], v[188:191], v[112:115]
	v_mfma_f32_16x16x32_bf16 v[100:103], v[160:163], v[196:199], v[100:103]
	v_mfma_f32_16x16x32_bf16 v[96:99], v[180:183], v[196:199], v[96:99]
	v_mfma_f32_16x16x32_bf16 v[84:87], v[160:163], v[204:207], v[84:87]
	v_mfma_f32_16x16x32_bf16 v[80:83], v[180:183], v[204:207], v[80:83]
	v_mfma_f32_16x16x32_bf16 v[68:71], v[160:163], v[212:215], v[68:71]
	v_mfma_f32_16x16x32_bf16 v[64:67], v[180:183], v[212:215], v[64:67]
	v_mfma_f32_16x16x32_bf16 v[116:119], v[164:167], v[192:195], v[116:119]
	v_mfma_f32_16x16x32_bf16 v[112:115], v[184:187], v[192:195], v[112:115]
	v_mfma_f32_16x16x32_bf16 v[100:103], v[164:167], v[200:203], v[100:103]
	v_mfma_f32_16x16x32_bf16 v[96:99], v[184:187], v[200:203], v[96:99]
	v_mfma_f32_16x16x32_bf16 v[84:87], v[164:167], v[208:211], v[84:87]
	v_mfma_f32_16x16x32_bf16 v[80:83], v[184:187], v[208:211], v[80:83]
	v_mfma_f32_16x16x32_bf16 v[68:71], v[164:167], v[216:219], v[68:71]
	v_mfma_f32_16x16x32_bf16 v[64:67], v[184:187], v[216:219], v[64:67]
	s_barrier
; #define PG8_STAGE(bufoff, gbase, voff) do { _Pragma("unroll") for (int _i = 0; _i < 2; ++_i) \
;         __builtin_amdgcn_global_load_lds((const unsigned*)((const char*)(gbase) + (voff)[_i]), (PG8_LAS unsigned*)(lds + (bufoff) + ldsw + _i * 8192), 16, 0, 0); } while (0)
; #define PG8_LDA(dst, b, h) do { _Pragma("unroll") for (int m = 0; m < 4; ++m) _Pragma("unroll") for (int k = 0; k < 2; ++k) dst[m][k] = *(const PG8_LAS bf16x8*)(lds + PG8_SA(b, h) + aoff + m * 2048 + k * 1024); } while (0)
; #define PG8_MMA(ai, bj, At, Bt) do { __builtin_amdgcn_s_setprio(1); _Pragma("unroll") for (int m = 0; m < 4; ++m) _Pragma("unroll") for (int n = 0; n < 2; ++n) _Pragma("unroll") for (int k = 0; k < 2; ++k) \
;         acc[ai][bj][m][n] = __builtin_amdgcn_mfma_f32_16x16x32_bf16(Bt[n][k], At[m][k], acc[ai][bj][m][n], 0, 0, 0); __builtin_amdgcn_s_setprio(0); } while (0)
; #define PG8_WAIT_V(n) asm volatile("s_waitcnt vmcnt(" #n ")" ::: "memory")
; #define PG8_WAIT_L(n) asm volatile("s_waitcnt lgkmcnt(" #n ")" ::: "memory")
; #define PG8_BAR __builtin_amdgcn_s_barrier()
; #define PG8_SCHED __builtin_amdgcn_sched_barrier(0)
; template <class Epi, class Sched, bool ALIGN_EPI = false, bool SP2 = false>
; __device__ __forceinline__ void gemm_phase(PG8_LAS unsigned char* lds, const Gemm g, const Sched& S, const Epi& E, const int wid) {
;     ...
;         for (int t = 0; t < nt; t += 2) {
;     ...
;             PG8_LDA(At, 1, 1); PG8_STAGE(PG8_SB(1, 0), b3, voffB); PG8_STAGE(PG8_SB(1, 1), b3 + hsB, voffB); PG8_STAGE(PG8_SA(1, 0), a3, voffA);
;             PG8_WAIT_V(8); PG8_WAIT_L(0); PG8_BAR; PG8_MMA(1, 0, At, B0); PG8_MMA(1, 1, At, B1); PG8_BAR; PG8_SCHED;
;     ...
;         if constexpr (ALIGN_EPI) { if (wr == 0) PG8_BAR; }
	s_add_i32 s30, s61, s36
	v_lshl_add_u64 v[220:221], v[220:221], 0, s[18:19]
	s_mov_b32 m0, s30
	ds_read_b128 v[188:191], v175 offset:49152
	ds_read_b128 v[192:195], v175 offset:50176
	ds_read_b128 v[196:199], v175 offset:51200
	ds_read_b128 v[200:203], v175 offset:52224
	ds_read_b128 v[204:207], v175 offset:53248
	ds_read_b128 v[208:211], v175 offset:54272
	ds_read_b128 v[212:215], v175 offset:55296
	ds_read_b128 v[216:219], v175 offset:56320
	global_load_lds_dwordx4 v[220:221], off
	s_add_i32 m0, s30, 0x2000
	s_add_u32 s8, s8, 0x80080
	v_lshl_add_u64 v[220:221], v[222:223], 0, s[18:19]
	s_addc_u32 s9, s9, 0
	s_add_i32 s30, s62, s36
	global_load_lds_dwordx4 v[220:221], off
	v_lshl_add_u64 v[220:221], s[8:9], 0, v[148:149]
	s_mov_b32 m0, s30
	s_nop 0
	global_load_lds_dwordx4 v[220:221], off
	v_lshl_add_u64 v[220:221], s[8:9], 0, v[144:145]
	s_add_i32 m0, s30, 0x2000
	s_nop 0
	global_load_lds_dwordx4 v[220:221], off
	v_lshl_add_u64 v[220:221], v[224:225], 0, s[18:19]
	s_mov_b32 m0, s45
	s_nop 0
	global_load_lds_dwordx4 v[220:221], off
	v_lshl_add_u64 v[220:221], v[226:227], 0, s[18:19]
	s_mov_b32 m0, s46
	s_nop 0
	global_load_lds_dwordx4 v[220:221], off
	s_waitcnt vmcnt(8)
	s_waitcnt lgkmcnt(0)
	s_barrier
	s_waitcnt lgkmcnt(0)
	v_mfma_f32_16x16x32_bf16 v[60:63], v[128:131], v[188:191], v[60:63]
	v_mfma_f32_16x16x32_bf16 v[56:59], v[136:139], v[188:191], v[56:59]
	v_mfma_f32_16x16x32_bf16 v[44:47], v[128:131], v[196:199], v[44:47]
	v_mfma_f32_16x16x32_bf16 v[40:43], v[136:139], v[196:199], v[40:43]
	v_mfma_f32_16x16x32_bf16 v[28:31], v[128:131], v[204:207], v[28:31]
	v_mfma_f32_16x16x32_bf16 v[24:27], v[136:139], v[204:207], v[24:27]
	v_mfma_f32_16x16x32_bf16 v[12:15], v[128:131], v[212:215], v[12:15]
	v_mfma_f32_16x16x32_bf16 v[8:11], v[136:139], v[212:215], v[8:11]
	v_mfma_f32_16x16x32_bf16 v[60:63], v[132:135], v[192:195], v[60:63]
	v_mfma_f32_16x16x32_bf16 v[56:59], v[140:143], v[192:195], v[56:59]
	v_mfma_f32_16x16x32_bf16 v[44:47], v[132:135], v[200:203], v[44:47]
	v_mfma_f32_16x16x32_bf16 v[40:43], v[140:143], v[200:203], v[40:43]
	v_mfma_f32_16x16x32_bf16 v[28:31], v[132:135], v[208:211], v[28:31]
	v_mfma_f32_16x16x32_bf16 v[24:27], v[140:143], v[208:211], v[24:27]
	v_mfma_f32_16x16x32_bf16 v[12:15], v[132:135], v[216:219], v[12:15]
	v_mfma_f32_16x16x32_bf16 v[8:11], v[140:143], v[216:219], v[8:11]
	v_mfma_f32_16x16x32_bf16 v[52:55], v[160:163], v[188:191], v[52:55]
	v_mfma_f32_16x16x32_bf16 v[48:51], v[180:183], v[188:191], v[48:51]
	v_mfma_f32_16x16x32_bf16 v[36:39], v[160:163], v[196:199], v[36:39]
	v_mfma_f32_16x16x32_bf16 v[32:35], v[180:183], v[196:199], v[32:35]
	v_mfma_f32_16x16x32_bf16 v[20:23], v[160:163], v[204:207], v[20:23]
	v_mfma_f32_16x16x32_bf16 v[16:19], v[180:183], v[204:207], v[16:19]
	v_mfma_f32_16x16x32_bf16 v[4:7], v[160:163], v[212:215], v[4:7]
	v_mfma_f32_16x16x32_bf16 v[0:3], v[180:183], v[212:215], v[0:3]
	v_mfma_f32_16x16x32_bf16 v[52:55], v[164:167], v[192:195], v[52:55]
	v_mfma_f32_16x16x32_bf16 v[48:51], v[184:187], v[192:195], v[48:51]
	v_mfma_f32_16x16x32_bf16 v[36:39], v[164:167], v[200:203], v[36:39]
	v_mfma_f32_16x16x32_bf16 v[32:35], v[184:187], v[200:203], v[32:35]
	v_mfma_f32_16x16x32_bf16 v[20:23], v[164:167], v[208:211], v[20:23]
	v_mfma_f32_16x16x32_bf16 v[16:19], v[184:187], v[208:211], v[16:19]
	v_mfma_f32_16x16x32_bf16 v[4:7], v[164:167], v[216:219], v[4:7]
	v_mfma_f32_16x16x32_bf16 v[0:3], v[184:187], v[216:219], v[0:3]
	s_barrier
	s_add_i32 s60, s60, 2
	s_add_u32 s58, s58, 0x100
	s_addc_u32 s59, s59, 0
	s_add_u32 s6, s6, 0x100
	s_addc_u32 s7, s7, 0
	s_cmp_gt_u32 s60, 29
	s_cbranch_scc0 .LBB0_1385
	s_and_b64 vcc, exec, s[20:21]
	s_cbranch_vccz .LBB0_1388
	s_barrier

; #define PG8_STAGE(bufoff, gbase, voff) do { _Pragma("unroll") for (int _i = 0; _i < 2; ++_i) \
;         __builtin_amdgcn_global_load_lds((const unsigned*)((const char*)(gbase) + (voff)[_i]), (PG8_LAS unsigned*)(lds + (bufoff) + ldsw + _i * 8192), 16, 0, 0); } while (0)
; #define PG8_LDA(dst, b, h) do { _Pragma("unroll") for (int m = 0; m < 4; ++m) _Pragma("unroll") for (int k = 0; k < 2; ++k) dst[m][k] = *(const PG8_LAS bf16x8*)(lds + PG8_SA(b, h) + aoff + m * 2048 + k * 1024); } while (0)
; #define PG8_LDB(dst, b, h) do { _Pragma("unroll") for (int n = 0; n < 2; ++n) _Pragma("unroll") for (int k = 0; k < 2; ++k) dst[n][k] = *(const PG8_LAS bf16x8*)(lds + PG8_SB(b, h) + boff + n * 2048 + k * 1024); } while (0)
; #define PG8_MMA(ai, bj, At, Bt) do { __builtin_amdgcn_s_setprio(1); _Pragma("unroll") for (int m = 0; m < 4; ++m) _Pragma("unroll") for (int n = 0; n < 2; ++n) _Pragma("unroll") for (int k = 0; k < 2; ++k) \
;         acc[ai][bj][m][n] = __builtin_amdgcn_mfma_f32_16x16x32_bf16(Bt[n][k], At[m][k], acc[ai][bj][m][n], 0, 0, 0); __builtin_amdgcn_s_setprio(0); } while (0)
; #define PG8_WAIT_V(n) asm volatile("s_waitcnt vmcnt(" #n ")" ::: "memory")
; #define PG8_WAIT_L(n) asm volatile("s_waitcnt lgkmcnt(" #n ")" ::: "memory")
; #define PG8_BAR __builtin_amdgcn_s_barrier()
; template <class Epi, class Sched, bool ALIGN_EPI = false, bool SP2 = false>
; __device__ __forceinline__ void gemm_phase(PG8_LAS unsigned char* lds, const Gemm g, const Sched& S, const Epi& E, const int wid) {
;     ...
;             const bool last = (t == nt - 2);
;             const char* a1 = cA + (size_t)(t + 1) * kstep;
;             const char* a2 = last ? nA : cA + (size_t)(t + 2) * kstep; const char* b2 = last ? nB : cB + (size_t)(t + 2) * kstep;
;             const char* a3 = a2 + kstep; const char* b3 = b2 + kstep;
;             if constexpr (SP2) {
;             PG8_LDB(B0, 0, 0); PG8_LDB(B1, 0, 1); PG8_SCHED; PG8_LDA(At, 0, 0); PG8_STAGE(PG8_SA(1, 1), a1 + hsA, voffA);
;             PG8_WAIT_V(8); PG8_WAIT_L(0); PG8_BAR; PG8_MMA(0, 0, At, B0); PG8_MMA(0, 1, At, B1); PG8_BAR; PG8_SCHED;
;             PG8_LDA(At, 0, 1); PG8_STAGE(PG8_SB(0, 0), b2, voffB); PG8_STAGE(PG8_SB(0, 1), b2 + hsB, voffB); PG8_STAGE(PG8_SA(0, 0), a2, voffA);
;             PG8_WAIT_V(8); PG8_WAIT_L(0); PG8_BAR; PG8_MMA(1, 0, At, B0); PG8_MMA(1, 1, At, B1); PG8_BAR; PG8_SCHED;
.LBB0_1462:
	ds_read_b128 v[128:131], v163
	ds_read_b128 v[132:135], v163 offset:1024
	ds_read_b128 v[136:139], v163 offset:2048
	ds_read_b128 v[140:143], v163 offset:3072
	ds_read_b128 v[156:159], v164
	ds_read_b128 v[166:169], v164 offset:1024
	ds_read_b128 v[170:173], v164 offset:2048
	ds_read_b128 v[174:177], v164 offset:3072
	s_add_u32 s28, s26, 0x100
	s_addc_u32 s29, s27, 0
	s_cmpk_eq_i32 s58, 0x54
	s_cselect_b32 s35, s5, s29
	s_cselect_b32 s34, s4, s28
	s_cselect_b32 s31, s25, s57
	s_cselect_b32 s30, s24, s56
	v_lshl_add_u64 v[160:161], s[26:27], 0, v[150:151]
	s_add_i32 m0, s40, 0xc000
	ds_read_b128 v[178:181], v165
	ds_read_b128 v[182:185], v165 offset:1024
	ds_read_b128 v[186:189], v165 offset:2048
	ds_read_b128 v[190:193], v165 offset:3072
	ds_read_b128 v[194:197], v165 offset:4096
	ds_read_b128 v[198:201], v165 offset:5120
	ds_read_b128 v[202:205], v165 offset:6144
	ds_read_b128 v[206:209], v165 offset:7168
	global_load_lds_dwordx4 v[160:161], off
	v_lshl_add_u64 v[160:161], s[26:27], 0, v[148:149]
	s_add_i32 m0, s40, 0xe000
	s_nop 0
	global_load_lds_dwordx4 v[160:161], off
	s_waitcnt vmcnt(8)
	s_waitcnt lgkmcnt(0)
	s_barrier
	s_waitcnt lgkmcnt(0)
	v_mfma_f32_16x16x32_bf16 v[124:127], v[128:131], v[178:181], v[124:127]
	v_mfma_f32_16x16x32_bf16 v[120:123], v[136:139], v[178:181], v[120:123]
	v_mfma_f32_16x16x32_bf16 v[116:119], v[128:131], v[186:189], v[116:119]
	v_mfma_f32_16x16x32_bf16 v[112:115], v[136:139], v[186:189], v[112:115]
	v_mfma_f32_16x16x32_bf16 v[92:95], v[128:131], v[194:197], v[92:95]
	v_mfma_f32_16x16x32_bf16 v[88:91], v[136:139], v[194:197], v[88:91]
	v_mfma_f32_16x16x32_bf16 v[84:87], v[128:131], v[202:205], v[84:87]
	v_mfma_f32_16x16x32_bf16 v[80:83], v[136:139], v[202:205], v[80:83]
	v_mfma_f32_16x16x32_bf16 v[124:127], v[132:135], v[182:185], v[124:127]
	v_mfma_f32_16x16x32_bf16 v[120:123], v[140:143], v[182:185], v[120:123]
	v_mfma_f32_16x16x32_bf16 v[116:119], v[132:135], v[190:193], v[116:119]
	v_mfma_f32_16x16x32_bf16 v[112:115], v[140:143], v[190:193], v[112:115]
	v_mfma_f32_16x16x32_bf16 v[92:95], v[132:135], v[198:201], v[92:95]
	v_mfma_f32_16x16x32_bf16 v[88:91], v[140:143], v[198:201], v[88:91]
	v_mfma_f32_16x16x32_bf16 v[84:87], v[132:135], v[206:209], v[84:87]
	v_mfma_f32_16x16x32_bf16 v[80:83], v[140:143], v[206:209], v[80:83]
	v_mfma_f32_16x16x32_bf16 v[108:111], v[156:159], v[178:181], v[108:111]
	v_mfma_f32_16x16x32_bf16 v[104:107], v[170:173], v[178:181], v[104:107]
	v_mfma_f32_16x16x32_bf16 v[100:103], v[156:159], v[186:189], v[100:103]
	v_mfma_f32_16x16x32_bf16 v[96:99], v[170:173], v[186:189], v[96:99]
	v_mfma_f32_16x16x32_bf16 v[76:79], v[156:159], v[194:197], v[76:79]
	v_mfma_f32_16x16x32_bf16 v[72:75], v[170:173], v[194:197], v[72:75]
	v_mfma_f32_16x16x32_bf16 v[68:71], v[156:159], v[202:205], v[68:71]
	v_mfma_f32_16x16x32_bf16 v[64:67], v[170:173], v[202:205], v[64:67]
	v_mfma_f32_16x16x32_bf16 v[108:111], v[166:169], v[182:185], v[108:111]
	v_mfma_f32_16x16x32_bf16 v[104:107], v[174:177], v[182:185], v[104:107]
	v_mfma_f32_16x16x32_bf16 v[100:103], v[166:169], v[190:193], v[100:103]
	v_mfma_f32_16x16x32_bf16 v[96:99], v[174:177], v[190:193], v[96:99]
	v_mfma_f32_16x16x32_bf16 v[76:79], v[166:169], v[198:201], v[76:79]
	v_mfma_f32_16x16x32_bf16 v[72:75], v[174:177], v[198:201], v[72:75]
	v_mfma_f32_16x16x32_bf16 v[68:71], v[166:169], v[206:209], v[68:71]
	v_mfma_f32_16x16x32_bf16 v[64:67], v[174:177], v[206:209], v[64:67]
	s_barrier
	s_add_i32 s26, s50, s39
	v_lshl_add_u64 v[160:161], s[30:31], 0, v[144:145]
	s_mov_b32 m0, s26
	ds_read_b128 v[178:181], v165 offset:16384
	ds_read_b128 v[182:185], v165 offset:17408
	ds_read_b128 v[186:189], v165 offset:18432
	ds_read_b128 v[190:193], v165 offset:19456
	ds_read_b128 v[194:197], v165 offset:20480
	ds_read_b128 v[198:201], v165 offset:21504
	ds_read_b128 v[202:205], v165 offset:22528
	ds_read_b128 v[206:209], v165 offset:23552
	global_load_lds_dwordx4 v[160:161], off
	s_add_i32 m0, s26, 0x2000
	s_add_u32 s26, s30, 0x160000
	v_lshl_add_u64 v[210:211], s[30:31], 0, v[146:147]
	s_addc_u32 s27, s31, 0
	s_add_i32 s59, s51, s39
	global_load_lds_dwordx4 v[210:211], off
	v_lshl_add_u64 v[212:213], s[26:27], 0, v[144:145]
	s_mov_b32 m0, s59
	v_lshl_add_u64 v[214:215], s[34:35], 0, v[146:147]
	global_load_lds_dwordx4 v[212:213], off
	v_lshl_add_u64 v[212:213], s[26:27], 0, v[146:147]
	s_add_i32 m0, s59, 0x2000
	s_nop 0
	global_load_lds_dwordx4 v[212:213], off
	v_lshl_add_u64 v[212:213], s[34:35], 0, v[144:145]
	s_mov_b32 m0, s40
	s_nop 0
	global_load_lds_dwordx4 v[212:213], off
	s_mov_b32 m0, s41
	s_nop 0
	global_load_lds_dwordx4 v[214:215], off
	s_waitcnt vmcnt(8)
	s_waitcnt lgkmcnt(0)
	s_barrier
; #define PG8_STAGE(bufoff, gbase, voff) do { _Pragma("unroll") for (int _i = 0; _i < 2; ++_i) \
;         __builtin_amdgcn_global_load_lds((const unsigned*)((const char*)(gbase) + (voff)[_i]), (PG8_LAS unsigned*)(lds + (bufoff) + ldsw + _i * 8192), 16, 0, 0); } while (0)
; #define PG8_LDA(dst, b, h) do { _Pragma("unroll") for (int m = 0; m < 4; ++m) _Pragma("unroll") for (int k = 0; k < 2; ++k) dst[m][k] = *(const PG8_LAS bf16x8*)(lds + PG8_SA(b, h) + aoff + m * 2048 + k * 1024); } while (0)
; #define PG8_LDB(dst, b, h) do { _Pragma("unroll") for (int n = 0; n < 2; ++n) _Pragma("unroll") for (int k = 0; k < 2; ++k) dst[n][k] = *(const PG8_LAS bf16x8*)(lds + PG8_SB(b, h) + boff + n * 2048 + k * 1024); } while (0)
; #define PG8_MMA(ai, bj, At, Bt) do { __builtin_amdgcn_s_setprio(1); _Pragma("unroll") for (int m = 0; m < 4; ++m) _Pragma("unroll") for (int n = 0; n < 2; ++n) _Pragma("unroll") for (int k = 0; k < 2; ++k) \
;         acc[ai][bj][m][n] = __builtin_amdgcn_mfma_f32_16x16x32_bf16(Bt[n][k], At[m][k], acc[ai][bj][m][n], 0, 0, 0); __builtin_amdgcn_s_setprio(0); } while (0)
; #define PG8_WAIT_V(n) asm volatile("s_waitcnt vmcnt(" #n ")" ::: "memory")
; #define PG8_WAIT_L(n) asm volatile("s_waitcnt lgkmcnt(" #n ")" ::: "memory")
; #define PG8_BAR __builtin_amdgcn_s_barrier()
; #define PG8_SCHED __builtin_amdgcn_sched_barrier(0)
; template <class Epi, class Sched, bool ALIGN_EPI = false, bool SP2 = false>
; __device__ __forceinline__ void gemm_phase(PG8_LAS unsigned char* lds, const Gemm g, const Sched& S, const Epi& E, const int wid) {
;     ...
;             PG8_WAIT_V(8); PG8_WAIT_L(0); PG8_BAR; PG8_MMA(1, 0, At, B0); PG8_MMA(1, 1, At, B1); PG8_BAR; PG8_SCHED;
;             PG8_LDB(B0, 1, 0); PG8_LDB(B1, 1, 1); PG8_SCHED; PG8_LDA(At, 1, 0); PG8_STAGE(PG8_SA(0, 1), a2 + hsA, voffA);
;             PG8_WAIT_V(8); PG8_WAIT_L(0); PG8_BAR; PG8_MMA(0, 0, At, B0); PG8_MMA(0, 1, At, B1); PG8_BAR; PG8_SCHED;
	s_waitcnt lgkmcnt(0)
	v_mfma_f32_16x16x32_bf16 v[60:63], v[128:131], v[178:181], v[60:63]
	v_mfma_f32_16x16x32_bf16 v[56:59], v[136:139], v[178:181], v[56:59]
	v_mfma_f32_16x16x32_bf16 v[52:55], v[128:131], v[186:189], v[52:55]
	v_mfma_f32_16x16x32_bf16 v[48:51], v[136:139], v[186:189], v[48:51]
	v_mfma_f32_16x16x32_bf16 v[28:31], v[128:131], v[194:197], v[28:31]
	v_mfma_f32_16x16x32_bf16 v[24:27], v[136:139], v[194:197], v[24:27]
	v_mfma_f32_16x16x32_bf16 v[20:23], v[128:131], v[202:205], v[20:23]
	v_mfma_f32_16x16x32_bf16 v[16:19], v[136:139], v[202:205], v[16:19]
	v_mfma_f32_16x16x32_bf16 v[60:63], v[132:135], v[182:185], v[60:63]
	v_mfma_f32_16x16x32_bf16 v[56:59], v[140:143], v[182:185], v[56:59]
	v_mfma_f32_16x16x32_bf16 v[52:55], v[132:135], v[190:193], v[52:55]
	v_mfma_f32_16x16x32_bf16 v[48:51], v[140:143], v[190:193], v[48:51]
	v_mfma_f32_16x16x32_bf16 v[28:31], v[132:135], v[198:201], v[28:31]
	v_mfma_f32_16x16x32_bf16 v[24:27], v[140:143], v[198:201], v[24:27]
	v_mfma_f32_16x16x32_bf16 v[20:23], v[132:135], v[206:209], v[20:23]
	v_mfma_f32_16x16x32_bf16 v[16:19], v[140:143], v[206:209], v[16:19]
	v_mfma_f32_16x16x32_bf16 v[44:47], v[156:159], v[178:181], v[44:47]
	v_mfma_f32_16x16x32_bf16 v[40:43], v[170:173], v[178:181], v[40:43]
	v_mfma_f32_16x16x32_bf16 v[36:39], v[156:159], v[186:189], v[36:39]
	v_mfma_f32_16x16x32_bf16 v[32:35], v[170:173], v[186:189], v[32:35]
	v_mfma_f32_16x16x32_bf16 v[12:15], v[156:159], v[194:197], v[12:15]
	v_mfma_f32_16x16x32_bf16 v[8:11], v[170:173], v[194:197], v[8:11]
	v_mfma_f32_16x16x32_bf16 v[4:7], v[156:159], v[202:205], v[4:7]
	v_mfma_f32_16x16x32_bf16 v[0:3], v[170:173], v[202:205], v[0:3]
	v_mfma_f32_16x16x32_bf16 v[44:47], v[166:169], v[182:185], v[44:47]
	v_mfma_f32_16x16x32_bf16 v[40:43], v[174:177], v[182:185], v[40:43]
	v_mfma_f32_16x16x32_bf16 v[36:39], v[166:169], v[190:193], v[36:39]
	v_mfma_f32_16x16x32_bf16 v[32:35], v[174:177], v[190:193], v[32:35]
	v_mfma_f32_16x16x32_bf16 v[12:15], v[166:169], v[198:201], v[12:15]
	v_mfma_f32_16x16x32_bf16 v[8:11], v[174:177], v[198:201], v[8:11]
	v_mfma_f32_16x16x32_bf16 v[4:7], v[166:169], v[206:209], v[4:7]
	v_mfma_f32_16x16x32_bf16 v[0:3], v[174:177], v[206:209], v[0:3]
	s_barrier
	s_add_i32 s59, 0, 0x18000
	s_add_i32 s60, 0, 0x1c000
	v_add_u32_e32 v140, s59, v162
	v_add_u32_e32 v174, s60, v162
	ds_read_b128 v[128:131], v140
	ds_read_b128 v[132:135], v140 offset:1024
	ds_read_b128 v[136:139], v140 offset:2048
	ds_read_b128 v[140:143], v140 offset:3072
	ds_read_b128 v[156:159], v174
	ds_read_b128 v[166:169], v174 offset:1024
	ds_read_b128 v[170:173], v174 offset:2048
	ds_read_b128 v[174:177], v174 offset:3072
	s_add_u32 s26, s34, 0x160000
	s_addc_u32 s27, s35, 0
	s_mov_b32 m0, s42
	v_lshl_add_u64 v[216:217], s[26:27], 0, v[144:145]
	ds_read_b128 v[178:181], v165 offset:32768
	ds_read_b128 v[182:185], v165 offset:33792
	ds_read_b128 v[186:189], v165 offset:34816
	ds_read_b128 v[190:193], v165 offset:35840
	ds_read_b128 v[194:197], v165 offset:36864
	ds_read_b128 v[198:201], v165 offset:37888
	ds_read_b128 v[202:205], v165 offset:38912
	ds_read_b128 v[206:209], v165 offset:39936
	global_load_lds_dwordx4 v[216:217], off
	v_lshl_add_u64 v[216:217], s[26:27], 0, v[146:147]
	s_mov_b32 m0, s43
	s_nop 0
	global_load_lds_dwordx4 v[216:217], off
	s_waitcnt vmcnt(8)
	s_waitcnt lgkmcnt(0)
	s_barrier
	s_waitcnt lgkmcnt(0)
	v_mfma_f32_16x16x32_bf16 v[124:127], v[128:131], v[178:181], v[124:127]
	v_mfma_f32_16x16x32_bf16 v[120:123], v[136:139], v[178:181], v[120:123]
	v_mfma_f32_16x16x32_bf16 v[116:119], v[128:131], v[186:189], v[116:119]
	v_mfma_f32_16x16x32_bf16 v[112:115], v[136:139], v[186:189], v[112:115]
	v_mfma_f32_16x16x32_bf16 v[92:95], v[128:131], v[194:197], v[92:95]
	v_mfma_f32_16x16x32_bf16 v[88:91], v[136:139], v[194:197], v[88:91]
	v_mfma_f32_16x16x32_bf16 v[84:87], v[128:131], v[202:205], v[84:87]
	v_mfma_f32_16x16x32_bf16 v[80:83], v[136:139], v[202:205], v[80:83]
	v_mfma_f32_16x16x32_bf16 v[124:127], v[132:135], v[182:185], v[124:127]
	v_mfma_f32_16x16x32_bf16 v[120:123], v[140:143], v[182:185], v[120:123]
	v_mfma_f32_16x16x32_bf16 v[116:119], v[132:135], v[190:193], v[116:119]
	v_mfma_f32_16x16x32_bf16 v[112:115], v[140:143], v[190:193], v[112:115]
	v_mfma_f32_16x16x32_bf16 v[92:95], v[132:135], v[198:201], v[92:95]
	v_mfma_f32_16x16x32_bf16 v[88:91], v[140:143], v[198:201], v[88:91]
	v_mfma_f32_16x16x32_bf16 v[84:87], v[132:135], v[206:209], v[84:87]
	v_mfma_f32_16x16x32_bf16 v[80:83], v[140:143], v[206:209], v[80:83]
	v_mfma_f32_16x16x32_bf16 v[108:111], v[156:159], v[178:181], v[108:111]
	v_mfma_f32_16x16x32_bf16 v[104:107], v[170:173], v[178:181], v[104:107]
	v_mfma_f32_16x16x32_bf16 v[100:103], v[156:159], v[186:189], v[100:103]
	v_mfma_f32_16x16x32_bf16 v[96:99], v[170:173], v[186:189], v[96:99]
	v_mfma_f32_16x16x32_bf16 v[76:79], v[156:159], v[194:197], v[76:79]
	v_mfma_f32_16x16x32_bf16 v[72:75], v[170:173], v[194:197], v[72:75]
	v_mfma_f32_16x16x32_bf16 v[68:71], v[156:159], v[202:205], v[68:71]
	v_mfma_f32_16x16x32_bf16 v[64:67], v[170:173], v[202:205], v[64:67]
	v_mfma_f32_16x16x32_bf16 v[108:111], v[166:169], v[182:185], v[108:111]
	v_mfma_f32_16x16x32_bf16 v[104:107], v[174:177], v[182:185], v[104:107]
	v_mfma_f32_16x16x32_bf16 v[100:103], v[166:169], v[190:193], v[100:103]
	v_mfma_f32_16x16x32_bf16 v[96:99], v[174:177], v[190:193], v[96:99]
	v_mfma_f32_16x16x32_bf16 v[76:79], v[166:169], v[198:201], v[76:79]
	v_mfma_f32_16x16x32_bf16 v[72:75], v[174:177], v[198:201], v[72:75]
	v_mfma_f32_16x16x32_bf16 v[68:71], v[166:169], v[206:209], v[68:71]
	v_mfma_f32_16x16x32_bf16 v[64:67], v[174:177], v[206:209], v[64:67]
	s_barrier
; #define PG8_STAGE(bufoff, gbase, voff) do { _Pragma("unroll") for (int _i = 0; _i < 2; ++_i) \
;         __builtin_amdgcn_global_load_lds((const unsigned*)((const char*)(gbase) + (voff)[_i]), (PG8_LAS unsigned*)(lds + (bufoff) + ldsw + _i * 8192), 16, 0, 0); } while (0)
; #define PG8_LDA(dst, b, h) do { _Pragma("unroll") for (int m = 0; m < 4; ++m) _Pragma("unroll") for (int k = 0; k < 2; ++k) dst[m][k] = *(const PG8_LAS bf16x8*)(lds + PG8_SA(b, h) + aoff + m * 2048 + k * 1024); } while (0)
; #define PG8_MMA(ai, bj, At, Bt) do { __builtin_amdgcn_s_setprio(1); _Pragma("unroll") for (int m = 0; m < 4; ++m) _Pragma("unroll") for (int n = 0; n < 2; ++n) _Pragma("unroll") for (int k = 0; k < 2; ++k) \
;         acc[ai][bj][m][n] = __builtin_amdgcn_mfma_f32_16x16x32_bf16(Bt[n][k], At[m][k], acc[ai][bj][m][n], 0, 0, 0); __builtin_amdgcn_s_setprio(0); } while (0)
; #define PG8_WAIT_V(n) asm volatile("s_waitcnt vmcnt(" #n ")" ::: "memory")
; #define PG8_WAIT_L(n) asm volatile("s_waitcnt lgkmcnt(" #n ")" ::: "memory")
; #define PG8_BAR __builtin_amdgcn_s_barrier()
; #define PG8_SCHED __builtin_amdgcn_sched_barrier(0)
; template <class Epi, class Sched, bool ALIGN_EPI = false, bool SP2 = false>
; __device__ __forceinline__ void gemm_phase(PG8_LAS unsigned char* lds, const Gemm g, const Sched& S, const Epi& E, const int wid) {
;     ...
;         for (int t = 0; t < nt; t += 2) {
;     ...
;             PG8_LDA(At, 1, 1); PG8_STAGE(PG8_SB(1, 0), b3, voffB); PG8_STAGE(PG8_SB(1, 1), b3 + hsB, voffB); PG8_STAGE(PG8_SA(1, 0), a3, voffA);
;             PG8_WAIT_V(8); PG8_WAIT_L(0); PG8_BAR; PG8_MMA(1, 0, At, B0); PG8_MMA(1, 1, At, B1); PG8_BAR; PG8_SCHED;
;     ...
;         if constexpr (ALIGN_EPI) { if (wr == 0) PG8_BAR; }
	s_add_i32 s26, s59, s39
	v_lshl_add_u64 v[160:161], v[160:161], 0, s[14:15]
	s_mov_b32 m0, s26
	ds_read_b128 v[178:181], v165 offset:49152
	ds_read_b128 v[182:185], v165 offset:50176
	ds_read_b128 v[186:189], v165 offset:51200
	ds_read_b128 v[190:193], v165 offset:52224
	ds_read_b128 v[194:197], v165 offset:53248
	ds_read_b128 v[198:201], v165 offset:54272
	ds_read_b128 v[202:205], v165 offset:55296
	ds_read_b128 v[206:209], v165 offset:56320
	global_load_lds_dwordx4 v[160:161], off
	s_add_i32 m0, s26, 0x2000
	s_add_u32 s26, s30, 0x160080
	v_lshl_add_u64 v[160:161], v[210:211], 0, s[14:15]
	s_addc_u32 s27, s31, 0
	s_add_i32 s30, s60, s39
	global_load_lds_dwordx4 v[160:161], off
	v_lshl_add_u64 v[160:161], s[26:27], 0, v[144:145]
	s_mov_b32 m0, s30
	s_nop 0
	global_load_lds_dwordx4 v[160:161], off
	v_lshl_add_u64 v[160:161], s[26:27], 0, v[146:147]
	s_add_i32 m0, s30, 0x2000
	s_nop 0
	global_load_lds_dwordx4 v[160:161], off
	v_lshl_add_u64 v[160:161], v[212:213], 0, s[14:15]
	s_mov_b32 m0, s47
	s_nop 0
	global_load_lds_dwordx4 v[160:161], off
	v_lshl_add_u64 v[160:161], v[214:215], 0, s[14:15]
	s_mov_b32 m0, s48
	s_nop 0
	global_load_lds_dwordx4 v[160:161], off
	s_waitcnt vmcnt(8)
	s_waitcnt lgkmcnt(0)
	s_barrier
	s_waitcnt lgkmcnt(0)
	v_mfma_f32_16x16x32_bf16 v[60:63], v[128:131], v[178:181], v[60:63]
	v_mfma_f32_16x16x32_bf16 v[56:59], v[136:139], v[178:181], v[56:59]
	v_mfma_f32_16x16x32_bf16 v[52:55], v[128:131], v[186:189], v[52:55]
	v_mfma_f32_16x16x32_bf16 v[48:51], v[136:139], v[186:189], v[48:51]
	v_mfma_f32_16x16x32_bf16 v[28:31], v[128:131], v[194:197], v[28:31]
	v_mfma_f32_16x16x32_bf16 v[24:27], v[136:139], v[194:197], v[24:27]
	v_mfma_f32_16x16x32_bf16 v[20:23], v[128:131], v[202:205], v[20:23]
	v_mfma_f32_16x16x32_bf16 v[16:19], v[136:139], v[202:205], v[16:19]
	v_mfma_f32_16x16x32_bf16 v[60:63], v[132:135], v[182:185], v[60:63]
	v_mfma_f32_16x16x32_bf16 v[56:59], v[140:143], v[182:185], v[56:59]
	v_mfma_f32_16x16x32_bf16 v[52:55], v[132:135], v[190:193], v[52:55]
	v_mfma_f32_16x16x32_bf16 v[48:51], v[140:143], v[190:193], v[48:51]
	v_mfma_f32_16x16x32_bf16 v[28:31], v[132:135], v[198:201], v[28:31]
	v_mfma_f32_16x16x32_bf16 v[24:27], v[140:143], v[198:201], v[24:27]
	v_mfma_f32_16x16x32_bf16 v[20:23], v[132:135], v[206:209], v[20:23]
	v_mfma_f32_16x16x32_bf16 v[16:19], v[140:143], v[206:209], v[16:19]
	v_mfma_f32_16x16x32_bf16 v[44:47], v[156:159], v[178:181], v[44:47]
	v_mfma_f32_16x16x32_bf16 v[40:43], v[170:173], v[178:181], v[40:43]
	v_mfma_f32_16x16x32_bf16 v[36:39], v[156:159], v[186:189], v[36:39]
	v_mfma_f32_16x16x32_bf16 v[32:35], v[170:173], v[186:189], v[32:35]
	v_mfma_f32_16x16x32_bf16 v[12:15], v[156:159], v[194:197], v[12:15]
	v_mfma_f32_16x16x32_bf16 v[8:11], v[170:173], v[194:197], v[8:11]
	v_mfma_f32_16x16x32_bf16 v[4:7], v[156:159], v[202:205], v[4:7]
	v_mfma_f32_16x16x32_bf16 v[0:3], v[170:173], v[202:205], v[0:3]
	v_mfma_f32_16x16x32_bf16 v[44:47], v[166:169], v[182:185], v[44:47]
	v_mfma_f32_16x16x32_bf16 v[40:43], v[174:177], v[182:185], v[40:43]
	v_mfma_f32_16x16x32_bf16 v[36:39], v[166:169], v[190:193], v[36:39]
	v_mfma_f32_16x16x32_bf16 v[32:35], v[174:177], v[190:193], v[32:35]
	v_mfma_f32_16x16x32_bf16 v[12:15], v[166:169], v[198:201], v[12:15]
	v_mfma_f32_16x16x32_bf16 v[8:11], v[174:177], v[198:201], v[8:11]
	v_mfma_f32_16x16x32_bf16 v[4:7], v[166:169], v[206:209], v[4:7]
	v_mfma_f32_16x16x32_bf16 v[0:3], v[174:177], v[206:209], v[0:3]
	s_barrier
	s_add_i32 s58, s58, 2
	s_add_u32 s56, s56, 0x100
	s_addc_u32 s57, s57, 0
	s_cmpk_gt_u32 s58, 0x55
	s_mov_b64 s[26:27], s[28:29]
	s_cbranch_scc0 .LBB0_1462
	s_and_b64 vcc, exec, s[16:17]
	s_cbranch_vccz .LBB0_1465
	s_barrier
